# E40: nt (non-temporal, L1-bypass) policy on the streaming read-once global loads of phases P0a/P0 (weight transposes, colmax, hn rows); otherwise E30
# baseline (speedup 1.0000x reference)
.LBB0_11:
	s_cmpk_gt_i32 s82, 0x2af
	s_mov_b64 s[2:3], -1
	s_cbranch_scc0 .LBB0_17
	s_cmpk_gt_u32 s82, 0x36f
	s_cbranch_scc0 .LBB0_14
	s_lshl_b32 s0, s12, 9
	s_and_b32 s0, s0, 0xfffff000
	s_sub_i32 s2, s10, s0
	s_lshl_b32 s0, s82, 5
	s_addk_i32 s0, 0x9200
	s_and_b32 s0, s0, 0xffffff00
	s_add_i32 s0, s0, s8
	v_readlane_b32 s36, v251, 5
	s_lshl_b64 s[6:7], s[0:1], 14
	v_readlane_b32 s42, v251, 11
	v_readlane_b32 s43, v251, 12
	s_add_u32 s6, s42, s6
	s_addc_u32 s7, s43, s7
	s_ashr_i32 s3, s2, 31
	s_lshl_b64 s[2:3], s[2:3], 2
	s_add_u32 s6, s6, s2
	v_readlane_b32 s40, v251, 9
	v_readlane_b32 s41, v251, 10
	v_or_b32_e32 v52, s0, v56
	s_addc_u32 s7, s7, s3
	v_lshl_add_u64 v[0:1], v[52:53], 2, s[40:41]
	v_lshl_add_u64 v[36:37], v[44:45], 2, s[6:7]
	s_movk_i32 s0, 0x4000
	global_load_dword v52, v[0:1], off nt
	v_add_co_u32_e32 v0, vcc, s0, v36
	s_mov_b32 s0, 0x8000
	s_nop 0
	v_addc_co_u32_e32 v1, vcc, 0, v37, vcc
	global_load_dwordx4 v[40:43], v[36:37], off nt
	global_load_dwordx4 v[60:63], v[36:37], off offset:1024 nt
	global_load_dwordx4 v[64:67], v[0:1], off nt
	global_load_dwordx4 v[68:71], v[0:1], off offset:1024 nt
	v_add_co_u32_e32 v0, vcc, s0, v36
	s_mov_b32 s0, 0x10000
	s_nop 0
	v_addc_co_u32_e32 v1, vcc, 0, v37, vcc
	v_add_co_u32_e32 v2, vcc, s33, v36
	global_load_dwordx4 v[28:31], v[0:1], off nt
	global_load_dwordx4 v[24:27], v[0:1], off offset:1024 nt
	v_addc_co_u32_e32 v3, vcc, 0, v37, vcc
	global_load_dwordx4 v[32:35], v[2:3], off nt
	global_load_dwordx4 v[72:75], v[2:3], off offset:1024 nt
	v_add_co_u32_e32 v0, vcc, s0, v36
	s_mov_b32 s0, 0x14000
	s_nop 0
	v_addc_co_u32_e32 v1, vcc, 0, v37, vcc
	v_add_co_u32_e32 v4, vcc, s0, v36
	s_mov_b32 s0, 0x18000
	s_nop 0
	v_addc_co_u32_e32 v5, vcc, 0, v37, vcc
	v_add_co_u32_e32 v2, vcc, s0, v36
	s_mov_b32 s0, 0x1c000
	s_nop 0
	v_addc_co_u32_e32 v3, vcc, 0, v37, vcc
	v_add_co_u32_e32 v6, vcc, s0, v36
	s_mov_b32 s0, 0x24000
	s_nop 0
	v_addc_co_u32_e32 v7, vcc, 0, v37, vcc
	v_add_co_u32_e32 v38, vcc, s34, v36
	v_readlane_b32 s37, v251, 6
	s_nop 0
	v_addc_co_u32_e32 v39, vcc, 0, v37, vcc
	global_load_dwordx4 v[76:79], v[0:1], off nt
	global_load_dwordx4 v[80:83], v[0:1], off offset:1024 nt
	global_load_dwordx4 v[84:87], v[4:5], off nt
	global_load_dwordx4 v[88:91], v[4:5], off offset:1024 nt
	global_load_dwordx4 v[20:23], v[2:3], off nt
	global_load_dwordx4 v[16:19], v[2:3], off offset:1024 nt
	global_load_dwordx4 v[12:15], v[6:7], off nt
	global_load_dwordx4 v[8:11], v[6:7], off offset:1024 nt
	s_nop 0
	global_load_dwordx4 v[4:7], v[38:39], off nt
	global_load_dwordx4 v[0:3], v[38:39], off offset:1024 nt
	v_add_co_u32_e32 v54, vcc, s0, v36
	v_readlane_b32 s38, v251, 7
	s_nop 0
	v_addc_co_u32_e32 v55, vcc, 0, v37, vcc
	v_readlane_b32 s39, v251, 8
	v_readlane_b32 s44, v251, 13
	v_readlane_b32 s45, v251, 14
	v_readlane_b32 s46, v251, 15
	v_readlane_b32 s47, v251, 16
	v_readlane_b32 s48, v251, 17
	v_readlane_b32 s49, v251, 18
	v_readlane_b32 s50, v251, 19
	v_readlane_b32 s51, v251, 20
	s_waitcnt vmcnt(18)
	v_and_b32_e32 v38, 0x7fffffff, v52
	s_nop 0
	v_readlane_b32 s0, v38, 0
	v_readlane_b32 s6, v38, 1
	s_waitcnt vmcnt(17)
	v_and_b32_e32 v93, 0x7fffffff, v43
	v_and_b32_e32 v92, 0x7fffffff, v42
	v_and_b32_e32 v41, 0x7fffffff, v41
	v_and_b32_e32 v40, 0x7fffffff, v40
	s_waitcnt vmcnt(15)
	v_and_b32_e32 v43, 0x7fffffff, v65
	v_and_b32_e32 v42, 0x7fffffff, v64
	v_pk_mul_f32 v[40:41], v[40:41], s[0:1] op_sel_hi:[1,0]
	v_and_b32_e32 v65, 0x7fffffff, v67
	v_and_b32_e32 v64, 0x7fffffff, v66
	v_pk_mul_f32 v[42:43], v[42:43], s[6:7] op_sel_hi:[1,0]
	v_and_b32_e32 v95, 0x7fffffff, v63
	v_and_b32_e32 v94, 0x7fffffff, v62
	v_and_b32_e32 v97, 0x7fffffff, v61
	v_and_b32_e32 v96, 0x7fffffff, v60
	s_waitcnt vmcnt(14)
	v_and_b32_e32 v67, 0x7fffffff, v69
	v_and_b32_e32 v66, 0x7fffffff, v68
	v_max3_f32 v39, v40, 0, v42
	v_max3_f32 v52, v41, 0, v43
	global_load_dwordx4 v[40:43], v[54:55], off nt
	global_load_dwordx4 v[60:63], v[54:55], off offset:1024 nt
	v_pk_mul_f32 v[54:55], v[92:93], s[0:1] op_sel_hi:[1,0]
	v_pk_mul_f32 v[64:65], v[64:65], s[6:7] op_sel_hi:[1,0]
	s_mov_b32 s7, 0x28000
	v_and_b32_e32 v69, 0x7fffffff, v71
	v_and_b32_e32 v68, 0x7fffffff, v70
	v_max3_f32 v59, v54, 0, v64
	v_max3_f32 v92, v55, 0, v65
	v_add_co_u32_e32 v54, vcc, s7, v36
	v_pk_mul_f32 v[64:65], v[96:97], s[0:1] op_sel_hi:[1,0]
	v_pk_mul_f32 v[66:67], v[66:67], s[6:7] op_sel_hi:[1,0]
	v_addc_co_u32_e32 v55, vcc, 0, v37, vcc
	v_pk_mul_f32 v[70:71], v[94:95], s[0:1] op_sel_hi:[1,0]
	v_pk_mul_f32 v[68:69], v[68:69], s[6:7] op_sel_hi:[1,0]
	v_max3_f32 v93, v64, 0, v66
	v_max3_f32 v94, v65, 0, v67
	s_waitcnt vmcnt(15)
	v_and_b32_e32 v67, 0x7fffffff, v31
	v_and_b32_e32 v66, 0x7fffffff, v30
	s_waitcnt vmcnt(13)
	v_and_b32_e32 v35, 0x7fffffff, v35
	v_and_b32_e32 v34, 0x7fffffff, v34
	v_readlane_b32 s0, v38, 2
	v_readlane_b32 s6, v38, 3
	v_max3_f32 v95, v70, 0, v68
	v_max3_f32 v96, v71, 0, v69
	v_and_b32_e32 v65, 0x7fffffff, v29
	v_and_b32_e32 v64, 0x7fffffff, v28
	v_and_b32_e32 v69, 0x7fffffff, v25
	v_and_b32_e32 v68, 0x7fffffff, v24
	v_and_b32_e32 v71, 0x7fffffff, v27
	v_and_b32_e32 v70, 0x7fffffff, v26
	global_load_dwordx4 v[24:27], v[54:55], off nt
	global_load_dwordx4 v[28:31], v[54:55], off offset:1024 nt
	v_pk_mul_f32 v[54:55], v[66:67], s[0:1] op_sel_hi:[1,0]
	v_pk_mul_f32 v[34:35], v[34:35], s[6:7] op_sel_hi:[1,0]
	s_mov_b32 s7, 0x2c000
	v_and_b32_e32 v33, 0x7fffffff, v33
	v_and_b32_e32 v32, 0x7fffffff, v32
	v_max3_f32 v59, v59, v54, v34
	v_add_co_u32_e32 v54, vcc, s7, v36
	s_waitcnt vmcnt(14)
	v_and_b32_e32 v75, 0x7fffffff, v75
	v_and_b32_e32 v74, 0x7fffffff, v74
	v_max3_f32 v97, v92, v55, v35
	v_addc_co_u32_e32 v55, vcc, 0, v37, vcc
	v_pk_mul_f32 v[34:35], v[64:65], s[0:1] op_sel_hi:[1,0]
	v_pk_mul_f32 v[32:33], v[32:33], s[6:7] op_sel_hi:[1,0]
	v_and_b32_e32 v73, 0x7fffffff, v73
	v_and_b32_e32 v72, 0x7fffffff, v72
	v_max3_f32 v52, v52, v35, v33
	v_max3_f32 v39, v39, v34, v32
	global_load_dwordx4 v[32:35], v[54:55], off nt
	global_load_dwordx4 v[64:67], v[54:55], off offset:1024 nt
	v_pk_mul_f32 v[54:55], v[70:71], s[0:1] op_sel_hi:[1,0]
	v_pk_mul_f32 v[70:71], v[74:75], s[6:7] op_sel_hi:[1,0]
	s_mov_b32 s7, 0x30000
	v_max3_f32 v96, v96, v55, v71
	v_max3_f32 v98, v95, v54, v70
	v_add_co_u32_e32 v54, vcc, s7, v36
	v_pk_mul_f32 v[68:69], v[68:69], s[0:1] op_sel_hi:[1,0]
	v_pk_mul_f32 v[70:71], v[72:73], s[6:7] op_sel_hi:[1,0]
	v_addc_co_u32_e32 v55, vcc, 0, v37, vcc
	v_max3_f32 v99, v94, v69, v71
	s_waitcnt vmcnt(15)
	v_and_b32_e32 v77, 0x7fffffff, v77
	v_and_b32_e32 v76, 0x7fffffff, v76
	s_waitcnt vmcnt(14)
	v_and_b32_e32 v95, 0x7fffffff, v81
	v_and_b32_e32 v94, 0x7fffffff, v80
	s_waitcnt vmcnt(13)
	v_and_b32_e32 v81, 0x7fffffff, v85
	v_and_b32_e32 v80, 0x7fffffff, v84
	v_readlane_b32 s0, v38, 4
	v_readlane_b32 s6, v38, 5
	v_max3_f32 v100, v93, v68, v70
	global_load_dwordx4 v[68:71], v[54:55], off nt
	global_load_dwordx4 v[72:75], v[54:55], off offset:1024 nt
	v_pk_mul_f32 v[54:55], v[76:77], s[0:1] op_sel_hi:[1,0]
	v_pk_mul_f32 v[76:77], v[80:81], s[6:7] op_sel_hi:[1,0]
	v_and_b32_e32 v79, 0x7fffffff, v79
	v_and_b32_e32 v78, 0x7fffffff, v78
	v_and_b32_e32 v93, 0x7fffffff, v83
	v_and_b32_e32 v92, 0x7fffffff, v82
	v_and_b32_e32 v83, 0x7fffffff, v87
	v_and_b32_e32 v82, 0x7fffffff, v86
	v_max3_f32 v39, v39, v54, v76
	v_add_co_u32_e32 v54, vcc, s35, v36
	s_waitcnt vmcnt(14)
	v_and_b32_e32 v85, 0x7fffffff, v89
	v_and_b32_e32 v84, 0x7fffffff, v88
	v_max3_f32 v52, v52, v55, v77
	v_addc_co_u32_e32 v55, vcc, 0, v37, vcc
	v_pk_mul_f32 v[76:77], v[78:79], s[0:1] op_sel_hi:[1,0]
	v_pk_mul_f32 v[78:79], v[82:83], s[6:7] op_sel_hi:[1,0]
	v_and_b32_e32 v87, 0x7fffffff, v91
	v_and_b32_e32 v86, 0x7fffffff, v90
	v_max3_f32 v59, v59, v76, v78
	v_max3_f32 v97, v97, v77, v79
	global_load_dwordx4 v[76:79], v[54:55], off nt
	global_load_dwordx4 v[80:83], v[54:55], off offset:1024 nt
	v_pk_mul_f32 v[54:55], v[94:95], s[0:1] op_sel_hi:[1,0]
	v_pk_mul_f32 v[84:85], v[84:85], s[6:7] op_sel_hi:[1,0]
	s_mov_b32 s7, 0x38000
	v_max3_f32 v94, v100, v54, v84
	v_max3_f32 v95, v99, v55, v85
	v_pk_mul_f32 v[84:85], v[92:93], s[0:1] op_sel_hi:[1,0]
	v_pk_mul_f32 v[86:87], v[86:87], s[6:7] op_sel_hi:[1,0]
	v_add_co_u32_e32 v54, vcc, s7, v36
	v_max3_f32 v92, v98, v84, v86
	v_max3_f32 v93, v96, v85, v87
	s_waitcnt vmcnt(15)
	v_and_b32_e32 v23, 0x7fffffff, v23
	v_and_b32_e32 v22, 0x7fffffff, v22
	s_waitcnt vmcnt(14)
	v_and_b32_e32 v85, 0x7fffffff, v17
	v_and_b32_e32 v84, 0x7fffffff, v16
	s_waitcnt vmcnt(13)
	v_and_b32_e32 v17, 0x7fffffff, v15
	v_and_b32_e32 v16, 0x7fffffff, v14
	v_readlane_b32 s0, v38, 6
	v_readlane_b32 s6, v38, 7
	v_addc_co_u32_e32 v55, vcc, 0, v37, vcc
	v_pk_mul_f32 v[22:23], v[22:23], s[0:1] op_sel_hi:[1,0]
	v_pk_mul_f32 v[16:17], v[16:17], s[6:7] op_sel_hi:[1,0]
	s_mov_b32 s7, 0x3c000
	v_and_b32_e32 v21, 0x7fffffff, v21
	v_and_b32_e32 v20, 0x7fffffff, v20
	v_and_b32_e32 v87, 0x7fffffff, v19
	v_and_b32_e32 v86, 0x7fffffff, v18
	v_and_b32_e32 v19, 0x7fffffff, v13
	v_and_b32_e32 v18, 0x7fffffff, v12
	s_waitcnt vmcnt(12)
	v_and_b32_e32 v89, 0x7fffffff, v11
	v_and_b32_e32 v88, 0x7fffffff, v10
	v_and_b32_e32 v91, 0x7fffffff, v9
	v_and_b32_e32 v90, 0x7fffffff, v8
	global_load_dwordx4 v[12:15], v[54:55], off nt
	global_load_dwordx4 v[8:11], v[54:55], off offset:1024 nt
	v_max3_f32 v59, v59, v22, v16
	v_add_co_u32_e32 v22, vcc, s7, v36
	v_max3_f32 v96, v97, v23, v17
	s_nop 0
	v_addc_co_u32_e32 v23, vcc, 0, v37, vcc
	v_pk_mul_f32 v[16:17], v[20:21], s[0:1] op_sel_hi:[1,0]
	v_pk_mul_f32 v[18:19], v[18:19], s[6:7] op_sel_hi:[1,0]
	v_pk_mul_f32 v[54:55], v[86:87], s[0:1] op_sel_hi:[1,0]
	v_max3_f32 v52, v52, v17, v19
	v_max3_f32 v39, v39, v16, v18
	global_load_dwordx4 v[16:19], v[22:23], off nt
	s_nop 0
	global_load_dwordx4 v[20:23], v[22:23], off offset:1024 nt
	v_pk_mul_f32 v[84:85], v[84:85], s[0:1] op_sel_hi:[1,0]
	v_pk_mul_f32 v[88:89], v[88:89], s[6:7] op_sel_hi:[1,0]
	s_waitcnt vmcnt(15)
	v_and_b32_e32 v7, 0x7fffffff, v7
	v_and_b32_e32 v6, 0x7fffffff, v6
	v_and_b32_e32 v5, 0x7fffffff, v5
	v_and_b32_e32 v4, 0x7fffffff, v4
	s_waitcnt vmcnt(14)
	v_and_b32_e32 v3, 0x7fffffff, v3
	v_and_b32_e32 v2, 0x7fffffff, v2
	v_and_b32_e32 v1, 0x7fffffff, v1
	v_and_b32_e32 v0, 0x7fffffff, v0
	v_readlane_b32 s0, v38, 8
	v_pk_mul_f32 v[86:87], v[90:91], s[6:7] op_sel_hi:[1,0]
	v_max3_f32 v89, v93, v55, v89
	v_max3_f32 v88, v92, v54, v88
	v_pk_mul_f32 v[4:5], v[4:5], s[0:1] op_sel_hi:[1,0]
	v_pk_mul_f32 v[6:7], v[6:7], s[0:1] op_sel_hi:[1,0]
	v_pk_mul_f32 v[0:1], v[0:1], s[0:1] op_sel_hi:[1,0]
	v_pk_mul_f32 v[2:3], v[2:3], s[0:1] op_sel_hi:[1,0]
	s_waitcnt vmcnt(13)
	v_and_b32_e32 v41, 0x7fffffff, v41
	v_and_b32_e32 v40, 0x7fffffff, v40
	v_and_b32_e32 v43, 0x7fffffff, v43
	v_and_b32_e32 v42, 0x7fffffff, v42
	s_waitcnt vmcnt(12)
	v_and_b32_e32 v55, 0x7fffffff, v61
	v_and_b32_e32 v54, 0x7fffffff, v60
	v_and_b32_e32 v61, 0x7fffffff, v63
	v_and_b32_e32 v60, 0x7fffffff, v62
	v_readlane_b32 s0, v38, 9
	v_max3_f32 v85, v95, v85, v87
	v_max3_f32 v84, v94, v84, v86
	v_pk_mul_f32 v[42:43], v[42:43], s[0:1] op_sel_hi:[1,0]
	v_pk_mul_f32 v[40:41], v[40:41], s[0:1] op_sel_hi:[1,0]
	v_pk_mul_f32 v[60:61], v[60:61], s[0:1] op_sel_hi:[1,0]
	v_pk_mul_f32 v[54:55], v[54:55], s[0:1] op_sel_hi:[1,0]
	v_max3_f32 v39, v39, v4, v40
	v_max3_f32 v40, v52, v5, v41
	v_max3_f32 v41, v59, v6, v42
	v_max3_f32 v42, v96, v7, v43
	v_max3_f32 v43, v84, v0, v54
	v_max3_f32 v52, v85, v1, v55
	v_max3_f32 v54, v88, v2, v60
	v_max3_f32 v55, v89, v3, v61
	s_waitcnt vmcnt(11)
	v_and_b32_e32 v1, 0x7fffffff, v25
	v_and_b32_e32 v0, 0x7fffffff, v24
	v_and_b32_e32 v3, 0x7fffffff, v27
	v_and_b32_e32 v2, 0x7fffffff, v26
	s_waitcnt vmcnt(10)
	v_and_b32_e32 v5, 0x7fffffff, v29
	v_and_b32_e32 v4, 0x7fffffff, v28
	v_and_b32_e32 v7, 0x7fffffff, v31
	v_and_b32_e32 v6, 0x7fffffff, v30
	v_readlane_b32 s0, v38, 10
	s_waitcnt vmcnt(9)
	v_and_b32_e32 v25, 0x7fffffff, v35
	v_and_b32_e32 v24, 0x7fffffff, v34
	v_pk_mul_f32 v[2:3], v[2:3], s[0:1] op_sel_hi:[1,0]
	v_pk_mul_f32 v[0:1], v[0:1], s[0:1] op_sel_hi:[1,0]
	v_pk_mul_f32 v[6:7], v[6:7], s[0:1] op_sel_hi:[1,0]
	v_pk_mul_f32 v[4:5], v[4:5], s[0:1] op_sel_hi:[1,0]
	v_and_b32_e32 v27, 0x7fffffff, v33
	v_and_b32_e32 v26, 0x7fffffff, v32
	s_waitcnt vmcnt(8)
	v_and_b32_e32 v29, 0x7fffffff, v67
	v_and_b32_e32 v28, 0x7fffffff, v66
	v_and_b32_e32 v31, 0x7fffffff, v65
	v_and_b32_e32 v30, 0x7fffffff, v64
	v_readlane_b32 s0, v38, 11
	v_readlane_b32 s6, v38, 17
	s_nop 0
	v_pk_mul_f32 v[26:27], v[26:27], s[0:1] op_sel_hi:[1,0]
	v_pk_mul_f32 v[24:25], v[24:25], s[0:1] op_sel_hi:[1,0]
	v_pk_mul_f32 v[30:31], v[30:31], s[0:1] op_sel_hi:[1,0]
	v_pk_mul_f32 v[28:29], v[28:29], s[0:1] op_sel_hi:[1,0]
	v_max3_f32 v32, v42, v3, v25
	v_max3_f32 v33, v41, v2, v24
	v_max3_f32 v34, v40, v1, v27
	v_max3_f32 v35, v39, v0, v26
	v_max3_f32 v39, v55, v7, v29
	v_max3_f32 v40, v54, v6, v28
	v_max3_f32 v41, v52, v5, v31
	v_max3_f32 v42, v43, v4, v30
	s_waitcnt vmcnt(7)
	v_and_b32_e32 v1, 0x7fffffff, v71
	v_and_b32_e32 v0, 0x7fffffff, v70
	v_and_b32_e32 v3, 0x7fffffff, v69
	v_and_b32_e32 v2, 0x7fffffff, v68
	s_waitcnt vmcnt(6)
	v_and_b32_e32 v5, 0x7fffffff, v75
	v_and_b32_e32 v4, 0x7fffffff, v74
	v_and_b32_e32 v7, 0x7fffffff, v73
	v_and_b32_e32 v6, 0x7fffffff, v72
	v_readlane_b32 s0, v38, 12
	s_waitcnt vmcnt(5)
	v_and_b32_e32 v25, 0x7fffffff, v77
	v_and_b32_e32 v24, 0x7fffffff, v76
	v_pk_mul_f32 v[2:3], v[2:3], s[0:1] op_sel_hi:[1,0]
	v_pk_mul_f32 v[0:1], v[0:1], s[0:1] op_sel_hi:[1,0]
	v_pk_mul_f32 v[6:7], v[6:7], s[0:1] op_sel_hi:[1,0]
	v_pk_mul_f32 v[4:5], v[4:5], s[0:1] op_sel_hi:[1,0]
	v_readlane_b32 s0, v38, 13
	v_and_b32_e32 v27, 0x7fffffff, v79
	v_and_b32_e32 v26, 0x7fffffff, v78
	v_pk_mul_f32 v[24:25], v[24:25], s[0:1] op_sel_hi:[1,0]
	s_waitcnt vmcnt(4)
	v_and_b32_e32 v29, 0x7fffffff, v81
	v_and_b32_e32 v28, 0x7fffffff, v80
	v_and_b32_e32 v31, 0x7fffffff, v83
	v_and_b32_e32 v30, 0x7fffffff, v82
	v_max3_f32 v52, v35, v2, v24
	v_add_co_u32_e32 v2, vcc, s68, v36
	v_pk_mul_f32 v[26:27], v[26:27], s[0:1] op_sel_hi:[1,0]
	v_pk_mul_f32 v[30:31], v[30:31], s[0:1] op_sel_hi:[1,0]
	v_pk_mul_f32 v[28:29], v[28:29], s[0:1] op_sel_hi:[1,0]
	v_max3_f32 v54, v34, v3, v25
	v_addc_co_u32_e32 v3, vcc, 0, v37, vcc
	s_mov_b32 s0, 0x44000
	v_max3_f32 v55, v33, v0, v26
	v_max3_f32 v59, v32, v1, v27
	v_max3_f32 v60, v42, v6, v28
	v_max3_f32 v61, v41, v7, v29
	v_max3_f32 v62, v40, v4, v30
	v_max3_f32 v39, v39, v5, v31
	global_load_dwordx4 v[24:27], v[2:3], off nt
	global_load_dwordx4 v[28:31], v[2:3], off offset:1024 nt
	v_add_co_u32_e32 v2, vcc, s0, v36
	s_waitcnt vmcnt(5)
	v_and_b32_e32 v1, 0x7fffffff, v13
	v_and_b32_e32 v0, 0x7fffffff, v12
	v_and_b32_e32 v5, 0x7fffffff, v15
	v_and_b32_e32 v4, 0x7fffffff, v14
	v_addc_co_u32_e32 v3, vcc, 0, v37, vcc
	s_waitcnt vmcnt(4)
	v_and_b32_e32 v7, 0x7fffffff, v9
	v_and_b32_e32 v6, 0x7fffffff, v8
	v_and_b32_e32 v9, 0x7fffffff, v11
	v_and_b32_e32 v8, 0x7fffffff, v10
	v_readlane_b32 s0, v38, 14
	global_load_dwordx4 v[32:35], v[2:3], off nt
	global_load_dwordx4 v[40:43], v[2:3], off offset:1024 nt
	v_pk_mul_f32 v[2:3], v[4:5], s[0:1] op_sel_hi:[1,0]
	v_pk_mul_f32 v[0:1], v[0:1], s[0:1] op_sel_hi:[1,0]
	v_pk_mul_f32 v[4:5], v[8:9], s[0:1] op_sel_hi:[1,0]
	v_pk_mul_f32 v[6:7], v[6:7], s[0:1] op_sel_hi:[1,0]
	s_waitcnt vmcnt(5)
	v_and_b32_e32 v11, 0x7fffffff, v17
	v_and_b32_e32 v10, 0x7fffffff, v16
	v_readlane_b32 s0, v38, 15
	v_and_b32_e32 v9, 0x7fffffff, v19
	v_and_b32_e32 v8, 0x7fffffff, v18
	v_pk_mul_f32 v[10:11], v[10:11], s[0:1] op_sel_hi:[1,0]
	s_waitcnt vmcnt(4)
	v_and_b32_e32 v13, 0x7fffffff, v23
	v_and_b32_e32 v12, 0x7fffffff, v22
	v_and_b32_e32 v15, 0x7fffffff, v21
	v_and_b32_e32 v14, 0x7fffffff, v20
	v_max3_f32 v52, v52, v0, v10
	v_add_co_u32_e32 v0, vcc, s69, v36
	v_pk_mul_f32 v[8:9], v[8:9], s[0:1] op_sel_hi:[1,0]
	v_pk_mul_f32 v[14:15], v[14:15], s[0:1] op_sel_hi:[1,0]
	v_pk_mul_f32 v[12:13], v[12:13], s[0:1] op_sel_hi:[1,0]
	v_max3_f32 v97, v54, v1, v11
	v_addc_co_u32_e32 v1, vcc, 0, v37, vcc
	s_mov_b32 s0, 0x4c000
	global_load_dwordx4 v[16:19], v[0:1], off nt
	global_load_dwordx4 v[20:23], v[0:1], off offset:1024 nt
	v_add_co_u32_e32 v0, vcc, s0, v36
	v_max3_f32 v98, v62, v4, v12
	s_nop 0
	v_addc_co_u32_e32 v1, vcc, 0, v37, vcc
	v_max3_f32 v99, v61, v7, v15
	v_max3_f32 v100, v60, v6, v14
	global_load_dwordx4 v[60:63], v[0:1], off nt
	global_load_dwordx4 v[64:67], v[0:1], off offset:1024 nt
	s_mov_b32 s0, 0x50000
	v_add_co_u32_e32 v0, vcc, s0, v36
	s_mov_b32 s0, 0x54000
	s_nop 0
	v_addc_co_u32_e32 v1, vcc, 0, v37, vcc
	global_load_dwordx4 v[68:71], v[0:1], off nt
	global_load_dwordx4 v[72:75], v[0:1], off offset:1024 nt
	v_add_co_u32_e32 v0, vcc, s0, v36
	s_mov_b32 s0, 0x58000
	s_nop 0
	v_addc_co_u32_e32 v1, vcc, 0, v37, vcc
	global_load_dwordx4 v[76:79], v[0:1], off nt
	global_load_dwordx4 v[80:83], v[0:1], off offset:1024 nt
	v_add_co_u32_e32 v0, vcc, s0, v36
	v_max3_f32 v59, v59, v3, v9
	s_nop 0
	v_addc_co_u32_e32 v1, vcc, 0, v37, vcc
	v_max3_f32 v96, v55, v2, v8
	v_max3_f32 v39, v39, v5, v13
	global_load_dwordx4 v[12:15], v[0:1], off nt
	global_load_dwordx4 v[8:11], v[0:1], off offset:1024 nt
	v_add_co_u32_e32 v0, vcc, s70, v36
	s_mov_b32 s0, 0x60000
	s_nop 0
	v_addc_co_u32_e32 v1, vcc, 0, v37, vcc
	global_load_dwordx4 v[4:7], v[0:1], off nt
	s_nop 0
	global_load_dwordx4 v[0:3], v[0:1], off offset:1024 nt
	v_add_co_u32_e32 v54, vcc, s0, v36
	v_readlane_b32 s0, v38, 16
	s_waitcnt vmcnt(15)
	v_and_b32_e32 v87, 0x7fffffff, v25
	v_and_b32_e32 v86, 0x7fffffff, v24
	v_addc_co_u32_e32 v55, vcc, 0, v37, vcc
	v_and_b32_e32 v85, 0x7fffffff, v27
	v_and_b32_e32 v84, 0x7fffffff, v26
	s_waitcnt vmcnt(14)
	v_and_b32_e32 v91, 0x7fffffff, v29
	v_and_b32_e32 v90, 0x7fffffff, v28
	v_and_b32_e32 v89, 0x7fffffff, v31
	v_and_b32_e32 v88, 0x7fffffff, v30
	global_load_dwordx4 v[24:27], v[54:55], off nt
	global_load_dwordx4 v[28:31], v[54:55], off offset:1024 nt
	v_pk_mul_f32 v[54:55], v[90:91], s[0:1] op_sel_hi:[1,0]
	s_waitcnt vmcnt(15)
	v_and_b32_e32 v33, 0x7fffffff, v33
	v_and_b32_e32 v32, 0x7fffffff, v32
	s_waitcnt vmcnt(14)
	v_and_b32_e32 v93, 0x7fffffff, v41
	v_and_b32_e32 v92, 0x7fffffff, v40
	v_pk_mul_f32 v[40:41], v[86:87], s[0:1] op_sel_hi:[1,0]
	v_pk_mul_f32 v[32:33], v[32:33], s[6:7] op_sel_hi:[1,0]
	s_mov_b32 s7, 0x64000
	v_and_b32_e32 v35, 0x7fffffff, v35
	v_and_b32_e32 v34, 0x7fffffff, v34
	v_max3_f32 v52, v52, v40, v32
	v_add_co_u32_e32 v40, vcc, s7, v36
	v_and_b32_e32 v95, 0x7fffffff, v43
	v_and_b32_e32 v94, 0x7fffffff, v42
	v_max3_f32 v97, v97, v41, v33
	v_addc_co_u32_e32 v41, vcc, 0, v37, vcc
	v_pk_mul_f32 v[32:33], v[84:85], s[0:1] op_sel_hi:[1,0]
	v_pk_mul_f32 v[34:35], v[34:35], s[6:7] op_sel_hi:[1,0]
	v_pk_mul_f32 v[84:85], v[92:93], s[6:7] op_sel_hi:[1,0]
	s_mov_b32 s7, 0x68000
	v_max3_f32 v100, v100, v54, v84
	v_max3_f32 v99, v99, v55, v85
	v_add_co_u32_e32 v54, vcc, s7, v36
	v_pk_mul_f32 v[84:85], v[88:89], s[0:1] op_sel_hi:[1,0]
	v_pk_mul_f32 v[86:87], v[94:95], s[6:7] op_sel_hi:[1,0]
	v_addc_co_u32_e32 v55, vcc, 0, v37, vcc
	v_max3_f32 v98, v98, v84, v86
	v_max3_f32 v39, v39, v85, v87
	s_waitcnt vmcnt(13)
	v_and_b32_e32 v87, 0x7fffffff, v19
	v_and_b32_e32 v86, 0x7fffffff, v18
	s_waitcnt vmcnt(11)
	v_and_b32_e32 v63, 0x7fffffff, v63
	v_and_b32_e32 v62, 0x7fffffff, v62
	v_readlane_b32 s0, v38, 18
	v_readlane_b32 s6, v38, 19
	v_max3_f32 v96, v96, v32, v34
	v_max3_f32 v59, v59, v33, v35
	global_load_dwordx4 v[32:35], v[40:41], off nt
	s_nop 0
	global_load_dwordx4 v[40:43], v[40:41], off offset:1024 nt
	v_and_b32_e32 v85, 0x7fffffff, v17
	v_and_b32_e32 v84, 0x7fffffff, v16
	v_and_b32_e32 v89, 0x7fffffff, v21
	v_and_b32_e32 v88, 0x7fffffff, v20
	v_and_b32_e32 v91, 0x7fffffff, v23
	v_and_b32_e32 v90, 0x7fffffff, v22
	global_load_dwordx4 v[16:19], v[54:55], off nt
	global_load_dwordx4 v[20:23], v[54:55], off offset:1024 nt
	v_pk_mul_f32 v[54:55], v[86:87], s[0:1] op_sel_hi:[1,0]
	v_pk_mul_f32 v[62:63], v[62:63], s[6:7] op_sel_hi:[1,0]
	s_mov_b32 s7, 0x6c000
	v_and_b32_e32 v61, 0x7fffffff, v61
	v_and_b32_e32 v60, 0x7fffffff, v60
	v_max3_f32 v96, v96, v54, v62
	v_add_co_u32_e32 v54, vcc, s7, v36
	s_waitcnt vmcnt(14)
	v_and_b32_e32 v93, 0x7fffffff, v67
	v_and_b32_e32 v92, 0x7fffffff, v66
	v_max3_f32 v59, v59, v55, v63
	v_addc_co_u32_e32 v55, vcc, 0, v37, vcc
	v_pk_mul_f32 v[62:63], v[84:85], s[0:1] op_sel_hi:[1,0]
	v_pk_mul_f32 v[60:61], v[60:61], s[6:7] op_sel_hi:[1,0]
	v_and_b32_e32 v95, 0x7fffffff, v65
	v_and_b32_e32 v94, 0x7fffffff, v64
	v_max3_f32 v97, v97, v63, v61
	v_max3_f32 v52, v52, v62, v60
	global_load_dwordx4 v[60:63], v[54:55], off nt
	global_load_dwordx4 v[64:67], v[54:55], off offset:1024 nt
	v_pk_mul_f32 v[54:55], v[90:91], s[0:1] op_sel_hi:[1,0]
	v_pk_mul_f32 v[84:85], v[92:93], s[6:7] op_sel_hi:[1,0]
	v_pk_mul_f32 v[86:87], v[94:95], s[6:7] op_sel_hi:[1,0]
	v_max3_f32 v39, v39, v55, v85
	v_max3_f32 v98, v98, v54, v84
	v_add_co_u32_e32 v54, vcc, s71, v36
	v_pk_mul_f32 v[84:85], v[88:89], s[0:1] op_sel_hi:[1,0]
	s_nop 0
	v_addc_co_u32_e32 v55, vcc, 0, v37, vcc
	v_max3_f32 v99, v99, v85, v87
	v_max3_f32 v100, v100, v84, v86
	s_waitcnt vmcnt(15)
	v_and_b32_e32 v87, 0x7fffffff, v69
	v_and_b32_e32 v86, 0x7fffffff, v68
	s_waitcnt vmcnt(13)
	v_and_b32_e32 v77, 0x7fffffff, v77
	v_and_b32_e32 v76, 0x7fffffff, v76
	v_readlane_b32 s0, v38, 20
	v_readlane_b32 s6, v38, 21
	v_and_b32_e32 v85, 0x7fffffff, v71
	v_and_b32_e32 v84, 0x7fffffff, v70
	v_and_b32_e32 v89, 0x7fffffff, v75
	v_and_b32_e32 v88, 0x7fffffff, v74
	v_and_b32_e32 v91, 0x7fffffff, v73
	v_and_b32_e32 v90, 0x7fffffff, v72
	global_load_dwordx4 v[68:71], v[54:55], off nt
	global_load_dwordx4 v[72:75], v[54:55], off offset:1024 nt
	v_pk_mul_f32 v[54:55], v[86:87], s[0:1] op_sel_hi:[1,0]
	v_pk_mul_f32 v[76:77], v[76:77], s[6:7] op_sel_hi:[1,0]
	s_mov_b32 s7, 0x74000
	v_and_b32_e32 v79, 0x7fffffff, v79
	v_and_b32_e32 v78, 0x7fffffff, v78
	v_max3_f32 v52, v52, v54, v76
	v_add_co_u32_e32 v54, vcc, s7, v36
	s_waitcnt vmcnt(14)
	v_and_b32_e32 v93, 0x7fffffff, v81
	v_and_b32_e32 v92, 0x7fffffff, v80
	v_max3_f32 v97, v97, v55, v77
	v_addc_co_u32_e32 v55, vcc, 0, v37, vcc
	v_pk_mul_f32 v[76:77], v[84:85], s[0:1] op_sel_hi:[1,0]
	v_pk_mul_f32 v[78:79], v[78:79], s[6:7] op_sel_hi:[1,0]
	v_and_b32_e32 v95, 0x7fffffff, v83
	v_and_b32_e32 v94, 0x7fffffff, v82
	v_max3_f32 v96, v96, v76, v78
	v_max3_f32 v59, v59, v77, v79
	global_load_dwordx4 v[76:79], v[54:55], off nt
	global_load_dwordx4 v[80:83], v[54:55], off offset:1024 nt
	v_pk_mul_f32 v[54:55], v[90:91], s[0:1] op_sel_hi:[1,0]
	v_pk_mul_f32 v[84:85], v[92:93], s[6:7] op_sel_hi:[1,0]
	s_mov_b32 s7, 0x78000
	v_max3_f32 v92, v100, v54, v84
	v_add_co_u32_e32 v54, vcc, s7, v36
	s_mov_b32 s7, 0x7c000
	v_max3_f32 v93, v99, v55, v85
	v_addc_co_u32_e32 v55, vcc, 0, v37, vcc
	v_pk_mul_f32 v[84:85], v[88:89], s[0:1] op_sel_hi:[1,0]
	v_pk_mul_f32 v[86:87], v[94:95], s[6:7] op_sel_hi:[1,0]
	v_add_co_u32_e32 v36, vcc, s7, v36
	v_max3_f32 v94, v98, v84, v86
	v_max3_f32 v39, v39, v85, v87
	s_waitcnt vmcnt(15)
	v_and_b32_e32 v13, 0x7fffffff, v13
	v_and_b32_e32 v12, 0x7fffffff, v12
	v_and_b32_e32 v15, 0x7fffffff, v15
	v_and_b32_e32 v14, 0x7fffffff, v14
	s_waitcnt vmcnt(14)
	v_and_b32_e32 v85, 0x7fffffff, v9
	v_and_b32_e32 v84, 0x7fffffff, v8
	v_and_b32_e32 v87, 0x7fffffff, v11
	v_and_b32_e32 v86, 0x7fffffff, v10
	s_waitcnt vmcnt(13)
	v_and_b32_e32 v9, 0x7fffffff, v7
	v_and_b32_e32 v8, 0x7fffffff, v6
	v_and_b32_e32 v11, 0x7fffffff, v5
	v_and_b32_e32 v10, 0x7fffffff, v4
	s_waitcnt vmcnt(12)
	v_and_b32_e32 v89, 0x7fffffff, v3
	v_and_b32_e32 v88, 0x7fffffff, v2
	v_and_b32_e32 v91, 0x7fffffff, v1
	v_and_b32_e32 v90, 0x7fffffff, v0
	global_load_dwordx4 v[0:3], v[54:55], off nt
	global_load_dwordx4 v[4:7], v[54:55], off offset:1024 nt
	v_readlane_b32 s0, v38, 22
	v_readlane_b32 s6, v38, 23
	v_addc_co_u32_e32 v37, vcc, 0, v37, vcc
	v_pk_mul_f32 v[14:15], v[14:15], s[0:1] op_sel_hi:[1,0]
	v_pk_mul_f32 v[12:13], v[12:13], s[0:1] op_sel_hi:[1,0]
	v_pk_mul_f32 v[10:11], v[10:11], s[6:7] op_sel_hi:[1,0]
	v_pk_mul_f32 v[8:9], v[8:9], s[6:7] op_sel_hi:[1,0]
	v_max3_f32 v52, v52, v12, v10
	v_max3_f32 v59, v59, v15, v9
	v_max3_f32 v95, v96, v14, v8
	v_max3_f32 v96, v97, v13, v11
	global_load_dwordx4 v[8:11], v[36:37], off nt
	global_load_dwordx4 v[12:15], v[36:37], off offset:1024 nt
	v_pk_mul_f32 v[36:37], v[86:87], s[0:1] op_sel_hi:[1,0]
	v_pk_mul_f32 v[54:55], v[84:85], s[0:1] op_sel_hi:[1,0]
	v_pk_mul_f32 v[86:87], v[88:89], s[6:7] op_sel_hi:[1,0]
	s_waitcnt vmcnt(15)
	v_and_b32_e32 v27, 0x7fffffff, v27
	v_and_b32_e32 v26, 0x7fffffff, v26
	v_and_b32_e32 v25, 0x7fffffff, v25
	v_and_b32_e32 v24, 0x7fffffff, v24
	s_waitcnt vmcnt(14)
	v_and_b32_e32 v31, 0x7fffffff, v31
	v_and_b32_e32 v30, 0x7fffffff, v30
	v_and_b32_e32 v29, 0x7fffffff, v29
	v_and_b32_e32 v28, 0x7fffffff, v28
	v_readlane_b32 s0, v38, 24
	v_pk_mul_f32 v[84:85], v[90:91], s[6:7] op_sel_hi:[1,0]
	v_max3_f32 v39, v39, v37, v87
	v_max3_f32 v86, v94, v36, v86
	v_pk_mul_f32 v[24:25], v[24:25], s[0:1] op_sel_hi:[1,0]
	v_pk_mul_f32 v[26:27], v[26:27], s[0:1] op_sel_hi:[1,0]
	v_pk_mul_f32 v[28:29], v[28:29], s[0:1] op_sel_hi:[1,0]
	v_pk_mul_f32 v[30:31], v[30:31], s[0:1] op_sel_hi:[1,0]
	s_waitcnt vmcnt(13)
	v_and_b32_e32 v33, 0x7fffffff, v33
	v_and_b32_e32 v32, 0x7fffffff, v32
	v_and_b32_e32 v35, 0x7fffffff, v35
	v_and_b32_e32 v34, 0x7fffffff, v34
	s_waitcnt vmcnt(12)
	v_and_b32_e32 v37, 0x7fffffff, v41
	v_and_b32_e32 v36, 0x7fffffff, v40
	v_and_b32_e32 v41, 0x7fffffff, v43
	v_and_b32_e32 v40, 0x7fffffff, v42
	v_readlane_b32 s0, v38, 25
	v_max3_f32 v55, v93, v55, v85
	v_max3_f32 v54, v92, v54, v84
	v_pk_mul_f32 v[34:35], v[34:35], s[0:1] op_sel_hi:[1,0]
	v_pk_mul_f32 v[32:33], v[32:33], s[0:1] op_sel_hi:[1,0]
	v_pk_mul_f32 v[40:41], v[40:41], s[0:1] op_sel_hi:[1,0]
	v_pk_mul_f32 v[36:37], v[36:37], s[0:1] op_sel_hi:[1,0]
	s_waitcnt vmcnt(11)
	v_and_b32_e32 v17, 0x7fffffff, v17
	v_and_b32_e32 v16, 0x7fffffff, v16
	v_and_b32_e32 v19, 0x7fffffff, v19
	v_and_b32_e32 v18, 0x7fffffff, v18
	s_waitcnt vmcnt(10)
	v_and_b32_e32 v21, 0x7fffffff, v21
	v_and_b32_e32 v20, 0x7fffffff, v20
	v_and_b32_e32 v23, 0x7fffffff, v23
	v_and_b32_e32 v22, 0x7fffffff, v22
	v_readlane_b32 s0, v38, 26
	v_max3_f32 v32, v52, v24, v32
	v_max3_f32 v33, v96, v25, v33
	v_max3_f32 v34, v95, v26, v34
	v_max3_f32 v35, v59, v27, v35
	v_max3_f32 v36, v54, v28, v36
	v_max3_f32 v37, v55, v29, v37
	v_max3_f32 v40, v86, v30, v40
	v_max3_f32 v39, v39, v31, v41
	v_pk_mul_f32 v[18:19], v[18:19], s[0:1] op_sel_hi:[1,0]
	v_pk_mul_f32 v[16:17], v[16:17], s[0:1] op_sel_hi:[1,0]
	v_pk_mul_f32 v[22:23], v[22:23], s[0:1] op_sel_hi:[1,0]
	v_pk_mul_f32 v[20:21], v[20:21], s[0:1] op_sel_hi:[1,0]
	s_waitcnt vmcnt(9)
	v_and_b32_e32 v25, 0x7fffffff, v63
	v_and_b32_e32 v24, 0x7fffffff, v62
	v_and_b32_e32 v27, 0x7fffffff, v61
	v_and_b32_e32 v26, 0x7fffffff, v60
	s_waitcnt vmcnt(8)
	v_and_b32_e32 v29, 0x7fffffff, v67
	v_and_b32_e32 v28, 0x7fffffff, v66
	v_and_b32_e32 v31, 0x7fffffff, v65
	v_and_b32_e32 v30, 0x7fffffff, v64
	v_readlane_b32 s0, v38, 27
	s_waitcnt vmcnt(3)
	v_and_b32_e32 v1, 0x7fffffff, v1
	v_pk_mul_f32 v[26:27], v[26:27], s[0:1] op_sel_hi:[1,0]
	v_pk_mul_f32 v[24:25], v[24:25], s[0:1] op_sel_hi:[1,0]
	v_pk_mul_f32 v[30:31], v[30:31], s[0:1] op_sel_hi:[1,0]
	v_pk_mul_f32 v[28:29], v[28:29], s[0:1] op_sel_hi:[1,0]
	v_max3_f32 v35, v35, v19, v25
	v_max3_f32 v34, v34, v18, v24
	v_max3_f32 v33, v33, v17, v27
	v_max3_f32 v32, v32, v16, v26
	v_max3_f32 v39, v39, v23, v29
	v_max3_f32 v40, v40, v22, v28
	v_max3_f32 v37, v37, v21, v31
	v_max3_f32 v36, v36, v20, v30
	v_and_b32_e32 v17, 0x7fffffff, v71
	v_and_b32_e32 v16, 0x7fffffff, v70
	v_and_b32_e32 v19, 0x7fffffff, v69
	v_and_b32_e32 v18, 0x7fffffff, v68
	v_and_b32_e32 v21, 0x7fffffff, v75
	v_and_b32_e32 v20, 0x7fffffff, v74
	v_and_b32_e32 v23, 0x7fffffff, v73
	v_and_b32_e32 v22, 0x7fffffff, v72
	v_readlane_b32 s0, v38, 28
	v_and_b32_e32 v25, 0x7fffffff, v77
	v_and_b32_e32 v24, 0x7fffffff, v76
	v_pk_mul_f32 v[18:19], v[18:19], s[0:1] op_sel_hi:[1,0]
	v_pk_mul_f32 v[16:17], v[16:17], s[0:1] op_sel_hi:[1,0]
	v_pk_mul_f32 v[22:23], v[22:23], s[0:1] op_sel_hi:[1,0]
	v_pk_mul_f32 v[20:21], v[20:21], s[0:1] op_sel_hi:[1,0]
	v_and_b32_e32 v27, 0x7fffffff, v79
	v_and_b32_e32 v26, 0x7fffffff, v78
	v_and_b32_e32 v29, 0x7fffffff, v81
	v_and_b32_e32 v28, 0x7fffffff, v80
	v_and_b32_e32 v31, 0x7fffffff, v83
	v_and_b32_e32 v30, 0x7fffffff, v82
	v_readlane_b32 s0, v38, 29
	v_and_b32_e32 v0, 0x7fffffff, v0
	v_and_b32_e32 v3, 0x7fffffff, v3
	v_pk_mul_f32 v[26:27], v[26:27], s[0:1] op_sel_hi:[1,0]
	v_pk_mul_f32 v[24:25], v[24:25], s[0:1] op_sel_hi:[1,0]
	v_pk_mul_f32 v[30:31], v[30:31], s[0:1] op_sel_hi:[1,0]
	v_pk_mul_f32 v[28:29], v[28:29], s[0:1] op_sel_hi:[1,0]
	v_and_b32_e32 v2, 0x7fffffff, v2
	s_waitcnt vmcnt(2)
	v_and_b32_e32 v5, 0x7fffffff, v5
	v_and_b32_e32 v4, 0x7fffffff, v4
	v_and_b32_e32 v7, 0x7fffffff, v7
	v_and_b32_e32 v6, 0x7fffffff, v6
	v_readlane_b32 s0, v38, 30
	s_waitcnt vmcnt(1)
	v_and_b32_e32 v11, 0x7fffffff, v11
	v_and_b32_e32 v10, 0x7fffffff, v10
	v_pk_mul_f32 v[2:3], v[2:3], s[0:1] op_sel_hi:[1,0]
	v_pk_mul_f32 v[0:1], v[0:1], s[0:1] op_sel_hi:[1,0]
	v_pk_mul_f32 v[6:7], v[6:7], s[0:1] op_sel_hi:[1,0]
	v_pk_mul_f32 v[4:5], v[4:5], s[0:1] op_sel_hi:[1,0]
	v_and_b32_e32 v9, 0x7fffffff, v9
	v_and_b32_e32 v8, 0x7fffffff, v8
	v_readlane_b32 s0, v38, 31
	v_max3_f32 v18, v32, v18, v24
	v_max3_f32 v19, v33, v19, v25
	v_max3_f32 v16, v34, v16, v26
	v_max3_f32 v17, v35, v17, v27
	s_waitcnt vmcnt(0)
	v_and_b32_e32 v15, 0x7fffffff, v15
	v_and_b32_e32 v14, 0x7fffffff, v14
	v_and_b32_e32 v13, 0x7fffffff, v13
	v_and_b32_e32 v12, 0x7fffffff, v12
	v_pk_mul_f32 v[8:9], v[8:9], s[0:1] op_sel_hi:[1,0]
	v_pk_mul_f32 v[10:11], v[10:11], s[0:1] op_sel_hi:[1,0]
	v_max3_f32 v22, v36, v22, v28
	v_max3_f32 v23, v37, v23, v29
	v_max3_f32 v20, v40, v20, v30
	v_max3_f32 v21, v39, v21, v31
	v_pk_mul_f32 v[12:13], v[12:13], s[0:1] op_sel_hi:[1,0]
	v_pk_mul_f32 v[14:15], v[14:15], s[0:1] op_sel_hi:[1,0]
	v_max3_f32 v3, v17, v3, v11
	v_max3_f32 v2, v16, v2, v10
	v_max3_f32 v1, v19, v1, v9
	v_max3_f32 v0, v18, v0, v8
	v_max3_f32 v7, v21, v7, v15
	v_max3_f32 v6, v20, v6, v14
	v_max3_f32 v5, v23, v5, v13
	v_max3_f32 v4, v22, v4, v12
	ds_write_b128 v57, v[0:3]
	ds_write_b128 v57, v[4:7] offset:1024
	s_waitcnt lgkmcnt(0)
	s_barrier
	ds_read2st64_b32 v[0:1], v58 offset1:8
	ds_read2st64_b32 v[2:3], v58 offset0:16 offset1:24
	ds_read2st64_b32 v[4:5], v58 offset0:32 offset1:40
	ds_read2st64_b32 v[6:7], v58 offset0:48 offset1:56
	s_waitcnt lgkmcnt(3)
	v_max_f32_e32 v1, v1, v1
	v_max_f32_e32 v0, v0, v0
	v_max_f32_e32 v0, v0, v1
	s_waitcnt lgkmcnt(2)
	v_max3_f32 v0, v0, v2, v3
	s_waitcnt lgkmcnt(1)
	v_max3_f32 v0, v0, v4, v5
	s_waitcnt lgkmcnt(0)
	v_max3_f32 v2, v0, v6, v7
	v_lshl_add_u64 v[0:1], v[46:47], 0, s[2:3]
	global_atomic_umax v[0:1], v2, off
	s_barrier
	s_mov_b64 s[2:3], 0
.LBB0_14:
	s_andn2_b64 vcc, exec, s[2:3]
	s_cbranch_vccnz .LBB0_16
	s_and_b32 s0, s14, 0xff
	s_mul_hi_u32 s0, s0, 0x15555556
	s_mulk_i32 s0, 0x1800
	s_sub_i32 s2, s13, s0
	s_mul_i32 s0, s82, 0xab
	s_addk_i32 s0, 0x3470
	s_lshr_b32 s0, s0, 3
	s_and_b32 s0, s0, 0x1f00
	s_add_i32 s0, s0, s8
	s_mul_hi_u32 s3, s0, 0xa000
	s_mul_i32 s0, s0, 0xa000
	s_add_u32 s0, s58, s0
	s_addc_u32 s36, s59, s3
	s_ashr_i32 s3, s2, 31
	s_lshl_b64 s[6:7], s[2:3], 2
	s_add_u32 s2, s0, s6
	s_addc_u32 s3, s36, s7
	v_lshl_add_u64 v[54:55], v[44:45], 2, s[2:3]
	s_movk_i32 s0, 0x2000
	v_add_co_u32_e32 v0, vcc, s0, v54
	s_mov_b32 s0, 0x16000
	s_nop 0
	v_addc_co_u32_e32 v1, vcc, 0, v55, vcc
	v_add_co_u32_e32 v12, vcc, s33, v54
	global_load_dwordx4 v[0:3], v[0:1], off nt
	s_nop 0
	v_addc_co_u32_e32 v13, vcc, 0, v55, vcc
	global_load_dwordx4 v[4:7], v[12:13], off nt
	v_add_co_u32_e32 v24, vcc, s0, v54
	v_lshl_add_u64 v[8:9], v[54:55], 0, s[4:5]
	s_nop 0
	v_addc_co_u32_e32 v25, vcc, 0, v55, vcc
	v_add_co_u32_e32 v28, vcc, s34, v54
	global_load_dwordx4 v[8:11], v[8:9], off offset:1024 nt
	s_nop 0
	global_load_dwordx4 v[12:15], v[12:13], off offset:1024 nt
	v_addc_co_u32_e32 v29, vcc, 0, v55, vcc
	global_load_dwordx4 v[16:19], v[28:29], off nt
	global_load_dwordx4 v[20:23], v[24:25], off nt
	s_nop 0
	global_load_dwordx4 v[24:27], v[24:25], off offset:1024 nt
	s_nop 0
	global_load_dwordx4 v[28:31], v[28:29], off offset:1024 nt
	s_mov_b32 s0, 0x2a000
	v_add_co_u32_e32 v40, vcc, s0, v54
	s_mov_b32 s0, 0x3e000
	s_nop 0
	v_addc_co_u32_e32 v41, vcc, 0, v55, vcc
	v_add_co_u32_e32 v60, vcc, s35, v54
	v_add_co_u32_e64 v108, s[2:3], s71, v54
	s_nop 0
	v_addc_co_u32_e32 v61, vcc, 0, v55, vcc
	v_add_co_u32_e32 v72, vcc, s0, v54
	s_mov_b32 s0, 0x52000
	s_nop 0
	v_addc_co_u32_e32 v73, vcc, 0, v55, vcc
	v_add_co_u32_e32 v76, vcc, s69, v54
	global_load_dwordx4 v[32:35], v[60:61], off nt
	global_load_dwordx4 v[36:39], v[40:41], off nt
	s_nop 0
	global_load_dwordx4 v[40:43], v[40:41], off offset:1024 nt
	s_nop 0
	global_load_dwordx4 v[60:63], v[60:61], off offset:1024 nt
	v_addc_co_u32_e32 v77, vcc, 0, v55, vcc
	v_add_co_u32_e32 v88, vcc, s0, v54
	s_mov_b32 s0, 0x66000
	s_nop 0
	v_addc_co_u32_e32 v89, vcc, 0, v55, vcc
	v_add_co_u32_e32 v92, vcc, s70, v54
	global_load_dwordx4 v[64:67], v[72:73], off nt
	global_load_dwordx4 v[68:71], v[76:77], off nt
	v_addc_co_u32_e32 v93, vcc, 0, v55, vcc
	v_add_co_u32_e32 v104, vcc, s0, v54
	s_mov_b32 s0, 0x7a000
	s_nop 0
	v_addc_co_u32_e32 v105, vcc, 0, v55, vcc
	v_addc_co_u32_e64 v109, vcc, 0, v55, s[2:3]
	global_load_dwordx4 v[72:75], v[72:73], off offset:1024 nt
	s_nop 0
	global_load_dwordx4 v[76:79], v[76:77], off offset:1024 nt
	s_nop 0
	global_load_dwordx4 v[80:83], v[88:89], off nt
	global_load_dwordx4 v[84:87], v[92:93], off nt
	s_nop 0
	global_load_dwordx4 v[88:91], v[88:89], off offset:1024 nt
	s_nop 0
	global_load_dwordx4 v[92:95], v[92:93], off offset:1024 nt
	s_nop 0
	global_load_dwordx4 v[96:99], v[104:105], off nt
	global_load_dwordx4 v[100:103], v[108:109], off nt
	s_nop 0
	global_load_dwordx4 v[104:107], v[104:105], off offset:1024 nt
	s_nop 0
	global_load_dwordx4 v[108:111], v[108:109], off offset:1024 nt
	s_waitcnt vmcnt(22)
	v_max3_f32 v4, |v0|, 0, |v4|
	v_add_co_u32_e32 v0, vcc, s0, v54
	v_max3_f32 v5, |v1|, 0, |v5|
	s_nop 0
	v_addc_co_u32_e32 v1, vcc, 0, v55, vcc
	s_mov_b32 s0, 0x84000
	v_max3_f32 v6, |v2|, 0, |v6|
	v_add_co_u32_e32 v2, vcc, s0, v54
	v_max3_f32 v7, |v3|, 0, |v7|
	s_nop 0
	v_addc_co_u32_e32 v3, vcc, 0, v55, vcc
	global_load_dwordx4 v[112:115], v[0:1], off nt
	global_load_dwordx4 v[116:119], v[2:3], off nt
	global_load_dwordx4 v[120:123], v[0:1], off offset:1024 nt
	global_load_dwordx4 v[124:127], v[2:3], off offset:1024 nt
	s_waitcnt vmcnt(24)
	v_max3_f32 v0, |v11|, 0, |v15|
	s_mov_b32 s0, 0x8e000
	s_waitcnt vmcnt(22)
	v_max3_f32 v2, v7, |v23|, |v19|
	v_max3_f32 v7, v4, |v20|, |v16|
	s_waitcnt vmcnt(20)
	v_max3_f32 v16, v0, |v27|, |v31|
	v_add_co_u32_e32 v0, vcc, s0, v54
	s_mov_b32 s0, 0x98000
	s_nop 0
	v_addc_co_u32_e32 v1, vcc, 0, v55, vcc
	v_add_co_u32_e32 v4, vcc, s0, v54
	v_max3_f32 v3, v6, |v22|, |v18|
	v_max3_f32 v6, v5, |v21|, |v17|
	v_addc_co_u32_e32 v5, vcc, 0, v55, vcc
	v_max3_f32 v52, |v8|, 0, |v12|
	v_max3_f32 v59, |v9|, 0, |v13|
	v_max3_f32 v128, |v10|, 0, |v14|
	global_load_dwordx4 v[8:11], v[0:1], off nt
	global_load_dwordx4 v[12:15], v[4:5], off nt
	s_mov_b32 s0, 0xa2000
	v_max3_f32 v19, v52, |v24|, |v28|
	v_add_co_u32_e32 v24, vcc, s0, v54
	v_max3_f32 v18, v59, |v25|, |v29|
	s_nop 0
	v_addc_co_u32_e32 v25, vcc, 0, v55, vcc
	v_add_co_u32_e32 v28, vcc, s72, v54
	s_mov_b32 s0, 0xb6000
	s_nop 0
	v_addc_co_u32_e32 v29, vcc, 0, v55, vcc
	s_waitcnt vmcnt(18)
	v_max3_f32 v19, v19, |v40|, |v60|
	v_add_co_u32_e32 v40, vcc, s0, v54
	v_max3_f32 v18, v18, |v41|, |v61|
	s_nop 0
	v_addc_co_u32_e32 v41, vcc, 0, v55, vcc
	s_mov_b32 s0, 0xc0000
	v_add_co_u32_e32 v60, vcc, s0, v54
	v_max3_f32 v3, v3, |v38|, |v34|
	s_nop 0
	v_addc_co_u32_e32 v61, vcc, 0, v55, vcc
	s_mov_b32 s0, 0xca000
	v_max3_f32 v2, v2, |v39|, |v35|
	s_waitcnt vmcnt(16)
	v_max3_f32 v3, v3, |v66|, |v70|
	s_waitcnt vmcnt(14)
	v_max3_f32 v19, v19, |v72|, |v76|
	v_add_co_u32_e32 v72, vcc, s0, v54
	v_max3_f32 v17, v128, |v26|, |v30|
	v_max3_f32 v2, v2, |v67|, |v71|
	v_max3_f32 v18, v18, |v73|, |v77|
	s_waitcnt vmcnt(12)
	v_max3_f32 v30, v3, |v82|, |v86|
	v_addc_co_u32_e32 v73, vcc, 0, v55, vcc
	s_mov_b32 s0, 0xd4000
	v_max3_f32 v17, v17, |v42|, |v62|
	v_max3_f32 v16, v16, |v43|, |v63|
	v_max3_f32 v31, v2, |v83|, |v87|
	s_waitcnt vmcnt(8)
	v_max3_f32 v43, v30, |v98|, |v102|
	v_add_co_u32_e32 v76, vcc, s0, v54
	v_max3_f32 v17, v17, |v74|, |v78|
	v_max3_f32 v42, v31, |v99|, |v103|
	v_addc_co_u32_e32 v77, vcc, 0, v55, vcc
	s_mov_b32 s0, 0xde000
	v_max3_f32 v16, v16, |v75|, |v79|
	v_max3_f32 v7, v7, |v36|, |v32|
	v_max3_f32 v6, v6, |v37|, |v33|
	v_max3_f32 v6, v6, |v65|, |v69|
	v_max3_f32 v7, v7, |v64|, |v68|
	v_max3_f32 v32, v19, |v88|, |v92|
	v_max3_f32 v33, v18, |v89|, |v93|
	v_max3_f32 v34, v17, |v90|, |v94|
	v_max3_f32 v35, v16, |v91|, |v95|
	s_waitcnt vmcnt(4)
	v_max3_f32 v74, v43, |v114|, |v118|
	v_max3_f32 v75, v42, |v115|, |v119|
	v_max3_f32 v26, v7, |v80|, |v84|
	v_max3_f32 v27, v6, |v81|, |v85|
	v_max3_f32 v62, v35, |v107|, |v111|
	v_max3_f32 v63, v34, |v106|, |v110|
	v_max3_f32 v64, v33, |v105|, |v109|
	v_max3_f32 v65, v32, |v104|, |v108|
	global_load_dwordx4 v[0:3], v[0:1], off offset:1024 nt
	s_nop 0
	global_load_dwordx4 v[4:7], v[4:5], off offset:1024 nt
	v_max3_f32 v52, v27, |v97|, |v101|
	global_load_dwordx4 v[16:19], v[24:25], off nt
	global_load_dwordx4 v[20:23], v[28:29], off nt
	v_max3_f32 v59, v26, |v96|, |v100|
	global_load_dwordx4 v[24:27], v[24:25], off offset:1024 nt
	s_nop 0
	global_load_dwordx4 v[28:31], v[28:29], off offset:1024 nt
	s_waitcnt vmcnt(8)
	v_max3_f32 v152, v65, |v120|, |v124|
	global_load_dwordx4 v[32:35], v[40:41], off nt
	global_load_dwordx4 v[36:39], v[60:61], off nt
	v_max3_f32 v153, v64, |v121|, |v125|
	v_max3_f32 v154, v63, |v122|, |v126|
	v_max3_f32 v155, v62, |v123|, |v127|
	global_load_dwordx4 v[40:43], v[40:41], off offset:1024 nt
	s_nop 0
	global_load_dwordx4 v[60:63], v[60:61], off offset:1024 nt
	v_max3_f32 v59, v59, |v112|, |v116|
	s_waitcnt vmcnt(10)
	v_max3_f32 v157, v74, |v10|, |v14|
	v_add_co_u32_e32 v10, vcc, s0, v54
	v_max3_f32 v156, v75, |v11|, |v15|
	s_nop 0
	v_addc_co_u32_e32 v11, vcc, 0, v55, vcc
	s_mov_b32 s0, 0xe8000
	v_add_co_u32_e32 v14, vcc, s0, v54
	s_mov_b32 s0, 0xf2000
	s_nop 0
	v_addc_co_u32_e32 v15, vcc, 0, v55, vcc
	global_load_dwordx4 v[64:67], v[72:73], off nt
	global_load_dwordx4 v[68:71], v[76:77], off nt
	s_nop 0
	global_load_dwordx4 v[72:75], v[72:73], off offset:1024 nt
	s_nop 0
	global_load_dwordx4 v[76:79], v[76:77], off offset:1024 nt
	v_max3_f32 v52, v52, |v113|, |v117|
	global_load_dwordx4 v[80:83], v[10:11], off nt
	global_load_dwordx4 v[84:87], v[14:15], off nt
	global_load_dwordx4 v[88:91], v[10:11], off offset:1024 nt
	global_load_dwordx4 v[92:95], v[14:15], off offset:1024 nt
	v_add_co_u32_e32 v10, vcc, s0, v54
	s_mov_b32 s0, 0xfc000
	s_nop 0
	v_addc_co_u32_e32 v11, vcc, 0, v55, vcc
	v_add_co_u32_e32 v14, vcc, s0, v54
	s_mov_b32 s0, 0x106000
	s_nop 0
	v_addc_co_u32_e32 v15, vcc, 0, v55, vcc
	global_load_dwordx4 v[96:99], v[10:11], off nt
	global_load_dwordx4 v[100:103], v[14:15], off nt
	global_load_dwordx4 v[104:107], v[10:11], off offset:1024 nt
	global_load_dwordx4 v[108:111], v[14:15], off offset:1024 nt
	v_add_co_u32_e32 v10, vcc, s0, v54
	s_mov_b32 s0, 0x110000
	s_nop 0
	v_addc_co_u32_e32 v11, vcc, 0, v55, vcc
	global_load_dwordx4 v[112:115], v[10:11], off nt
	global_load_dwordx4 v[116:119], v[10:11], off offset:1024 nt
	v_add_co_u32_e32 v10, vcc, s0, v54
	s_mov_b32 s0, 0x11a000
	s_nop 0
	v_addc_co_u32_e32 v11, vcc, 0, v55, vcc
	global_load_dwordx4 v[120:123], v[10:11], off nt
	global_load_dwordx4 v[124:127], v[10:11], off offset:1024 nt
	v_add_co_u32_e32 v10, vcc, s0, v54
	s_mov_b32 s0, 0x124000
	s_nop 0
	v_addc_co_u32_e32 v11, vcc, 0, v55, vcc
	global_load_dwordx4 v[128:131], v[10:11], off nt
	global_load_dwordx4 v[132:135], v[10:11], off offset:1024 nt
	v_add_co_u32_e32 v10, vcc, s0, v54
	s_mov_b32 s0, 0x12e000
	s_nop 0
	v_addc_co_u32_e32 v11, vcc, 0, v55, vcc
	global_load_dwordx4 v[136:139], v[10:11], off nt
	global_load_dwordx4 v[140:143], v[10:11], off offset:1024 nt
	v_add_co_u32_e32 v10, vcc, s0, v54
	s_mov_b32 s0, 0x138000
	s_nop 0
	v_addc_co_u32_e32 v11, vcc, 0, v55, vcc
	v_add_co_u32_e32 v14, vcc, s0, v54
	global_load_dwordx4 v[144:147], v[10:11], off nt
	s_nop 0
	v_addc_co_u32_e32 v15, vcc, 0, v55, vcc
	global_load_dwordx4 v[148:151], v[14:15], off nt
	v_max3_f32 v52, v52, |v9|, |v13|
	v_max3_f32 v54, v59, |v8|, |v12|
	global_load_dwordx4 v[8:11], v[10:11], off offset:1024 nt
	s_nop 0
	global_load_dwordx4 v[12:15], v[14:15], off offset:1024 nt
	s_waitcnt vmcnt(32)
	v_max3_f32 v3, v155, |v3|, |v7|
	v_max3_f32 v2, v154, |v2|, |v6|
	v_max3_f32 v1, v153, |v1|, |v5|
	v_max3_f32 v0, v152, |v0|, |v4|
	s_waitcnt vmcnt(30)
	v_max3_f32 v4, v54, |v16|, |v20|
	v_max3_f32 v5, v52, |v17|, |v21|
	v_max3_f32 v6, v157, |v18|, |v22|
	v_max3_f32 v7, v156, |v19|, |v23|
	s_waitcnt vmcnt(28)
	v_max3_f32 v0, v0, |v24|, |v28|
	v_max3_f32 v1, v1, |v25|, |v29|
	v_max3_f32 v2, v2, |v26|, |v30|
	v_max3_f32 v3, v3, |v27|, |v31|
	s_waitcnt vmcnt(26)
	v_max3_f32 v7, v7, |v35|, |v39|
	v_max3_f32 v6, v6, |v34|, |v38|
	v_max3_f32 v5, v5, |v33|, |v37|
	v_max3_f32 v4, v4, |v32|, |v36|
	s_waitcnt vmcnt(24)
	v_max3_f32 v3, v3, |v43|, |v63|
	v_max3_f32 v2, v2, |v42|, |v62|
	v_max3_f32 v1, v1, |v41|, |v61|
	v_max3_f32 v0, v0, |v40|, |v60|
	s_waitcnt vmcnt(22)
	v_max3_f32 v4, v4, |v64|, |v68|
	v_max3_f32 v5, v5, |v65|, |v69|
	v_max3_f32 v6, v6, |v66|, |v70|
	v_max3_f32 v7, v7, |v67|, |v71|
	s_waitcnt vmcnt(20)
	v_max3_f32 v0, v0, |v72|, |v76|
	v_max3_f32 v1, v1, |v73|, |v77|
	v_max3_f32 v2, v2, |v74|, |v78|
	v_max3_f32 v3, v3, |v75|, |v79|
	s_waitcnt vmcnt(18)
	v_max3_f32 v7, v7, |v83|, |v87|
	v_max3_f32 v6, v6, |v82|, |v86|
	v_max3_f32 v5, v5, |v81|, |v85|
	v_max3_f32 v4, v4, |v80|, |v84|
	s_waitcnt vmcnt(16)
	v_max3_f32 v3, v3, |v91|, |v95|
	v_max3_f32 v2, v2, |v90|, |v94|
	v_max3_f32 v1, v1, |v89|, |v93|
	v_max3_f32 v0, v0, |v88|, |v92|
	s_waitcnt vmcnt(14)
	v_max3_f32 v4, v4, |v96|, |v100|
	v_max3_f32 v5, v5, |v97|, |v101|
	v_max3_f32 v6, v6, |v98|, |v102|
	v_max3_f32 v7, v7, |v99|, |v103|
	s_waitcnt vmcnt(12)
	v_max3_f32 v0, v0, |v104|, |v108|
	v_max3_f32 v1, v1, |v105|, |v109|
	v_max3_f32 v2, v2, |v106|, |v110|
	v_max3_f32 v3, v3, |v107|, |v111|
	s_waitcnt vmcnt(9)
	v_max3_f32 v7, v7, |v115|, |v123|
	v_max3_f32 v6, v6, |v114|, |v122|
	v_max3_f32 v5, v5, |v113|, |v121|
	v_max3_f32 v4, v4, |v112|, |v120|
	s_waitcnt vmcnt(8)
	v_max3_f32 v3, v3, |v119|, |v127|
	v_max3_f32 v2, v2, |v118|, |v126|
	v_max3_f32 v1, v1, |v117|, |v125|
	v_max3_f32 v0, v0, |v116|, |v124|
	s_waitcnt vmcnt(5)
	v_max3_f32 v4, v4, |v128|, |v136|
	v_max3_f32 v5, v5, |v129|, |v137|
	v_max3_f32 v6, v6, |v130|, |v138|
	v_max3_f32 v7, v7, |v131|, |v139|
	s_waitcnt vmcnt(4)
	v_max3_f32 v16, v0, |v132|, |v140|
	v_max3_f32 v17, v1, |v133|, |v141|
	v_max3_f32 v18, v2, |v134|, |v142|
	v_max3_f32 v19, v3, |v135|, |v143|
	s_waitcnt vmcnt(2)
	v_max3_f32 v3, v7, |v147|, |v151|
	v_max3_f32 v2, v6, |v146|, |v150|
	v_max3_f32 v1, v5, |v145|, |v149|
	v_max3_f32 v0, v4, |v144|, |v148|
	s_waitcnt vmcnt(0)
	v_max3_f32 v7, v19, |v11|, |v15|
	v_max3_f32 v6, v18, |v10|, |v14|
	v_max3_f32 v5, v17, |v9|, |v13|
	v_max3_f32 v4, v16, |v8|, |v12|
	ds_write_b128 v57, v[0:3]
	ds_write_b128 v57, v[4:7] offset:1024
	s_waitcnt lgkmcnt(0)
	s_barrier
	ds_read2st64_b32 v[0:1], v58 offset1:8
	ds_read2st64_b32 v[2:3], v58 offset0:16 offset1:24
	ds_read2st64_b32 v[4:5], v58 offset0:32 offset1:40
	ds_read2st64_b32 v[6:7], v58 offset0:48 offset1:56
	s_waitcnt lgkmcnt(3)
	v_max_f32_e32 v1, v1, v1
	v_max_f32_e32 v0, v0, v0
	v_max_f32_e32 v0, v0, v1
	s_waitcnt lgkmcnt(2)
	v_max3_f32 v0, v0, v2, v3
	s_waitcnt lgkmcnt(1)
	v_max3_f32 v0, v0, v4, v5
	s_waitcnt lgkmcnt(0)
	v_max3_f32 v2, v0, v6, v7
	v_lshl_add_u64 v[0:1], v[48:49], 0, s[6:7]
	global_atomic_umax v[0:1], v2, off
	s_barrier

.LBB0_17:
	s_andn2_b64 vcc, exec, s[2:3]
	s_cbranch_vccnz .LBB0_10
	s_mul_hi_i32 s0, s82, 0x2fa0be83
	s_lshr_b32 s2, s0, 31
	s_ashr_i32 s0, s0, 3
	s_add_i32 s0, s0, s2
	s_lshl_b32 s2, s0, 8
	s_add_i32 s7, s2, s8
	v_readlane_b32 s36, v251, 21
	s_mul_i32 s3, s7, 0x15800
	v_readlane_b32 s48, v251, 33
	s_mul_hi_i32 s2, s7, 0x15800
	v_readlane_b32 s49, v251, 34
	s_add_u32 s6, s48, s3
	s_mulk_i32 s0, 0xaa00
	s_addc_u32 s36, s49, s2
	s_add_i32 s2, s9, s0
	s_ashr_i32 s3, s2, 31
	s_lshl_b64 s[2:3], s[2:3], 2
	v_or_b32_e32 v0, s7, v56
	v_readlane_b32 s46, v251, 31
	v_readlane_b32 s47, v251, 32
	s_add_u32 s6, s6, s2
	v_ashrrev_i32_e32 v1, 31, v0
	v_lshl_add_u64 v[0:1], v[0:1], 2, s[46:47]
	s_addc_u32 s7, s36, s3
	global_load_dword v52, v[0:1], off nt
	v_lshl_add_u64 v[0:1], v[44:45], 2, s[6:7]
	s_mov_b32 s0, 0x15000
	v_add_co_u32_e32 v2, vcc, s0, v0
	global_load_dwordx4 v[4:7], v[0:1], off nt
	global_load_dwordx4 v[8:11], v[0:1], off offset:1024 nt
	v_addc_co_u32_e32 v3, vcc, 0, v1, vcc
	global_load_dwordx4 v[12:15], v[2:3], off offset:2048 nt
	global_load_dwordx4 v[16:19], v[2:3], off offset:3072 nt
	s_mov_b32 s0, 0x2b000
	v_add_co_u32_e32 v2, vcc, s0, v0
	s_mov_b32 s0, 0x56000
	s_nop 0
	v_addc_co_u32_e32 v3, vcc, 0, v1, vcc
	global_load_dwordx4 v[20:23], v[2:3], off nt
	global_load_dwordx4 v[24:27], v[2:3], off offset:1024 nt
	v_add_co_u32_e32 v2, vcc, s68, v0
	v_readlane_b32 s37, v251, 22
	s_nop 0
	v_addc_co_u32_e32 v3, vcc, 0, v1, vcc
	global_load_dwordx4 v[28:31], v[2:3], off offset:2048 nt
	global_load_dwordx4 v[32:35], v[2:3], off offset:3072 nt
	v_add_co_u32_e32 v2, vcc, s0, v0
	s_mov_b32 s0, 0x6b000
	s_nop 0
	v_addc_co_u32_e32 v3, vcc, 0, v1, vcc
	v_add_co_u32_e32 v54, vcc, s0, v0
	s_mov_b32 s0, 0x81000
	s_nop 0
	v_addc_co_u32_e32 v55, vcc, 0, v1, vcc
	v_add_co_u32_e32 v72, vcc, s0, v0
	s_mov_b32 s0, 0x96000
	s_nop 0
	v_addc_co_u32_e32 v73, vcc, 0, v1, vcc
	global_load_dwordx4 v[36:39], v[2:3], off nt
	global_load_dwordx4 v[40:43], v[2:3], off offset:1024 nt
	global_load_dwordx4 v[60:63], v[54:55], off offset:2048 nt
	global_load_dwordx4 v[64:67], v[54:55], off offset:3072 nt
	global_load_dwordx4 v[68:71], v[72:73], off nt
	s_nop 0
	global_load_dwordx4 v[72:75], v[72:73], off offset:1024 nt
	v_add_co_u32_e32 v76, vcc, s0, v0
	v_readlane_b32 s38, v251, 23
	s_nop 0
	v_addc_co_u32_e32 v77, vcc, 0, v1, vcc
	v_readlane_b32 s39, v251, 24
	v_readlane_b32 s40, v251, 25
	v_readlane_b32 s41, v251, 26
	v_readlane_b32 s42, v251, 27
	v_readlane_b32 s43, v251, 28
	v_readlane_b32 s44, v251, 29
	v_readlane_b32 s45, v251, 30
	v_readlane_b32 s50, v251, 35
	v_readlane_b32 s51, v251, 36
	s_waitcnt vmcnt(14)
	v_and_b32_e32 v2, 0x7fffffff, v52
	s_nop 0
	v_readlane_b32 s0, v2, 0
	v_readlane_b32 s6, v2, 1
	s_waitcnt vmcnt(13)
	v_and_b32_e32 v7, 0x7fffffff, v7
	v_and_b32_e32 v6, 0x7fffffff, v6
	v_and_b32_e32 v5, 0x7fffffff, v5
	v_and_b32_e32 v4, 0x7fffffff, v4
	s_waitcnt vmcnt(12)
	v_and_b32_e32 v11, 0x7fffffff, v11
	v_and_b32_e32 v10, 0x7fffffff, v10
	v_and_b32_e32 v9, 0x7fffffff, v9
	v_and_b32_e32 v8, 0x7fffffff, v8
	s_waitcnt vmcnt(11)
	v_and_b32_e32 v13, 0x7fffffff, v13
	v_and_b32_e32 v12, 0x7fffffff, v12
	v_and_b32_e32 v15, 0x7fffffff, v15
	v_and_b32_e32 v14, 0x7fffffff, v14
	s_waitcnt vmcnt(10)
	v_and_b32_e32 v17, 0x7fffffff, v17
	v_and_b32_e32 v16, 0x7fffffff, v16
	v_and_b32_e32 v19, 0x7fffffff, v19
	v_and_b32_e32 v18, 0x7fffffff, v18
	v_pk_mul_f32 v[4:5], v[4:5], s[0:1] op_sel_hi:[1,0]
	v_pk_mul_f32 v[6:7], v[6:7], s[0:1] op_sel_hi:[1,0]
	v_pk_mul_f32 v[8:9], v[8:9], s[0:1] op_sel_hi:[1,0]
	v_pk_mul_f32 v[10:11], v[10:11], s[0:1] op_sel_hi:[1,0]
	v_pk_mul_f32 v[12:13], v[12:13], s[6:7] op_sel_hi:[1,0]
	v_pk_mul_f32 v[14:15], v[14:15], s[6:7] op_sel_hi:[1,0]
	v_pk_mul_f32 v[18:19], v[18:19], s[6:7] op_sel_hi:[1,0]
	v_pk_mul_f32 v[16:17], v[16:17], s[6:7] op_sel_hi:[1,0]
	v_max3_f32 v3, v4, 0, v12
	v_max3_f32 v52, v5, 0, v13
	v_max3_f32 v54, v6, 0, v14
	v_max3_f32 v55, v7, 0, v15
	v_max3_f32 v59, v8, 0, v16
	v_max3_f32 v78, v9, 0, v17
	v_max3_f32 v79, v10, 0, v18
	v_max3_f32 v80, v11, 0, v19
	global_load_dwordx4 v[4:7], v[76:77], off offset:2048 nt
	global_load_dwordx4 v[8:11], v[76:77], off offset:3072 nt
	s_waitcnt vmcnt(11)
	v_and_b32_e32 v13, 0x7fffffff, v21
	v_and_b32_e32 v12, 0x7fffffff, v20
	v_and_b32_e32 v15, 0x7fffffff, v23
	v_and_b32_e32 v14, 0x7fffffff, v22
	s_waitcnt vmcnt(9)
	v_and_b32_e32 v17, 0x7fffffff, v31
	v_and_b32_e32 v16, 0x7fffffff, v30
	v_and_b32_e32 v19, 0x7fffffff, v29
	v_and_b32_e32 v18, 0x7fffffff, v28
	v_add_co_u32_e32 v28, vcc, s72, v0
	v_readlane_b32 s0, v2, 2
	v_readlane_b32 s6, v2, 3
	v_addc_co_u32_e32 v29, vcc, 0, v1, vcc
	v_pk_mul_f32 v[14:15], v[14:15], s[0:1] op_sel_hi:[1,0]
	v_pk_mul_f32 v[12:13], v[12:13], s[0:1] op_sel_hi:[1,0]
	v_pk_mul_f32 v[18:19], v[18:19], s[6:7] op_sel_hi:[1,0]
	v_pk_mul_f32 v[16:17], v[16:17], s[6:7] op_sel_hi:[1,0]
	s_mov_b32 s7, 0xc1000
	v_and_b32_e32 v21, 0x7fffffff, v25
	v_and_b32_e32 v20, 0x7fffffff, v24
	v_and_b32_e32 v23, 0x7fffffff, v27
	v_and_b32_e32 v22, 0x7fffffff, v26
	s_waitcnt vmcnt(8)
	v_and_b32_e32 v25, 0x7fffffff, v35
	v_and_b32_e32 v24, 0x7fffffff, v34
	v_and_b32_e32 v27, 0x7fffffff, v33
	v_and_b32_e32 v26, 0x7fffffff, v32
	v_max3_f32 v76, v55, v15, v17
	v_max3_f32 v77, v54, v14, v16
	v_max3_f32 v52, v52, v13, v19
	v_max3_f32 v3, v3, v12, v18
	global_load_dwordx4 v[12:15], v[28:29], off nt
	global_load_dwordx4 v[16:19], v[28:29], off offset:1024 nt
	v_add_co_u32_e32 v28, vcc, s7, v0
	v_pk_mul_f32 v[22:23], v[22:23], s[0:1] op_sel_hi:[1,0]
	s_nop 0
	v_addc_co_u32_e32 v29, vcc, 0, v1, vcc
	v_pk_mul_f32 v[20:21], v[20:21], s[0:1] op_sel_hi:[1,0]
	v_pk_mul_f32 v[26:27], v[26:27], s[6:7] op_sel_hi:[1,0]
	v_pk_mul_f32 v[24:25], v[24:25], s[6:7] op_sel_hi:[1,0]
	v_max3_f32 v78, v78, v21, v27
	v_max3_f32 v80, v80, v23, v25
	v_max3_f32 v79, v79, v22, v24
	v_max3_f32 v59, v59, v20, v26
	global_load_dwordx4 v[20:23], v[28:29], off offset:2048 nt
	global_load_dwordx4 v[24:27], v[28:29], off offset:3072 nt
	s_mov_b32 s0, 0xd7000
	s_waitcnt vmcnt(11)
	v_and_b32_e32 v31, 0x7fffffff, v39
	v_and_b32_e32 v30, 0x7fffffff, v38
	v_and_b32_e32 v33, 0x7fffffff, v37
	v_and_b32_e32 v32, 0x7fffffff, v36
	s_waitcnt vmcnt(10)
	v_and_b32_e32 v39, 0x7fffffff, v41
	v_and_b32_e32 v38, 0x7fffffff, v40
	s_waitcnt vmcnt(9)
	v_and_b32_e32 v35, 0x7fffffff, v61
	v_and_b32_e32 v34, 0x7fffffff, v60
	v_and_b32_e32 v41, 0x7fffffff, v63
	v_and_b32_e32 v40, 0x7fffffff, v62
	v_add_co_u32_e32 v60, vcc, s0, v0
	v_readlane_b32 s0, v2, 4
	v_readlane_b32 s6, v2, 5
	v_addc_co_u32_e32 v61, vcc, 0, v1, vcc
	v_pk_mul_f32 v[28:29], v[32:33], s[0:1] op_sel_hi:[1,0]
	v_pk_mul_f32 v[32:33], v[40:41], s[6:7] op_sel_hi:[1,0]
	v_pk_mul_f32 v[34:35], v[34:35], s[6:7] op_sel_hi:[1,0]
	s_mov_b32 s7, 0xec000
	v_and_b32_e32 v37, 0x7fffffff, v43
	v_and_b32_e32 v36, 0x7fffffff, v42
	s_waitcnt vmcnt(8)
	v_and_b32_e32 v43, 0x7fffffff, v65
	v_and_b32_e32 v42, 0x7fffffff, v64
	v_add_co_u32_e32 v40, vcc, s7, v0
	v_pk_mul_f32 v[30:31], v[30:31], s[0:1] op_sel_hi:[1,0]
	s_nop 0
	v_addc_co_u32_e32 v41, vcc, 0, v1, vcc
	v_pk_mul_f32 v[38:39], v[38:39], s[0:1] op_sel_hi:[1,0]
	v_pk_mul_f32 v[42:43], v[42:43], s[6:7] op_sel_hi:[1,0]
	v_and_b32_e32 v55, 0x7fffffff, v67
	v_and_b32_e32 v54, 0x7fffffff, v66
	v_max3_f32 v3, v3, v28, v34
	v_max3_f32 v52, v52, v29, v35
	v_max3_f32 v77, v77, v30, v32
	v_max3_f32 v76, v76, v31, v33
	global_load_dwordx4 v[28:31], v[60:61], off nt
	global_load_dwordx4 v[32:35], v[60:61], off offset:1024 nt
	v_max3_f32 v59, v59, v38, v42
	v_max3_f32 v78, v78, v39, v43
	s_waitcnt vmcnt(7)
	v_and_b32_e32 v43, 0x7fffffff, v7
	v_and_b32_e32 v42, 0x7fffffff, v6
	v_and_b32_e32 v63, 0x7fffffff, v5
	v_and_b32_e32 v62, 0x7fffffff, v4
	s_waitcnt vmcnt(6)
	v_and_b32_e32 v65, 0x7fffffff, v11
	v_and_b32_e32 v64, 0x7fffffff, v10
	v_and_b32_e32 v67, 0x7fffffff, v9
	v_and_b32_e32 v66, 0x7fffffff, v8
	global_load_dwordx4 v[4:7], v[40:41], off offset:2048 nt
	global_load_dwordx4 v[8:11], v[40:41], off offset:3072 nt
	v_pk_mul_f32 v[36:37], v[36:37], s[0:1] op_sel_hi:[1,0]
	v_pk_mul_f32 v[54:55], v[54:55], s[6:7] op_sel_hi:[1,0]
	s_mov_b32 s0, 0x102000
	v_max3_f32 v79, v79, v36, v54
	v_max3_f32 v80, v80, v37, v55
	v_and_b32_e32 v37, 0x7fffffff, v69
	v_and_b32_e32 v36, 0x7fffffff, v68
	v_and_b32_e32 v39, 0x7fffffff, v71
	v_and_b32_e32 v38, 0x7fffffff, v70
	v_add_co_u32_e32 v40, vcc, s0, v0
	v_readlane_b32 s0, v2, 6
	v_readlane_b32 s6, v2, 7
	v_addc_co_u32_e32 v41, vcc, 0, v1, vcc
	v_pk_mul_f32 v[38:39], v[38:39], s[0:1] op_sel_hi:[1,0]
	v_pk_mul_f32 v[36:37], v[36:37], s[0:1] op_sel_hi:[1,0]
	v_pk_mul_f32 v[62:63], v[62:63], s[6:7] op_sel_hi:[1,0]
	v_pk_mul_f32 v[42:43], v[42:43], s[6:7] op_sel_hi:[1,0]
	v_and_b32_e32 v61, 0x7fffffff, v75
	v_and_b32_e32 v60, 0x7fffffff, v74
	v_max3_f32 v74, v76, v39, v43
	v_max3_f32 v75, v77, v38, v42
	v_max3_f32 v52, v52, v37, v63
	v_max3_f32 v3, v3, v36, v62
	global_load_dwordx4 v[36:39], v[40:41], off nt
	s_nop 0
	global_load_dwordx4 v[40:43], v[40:41], off offset:1024 nt
	s_mov_b32 s7, 0x117000
	v_and_b32_e32 v55, 0x7fffffff, v73
	v_and_b32_e32 v54, 0x7fffffff, v72
	v_add_co_u32_e32 v68, vcc, s7, v0
	v_pk_mul_f32 v[60:61], v[60:61], s[0:1] op_sel_hi:[1,0]
	s_nop 0
	v_addc_co_u32_e32 v69, vcc, 0, v1, vcc
	v_pk_mul_f32 v[62:63], v[64:65], s[6:7] op_sel_hi:[1,0]
	v_pk_mul_f32 v[54:55], v[54:55], s[0:1] op_sel_hi:[1,0]
	v_pk_mul_f32 v[64:65], v[66:67], s[6:7] op_sel_hi:[1,0]
	s_mov_b32 s0, 0x12d000
	v_max3_f32 v78, v78, v55, v65
	v_max3_f32 v59, v59, v54, v64
	s_waitcnt vmcnt(9)
	v_and_b32_e32 v55, 0x7fffffff, v15
	v_and_b32_e32 v54, 0x7fffffff, v14
	v_and_b32_e32 v65, 0x7fffffff, v13
	v_and_b32_e32 v64, 0x7fffffff, v12
	s_waitcnt vmcnt(8)
	v_and_b32_e32 v67, 0x7fffffff, v19
	v_and_b32_e32 v66, 0x7fffffff, v18
	v_and_b32_e32 v71, 0x7fffffff, v17
	v_and_b32_e32 v70, 0x7fffffff, v16
	s_waitcnt vmcnt(7)
	v_and_b32_e32 v17, 0x7fffffff, v21
	v_and_b32_e32 v16, 0x7fffffff, v20
	v_and_b32_e32 v19, 0x7fffffff, v23
	v_and_b32_e32 v18, 0x7fffffff, v22
	v_add_co_u32_e32 v20, vcc, s0, v0
	v_readlane_b32 s0, v2, 8
	v_readlane_b32 s6, v2, 9
	v_max3_f32 v76, v80, v61, v63
	v_max3_f32 v77, v79, v60, v62
	global_load_dwordx4 v[60:63], v[68:69], off offset:2048 nt
	global_load_dwordx4 v[12:15], v[68:69], off offset:3072 nt
	s_waitcnt vmcnt(8)
	v_and_b32_e32 v73, 0x7fffffff, v27
	v_and_b32_e32 v72, 0x7fffffff, v26
	v_addc_co_u32_e32 v21, vcc, 0, v1, vcc
	v_pk_mul_f32 v[22:23], v[64:65], s[0:1] op_sel_hi:[1,0]
	v_pk_mul_f32 v[26:27], v[54:55], s[0:1] op_sel_hi:[1,0]
	v_pk_mul_f32 v[18:19], v[18:19], s[6:7] op_sel_hi:[1,0]
	v_pk_mul_f32 v[16:17], v[16:17], s[6:7] op_sel_hi:[1,0]
	v_max3_f32 v68, v75, v26, v18
	v_max3_f32 v3, v3, v22, v16
	v_max3_f32 v52, v52, v23, v17
	v_max3_f32 v69, v74, v27, v19
	global_load_dwordx4 v[16:19], v[20:21], off nt
	s_nop 0
	global_load_dwordx4 v[20:23], v[20:21], off offset:1024 nt
	s_mov_b32 s7, 0x142000
	v_and_b32_e32 v25, 0x7fffffff, v25
	v_and_b32_e32 v24, 0x7fffffff, v24
	v_add_co_u32_e32 v54, vcc, s7, v0
	v_pk_mul_f32 v[26:27], v[70:71], s[0:1] op_sel_hi:[1,0]
	s_nop 0
	v_addc_co_u32_e32 v55, vcc, 0, v1, vcc
	v_pk_mul_f32 v[24:25], v[24:25], s[6:7] op_sel_hi:[1,0]
	v_pk_mul_f32 v[64:65], v[66:67], s[0:1] op_sel_hi:[1,0]
	v_pk_mul_f32 v[66:67], v[72:73], s[6:7] op_sel_hi:[1,0]
	v_max3_f32 v59, v59, v26, v24
	v_max3_f32 v70, v78, v27, v25
	global_load_dwordx4 v[24:27], v[54:55], off offset:2048 nt
	v_max3_f32 v71, v77, v64, v66
	v_max3_f32 v72, v76, v65, v67
	s_waitcnt vmcnt(8)
	v_and_b32_e32 v65, 0x7fffffff, v7
	v_and_b32_e32 v64, 0x7fffffff, v6
	v_and_b32_e32 v67, 0x7fffffff, v5
	v_and_b32_e32 v66, 0x7fffffff, v4
	global_load_dwordx4 v[4:7], v[54:55], off offset:3072 nt
	v_and_b32_e32 v29, 0x7fffffff, v29
	v_and_b32_e32 v28, 0x7fffffff, v28
	v_and_b32_e32 v31, 0x7fffffff, v31
	v_and_b32_e32 v30, 0x7fffffff, v30
	v_and_b32_e32 v33, 0x7fffffff, v33
	v_and_b32_e32 v32, 0x7fffffff, v32
	v_and_b32_e32 v35, 0x7fffffff, v35
	v_and_b32_e32 v34, 0x7fffffff, v34
	v_readlane_b32 s0, v2, 10
	s_waitcnt vmcnt(8)
	v_and_b32_e32 v11, 0x7fffffff, v11
	v_and_b32_e32 v10, 0x7fffffff, v10
	v_and_b32_e32 v9, 0x7fffffff, v9
	v_and_b32_e32 v8, 0x7fffffff, v8
	v_pk_mul_f32 v[30:31], v[30:31], s[0:1] op_sel_hi:[1,0]
	v_pk_mul_f32 v[28:29], v[28:29], s[0:1] op_sel_hi:[1,0]
	v_pk_mul_f32 v[34:35], v[34:35], s[0:1] op_sel_hi:[1,0]
	v_pk_mul_f32 v[32:33], v[32:33], s[0:1] op_sel_hi:[1,0]
	v_readlane_b32 s0, v2, 11
	v_readlane_b32 s6, v2, 17
	s_waitcnt vmcnt(3)
	v_and_b32_e32 v17, 0x7fffffff, v17
	v_pk_mul_f32 v[54:55], v[66:67], s[0:1] op_sel_hi:[1,0]
	v_pk_mul_f32 v[64:65], v[64:65], s[0:1] op_sel_hi:[1,0]
	v_pk_mul_f32 v[8:9], v[8:9], s[0:1] op_sel_hi:[1,0]
	v_pk_mul_f32 v[10:11], v[10:11], s[0:1] op_sel_hi:[1,0]
	v_max3_f32 v66, v69, v31, v65
	v_max3_f32 v67, v68, v30, v64
	v_max3_f32 v52, v52, v29, v55
	v_max3_f32 v3, v3, v28, v54
	v_max3_f32 v68, v72, v35, v11
	v_max3_f32 v69, v71, v34, v10
	v_max3_f32 v70, v70, v33, v9
	v_max3_f32 v59, v59, v32, v8
	v_and_b32_e32 v9, 0x7fffffff, v39
	v_and_b32_e32 v8, 0x7fffffff, v38
	v_and_b32_e32 v11, 0x7fffffff, v37
	v_and_b32_e32 v10, 0x7fffffff, v36
	v_and_b32_e32 v29, 0x7fffffff, v43
	v_and_b32_e32 v28, 0x7fffffff, v42
	v_and_b32_e32 v31, 0x7fffffff, v41
	v_and_b32_e32 v30, 0x7fffffff, v40
	v_readlane_b32 s0, v2, 12
	v_and_b32_e32 v55, 0x7fffffff, v61
	v_and_b32_e32 v54, 0x7fffffff, v60
	v_pk_mul_f32 v[36:37], v[10:11], s[0:1] op_sel_hi:[1,0]
	v_pk_mul_f32 v[38:39], v[8:9], s[0:1] op_sel_hi:[1,0]
	v_pk_mul_f32 v[40:41], v[30:31], s[0:1] op_sel_hi:[1,0]
	v_pk_mul_f32 v[42:43], v[28:29], s[0:1] op_sel_hi:[1,0]
	s_mov_b32 s0, 0x158000
	v_add_co_u32_e32 v28, vcc, s0, v0
	s_mov_b32 s0, 0x16d000
	s_nop 0
	v_addc_co_u32_e32 v29, vcc, 0, v1, vcc
	v_and_b32_e32 v61, 0x7fffffff, v63
	v_and_b32_e32 v60, 0x7fffffff, v62
	v_and_b32_e32 v63, 0x7fffffff, v13
	v_and_b32_e32 v62, 0x7fffffff, v12
	v_and_b32_e32 v65, 0x7fffffff, v15
	v_add_co_u32_e32 v12, vcc, s0, v0
	v_and_b32_e32 v64, 0x7fffffff, v14
	v_readlane_b32 s0, v2, 13
	v_and_b32_e32 v16, 0x7fffffff, v16
	v_and_b32_e32 v19, 0x7fffffff, v19
	v_pk_mul_f32 v[60:61], v[60:61], s[0:1] op_sel_hi:[1,0]
	v_pk_mul_f32 v[54:55], v[54:55], s[0:1] op_sel_hi:[1,0]
	v_pk_mul_f32 v[64:65], v[64:65], s[0:1] op_sel_hi:[1,0]
	v_pk_mul_f32 v[62:63], v[62:63], s[0:1] op_sel_hi:[1,0]
	v_and_b32_e32 v18, 0x7fffffff, v18
	s_waitcnt vmcnt(2)
	v_and_b32_e32 v21, 0x7fffffff, v21
	v_and_b32_e32 v20, 0x7fffffff, v20
	v_and_b32_e32 v23, 0x7fffffff, v23
	v_and_b32_e32 v22, 0x7fffffff, v22
	v_readlane_b32 s0, v2, 14
	v_addc_co_u32_e32 v13, vcc, 0, v1, vcc
	v_max3_f32 v3, v3, v36, v54
	v_max3_f32 v52, v52, v37, v55
	v_max3_f32 v67, v67, v38, v60
	v_max3_f32 v66, v66, v39, v61
	v_max3_f32 v59, v59, v40, v62
	v_max3_f32 v70, v70, v41, v63
	v_max3_f32 v69, v69, v42, v64
	v_max3_f32 v68, v68, v43, v65
	v_pk_mul_f32 v[36:37], v[18:19], s[0:1] op_sel_hi:[1,0]
	v_pk_mul_f32 v[38:39], v[16:17], s[0:1] op_sel_hi:[1,0]
	v_pk_mul_f32 v[40:41], v[22:23], s[0:1] op_sel_hi:[1,0]
	v_pk_mul_f32 v[42:43], v[20:21], s[0:1] op_sel_hi:[1,0]
	s_mov_b32 s0, 0x183000
	v_add_co_u32_e32 v20, vcc, s0, v0
	s_mov_b32 s0, 0x198000
	s_nop 0
	v_addc_co_u32_e32 v21, vcc, 0, v1, vcc
	s_waitcnt vmcnt(0)
	v_and_b32_e32 v62, 0x7fffffff, v6
	v_add_co_u32_e32 v6, vcc, s0, v0
	v_and_b32_e32 v63, 0x7fffffff, v7
	s_nop 0
	v_addc_co_u32_e32 v7, vcc, 0, v1, vcc
	global_load_dwordx4 v[8:11], v[28:29], off nt
	global_load_dwordx4 v[16:19], v[20:21], off nt
	global_load_dwordx4 v[32:35], v[12:13], off offset:2048 nt
	v_and_b32_e32 v55, 0x7fffffff, v27
	v_and_b32_e32 v54, 0x7fffffff, v26
	v_and_b32_e32 v61, 0x7fffffff, v25
	v_and_b32_e32 v60, 0x7fffffff, v24
	global_load_dwordx4 v[24:27], v[6:7], off offset:2048 nt
	v_and_b32_e32 v65, 0x7fffffff, v5
	global_load_dwordx4 v[12:15], v[12:13], off offset:3072 nt
	v_and_b32_e32 v64, 0x7fffffff, v4
	global_load_dwordx4 v[28:31], v[28:29], off offset:1024 nt
	v_readlane_b32 s0, v2, 15
	global_load_dwordx4 v[4:7], v[6:7], off offset:3072 nt
	s_waitcnt vmcnt(2)
	v_and_b32_e32 v71, 0x7fffffff, v15
	v_pk_mul_f32 v[60:61], v[60:61], s[0:1] op_sel_hi:[1,0]
	v_pk_mul_f32 v[54:55], v[54:55], s[0:1] op_sel_hi:[1,0]
	v_pk_mul_f32 v[64:65], v[64:65], s[0:1] op_sel_hi:[1,0]
	v_pk_mul_f32 v[62:63], v[62:63], s[0:1] op_sel_hi:[1,0]
	s_mov_b32 s0, 0x1ae000
	global_load_dwordx4 v[20:23], v[20:21], off offset:1024 nt
	v_max3_f32 v75, v69, v40, v62
	v_add_co_u32_e32 v40, vcc, s0, v0
	v_max3_f32 v74, v68, v41, v63
	s_nop 0
	v_addc_co_u32_e32 v41, vcc, 0, v1, vcc
	s_mov_b32 s0, 0x1c3000
	v_max3_f32 v73, v67, v36, v54
	v_add_co_u32_e32 v54, vcc, s0, v0
	v_max3_f32 v72, v66, v37, v55
	s_nop 0
	v_addc_co_u32_e32 v55, vcc, 0, v1, vcc
	v_max3_f32 v52, v52, v39, v61
	v_max3_f32 v3, v3, v38, v60
	v_max3_f32 v76, v70, v43, v65
	v_max3_f32 v59, v59, v42, v64
	global_load_dwordx4 v[36:39], v[40:41], off nt
	s_nop 0
	global_load_dwordx4 v[40:43], v[40:41], off offset:1024 nt
	v_and_b32_e32 v61, 0x7fffffff, v11
	v_and_b32_e32 v60, 0x7fffffff, v10
	v_and_b32_e32 v63, 0x7fffffff, v9
	v_and_b32_e32 v62, 0x7fffffff, v8
	v_and_b32_e32 v69, 0x7fffffff, v13
	v_and_b32_e32 v68, 0x7fffffff, v12
	v_and_b32_e32 v70, 0x7fffffff, v14
	global_load_dwordx4 v[8:11], v[54:55], off offset:2048 nt
	global_load_dwordx4 v[12:15], v[54:55], off offset:3072 nt
	s_mov_b32 s0, 0x1d9000
	s_waitcnt vmcnt(6)
	v_and_b32_e32 v65, 0x7fffffff, v31
	v_and_b32_e32 v64, 0x7fffffff, v30
	v_and_b32_e32 v66, 0x7fffffff, v28
	v_and_b32_e32 v28, 0x7fffffff, v32
	v_and_b32_e32 v31, 0x7fffffff, v35
	v_and_b32_e32 v30, 0x7fffffff, v34
	v_add_co_u32_e32 v32, vcc, s0, v0
	v_readlane_b32 s0, v2, 16
	v_and_b32_e32 v67, 0x7fffffff, v29
	v_and_b32_e32 v29, 0x7fffffff, v33
	v_addc_co_u32_e32 v33, vcc, 0, v1, vcc
	v_pk_mul_f32 v[54:55], v[60:61], s[0:1] op_sel_hi:[1,0]
	v_pk_mul_f32 v[30:31], v[30:31], s[6:7] op_sel_hi:[1,0]
	v_pk_mul_f32 v[34:35], v[62:63], s[0:1] op_sel_hi:[1,0]
	v_max3_f32 v73, v73, v54, v30
	v_add_co_u32_e32 v54, vcc, s73, v0
	v_pk_mul_f32 v[28:29], v[28:29], s[6:7] op_sel_hi:[1,0]
	v_max3_f32 v72, v72, v55, v31
	v_addc_co_u32_e32 v55, vcc, 0, v1, vcc
	v_pk_mul_f32 v[60:61], v[66:67], s[0:1] op_sel_hi:[1,0]
	v_pk_mul_f32 v[62:63], v[64:65], s[0:1] op_sel_hi:[1,0]
	v_pk_mul_f32 v[64:65], v[70:71], s[6:7] op_sel_hi:[1,0]
	v_pk_mul_f32 v[66:67], v[68:69], s[6:7] op_sel_hi:[1,0]
	v_max3_f32 v3, v3, v34, v28
	v_max3_f32 v52, v52, v35, v29
	global_load_dwordx4 v[28:31], v[32:33], off nt
	s_nop 0
	global_load_dwordx4 v[32:35], v[32:33], off offset:1024 nt
	v_max3_f32 v59, v59, v60, v66
	v_max3_f32 v76, v76, v61, v67
	v_max3_f32 v75, v75, v62, v64
	v_max3_f32 v74, v74, v63, v65
	v_and_b32_e32 v61, 0x7fffffff, v17
	v_and_b32_e32 v60, 0x7fffffff, v16
	v_and_b32_e32 v63, 0x7fffffff, v19
	v_and_b32_e32 v62, 0x7fffffff, v18
	s_waitcnt vmcnt(7)
	v_and_b32_e32 v69, 0x7fffffff, v7
	v_and_b32_e32 v68, 0x7fffffff, v6
	v_and_b32_e32 v71, 0x7fffffff, v5
	v_and_b32_e32 v70, 0x7fffffff, v4
	global_load_dwordx4 v[4:7], v[54:55], off offset:2048 nt
	global_load_dwordx4 v[16:19], v[54:55], off offset:3072 nt
	v_readlane_b32 s0, v2, 18
	v_readlane_b32 s6, v2, 19
	s_waitcnt vmcnt(8)
	v_and_b32_e32 v67, 0x7fffffff, v23
	v_and_b32_e32 v66, 0x7fffffff, v22
	v_and_b32_e32 v23, 0x7fffffff, v25
	v_and_b32_e32 v22, 0x7fffffff, v24
	v_add_co_u32_e32 v24, vcc, s74, v0
	v_and_b32_e32 v65, 0x7fffffff, v21
	v_and_b32_e32 v64, 0x7fffffff, v20
	v_and_b32_e32 v21, 0x7fffffff, v27
	v_and_b32_e32 v20, 0x7fffffff, v26
	v_addc_co_u32_e32 v25, vcc, 0, v1, vcc
	v_pk_mul_f32 v[54:55], v[60:61], s[0:1] op_sel_hi:[1,0]
	v_pk_mul_f32 v[22:23], v[22:23], s[6:7] op_sel_hi:[1,0]
	v_pk_mul_f32 v[26:27], v[62:63], s[0:1] op_sel_hi:[1,0]
	v_pk_mul_f32 v[20:21], v[20:21], s[6:7] op_sel_hi:[1,0]
	v_max3_f32 v3, v3, v54, v22
	v_add_co_u32_e32 v54, vcc, s75, v0
	v_max3_f32 v72, v72, v27, v21
	v_max3_f32 v73, v73, v26, v20
	v_max3_f32 v52, v52, v55, v23
	global_load_dwordx4 v[20:23], v[24:25], off nt
	s_nop 0
	global_load_dwordx4 v[24:27], v[24:25], off offset:1024 nt
	v_addc_co_u32_e32 v55, vcc, 0, v1, vcc
	v_pk_mul_f32 v[60:61], v[66:67], s[0:1] op_sel_hi:[1,0]
	v_pk_mul_f32 v[62:63], v[64:65], s[0:1] op_sel_hi:[1,0]
	v_pk_mul_f32 v[64:65], v[70:71], s[6:7] op_sel_hi:[1,0]
	v_pk_mul_f32 v[66:67], v[68:69], s[6:7] op_sel_hi:[1,0]
	v_max3_f32 v70, v76, v63, v65
	v_max3_f32 v68, v74, v61, v67
	v_max3_f32 v69, v75, v60, v66
	v_max3_f32 v59, v59, v62, v64
	s_waitcnt vmcnt(8)
	v_and_b32_e32 v61, 0x7fffffff, v43
	v_and_b32_e32 v60, 0x7fffffff, v42
	v_and_b32_e32 v63, 0x7fffffff, v41
	v_and_b32_e32 v62, 0x7fffffff, v40
	s_waitcnt vmcnt(7)
	v_and_b32_e32 v41, 0x7fffffff, v9
	v_and_b32_e32 v40, 0x7fffffff, v8
	v_and_b32_e32 v43, 0x7fffffff, v11
	v_and_b32_e32 v42, 0x7fffffff, v10
	s_waitcnt vmcnt(6)
	v_and_b32_e32 v65, 0x7fffffff, v13
	v_and_b32_e32 v64, 0x7fffffff, v12
	v_and_b32_e32 v67, 0x7fffffff, v15
	v_and_b32_e32 v66, 0x7fffffff, v14
	global_load_dwordx4 v[8:11], v[54:55], off offset:2048 nt
	global_load_dwordx4 v[12:15], v[54:55], off offset:3072 nt
	v_and_b32_e32 v39, 0x7fffffff, v39
	v_and_b32_e32 v38, 0x7fffffff, v38
	v_and_b32_e32 v37, 0x7fffffff, v37
	v_and_b32_e32 v36, 0x7fffffff, v36
	v_add_co_u32_e32 v54, vcc, s76, v0
	v_readlane_b32 s0, v2, 20
	v_readlane_b32 s6, v2, 21
	v_addc_co_u32_e32 v55, vcc, 0, v1, vcc
	v_pk_mul_f32 v[36:37], v[36:37], s[0:1] op_sel_hi:[1,0]
	v_pk_mul_f32 v[38:39], v[38:39], s[0:1] op_sel_hi:[1,0]
	v_pk_mul_f32 v[42:43], v[42:43], s[6:7] op_sel_hi:[1,0]
	v_pk_mul_f32 v[40:41], v[40:41], s[6:7] op_sel_hi:[1,0]
	v_max3_f32 v71, v73, v38, v42
	v_max3_f32 v3, v3, v36, v40
	v_max3_f32 v52, v52, v37, v41
	v_max3_f32 v72, v72, v39, v43
	global_load_dwordx4 v[36:39], v[54:55], off nt
	global_load_dwordx4 v[40:43], v[54:55], off offset:1024 nt
	v_add_co_u32_e32 v54, vcc, s77, v0
	v_pk_mul_f32 v[62:63], v[62:63], s[0:1] op_sel_hi:[1,0]
	s_nop 0
	v_addc_co_u32_e32 v55, vcc, 0, v1, vcc
	v_pk_mul_f32 v[60:61], v[60:61], s[0:1] op_sel_hi:[1,0]
	v_pk_mul_f32 v[66:67], v[66:67], s[6:7] op_sel_hi:[1,0]
	v_pk_mul_f32 v[64:65], v[64:65], s[6:7] op_sel_hi:[1,0]
	v_max3_f32 v69, v69, v60, v66
	v_max3_f32 v59, v59, v62, v64
	v_max3_f32 v70, v70, v63, v65
	v_max3_f32 v68, v68, v61, v67
	s_waitcnt vmcnt(9)
	v_and_b32_e32 v29, 0x7fffffff, v29
	v_and_b32_e32 v28, 0x7fffffff, v28
	v_and_b32_e32 v31, 0x7fffffff, v31
	v_and_b32_e32 v30, 0x7fffffff, v30
	s_waitcnt vmcnt(8)
	v_and_b32_e32 v65, 0x7fffffff, v33
	v_and_b32_e32 v64, 0x7fffffff, v32
	v_and_b32_e32 v61, 0x7fffffff, v35
	v_and_b32_e32 v60, 0x7fffffff, v34
	s_waitcnt vmcnt(7)
	v_and_b32_e32 v33, 0x7fffffff, v7
	v_and_b32_e32 v32, 0x7fffffff, v6
	v_and_b32_e32 v35, 0x7fffffff, v5
	v_and_b32_e32 v34, 0x7fffffff, v4
	s_waitcnt vmcnt(6)
	v_and_b32_e32 v63, 0x7fffffff, v19
	v_and_b32_e32 v62, 0x7fffffff, v18
	v_and_b32_e32 v67, 0x7fffffff, v17
	v_and_b32_e32 v66, 0x7fffffff, v16
	global_load_dwordx4 v[4:7], v[54:55], off offset:2048 nt
	global_load_dwordx4 v[16:19], v[54:55], off offset:3072 nt
	v_add_co_u32_e32 v54, vcc, s78, v0
	v_readlane_b32 s0, v2, 22
	v_readlane_b32 s6, v2, 23
	v_addc_co_u32_e32 v55, vcc, 0, v1, vcc
	v_pk_mul_f32 v[30:31], v[30:31], s[0:1] op_sel_hi:[1,0]
	v_pk_mul_f32 v[28:29], v[28:29], s[0:1] op_sel_hi:[1,0]
	v_pk_mul_f32 v[34:35], v[34:35], s[6:7] op_sel_hi:[1,0]
	v_pk_mul_f32 v[32:33], v[32:33], s[6:7] op_sel_hi:[1,0]
	v_max3_f32 v52, v52, v29, v35
	v_max3_f32 v72, v72, v31, v33
	v_max3_f32 v73, v71, v30, v32
	v_max3_f32 v3, v3, v28, v34
	global_load_dwordx4 v[28:31], v[54:55], off nt
	global_load_dwordx4 v[32:35], v[54:55], off offset:1024 nt
	v_add_co_u32_e32 v54, vcc, s79, v0
	v_pk_mul_f32 v[60:61], v[60:61], s[0:1] op_sel_hi:[1,0]
	s_nop 0
	v_addc_co_u32_e32 v55, vcc, 0, v1, vcc
	v_pk_mul_f32 v[62:63], v[62:63], s[6:7] op_sel_hi:[1,0]
	v_pk_mul_f32 v[64:65], v[64:65], s[0:1] op_sel_hi:[1,0]
	v_pk_mul_f32 v[66:67], v[66:67], s[6:7] op_sel_hi:[1,0]
	v_max3_f32 v74, v68, v61, v63
	v_max3_f32 v75, v69, v60, v62
	global_load_dwordx4 v[60:63], v[54:55], off offset:2048 nt
	v_max3_f32 v76, v70, v65, v67
	v_max3_f32 v59, v59, v64, v66
	s_waitcnt vmcnt(10)
	v_and_b32_e32 v23, 0x7fffffff, v23
	v_and_b32_e32 v22, 0x7fffffff, v22
	v_and_b32_e32 v21, 0x7fffffff, v21
	v_and_b32_e32 v20, 0x7fffffff, v20
	s_waitcnt vmcnt(9)
	v_and_b32_e32 v69, 0x7fffffff, v27
	v_and_b32_e32 v68, 0x7fffffff, v26
	s_waitcnt vmcnt(8)
	v_and_b32_e32 v27, 0x7fffffff, v9
	v_and_b32_e32 v26, 0x7fffffff, v8
	v_and_b32_e32 v65, 0x7fffffff, v11
	v_and_b32_e32 v64, 0x7fffffff, v10
	global_load_dwordx4 v[8:11], v[54:55], off offset:3072 nt
	v_add_co_u32_e32 v54, vcc, s80, v0
	v_readlane_b32 s0, v2, 24
	v_readlane_b32 s6, v2, 25
	s_waitcnt vmcnt(8)
	v_and_b32_e32 v67, 0x7fffffff, v13
	v_and_b32_e32 v66, 0x7fffffff, v12
	v_and_b32_e32 v71, 0x7fffffff, v15
	v_and_b32_e32 v70, 0x7fffffff, v14
	v_addc_co_u32_e32 v55, vcc, 0, v1, vcc
	v_pk_mul_f32 v[12:13], v[20:21], s[0:1] op_sel_hi:[1,0]
	v_pk_mul_f32 v[14:15], v[22:23], s[0:1] op_sel_hi:[1,0]
	v_pk_mul_f32 v[20:21], v[64:65], s[6:7] op_sel_hi:[1,0]
	v_pk_mul_f32 v[22:23], v[26:27], s[6:7] op_sel_hi:[1,0]
	v_and_b32_e32 v25, 0x7fffffff, v25
	v_and_b32_e32 v24, 0x7fffffff, v24
	v_max3_f32 v3, v3, v12, v22
	v_max3_f32 v52, v52, v13, v23
	v_max3_f32 v73, v73, v14, v20
	v_max3_f32 v72, v72, v15, v21
	global_load_dwordx4 v[12:15], v[54:55], off nt
	global_load_dwordx4 v[20:23], v[54:55], off offset:1024 nt
	v_add_co_u32_e32 v0, vcc, s81, v0
	v_pk_mul_f32 v[24:25], v[24:25], s[0:1] op_sel_hi:[1,0]
	s_nop 0
	v_addc_co_u32_e32 v1, vcc, 0, v1, vcc
	v_pk_mul_f32 v[26:27], v[66:67], s[6:7] op_sel_hi:[1,0]
	v_pk_mul_f32 v[54:55], v[70:71], s[6:7] op_sel_hi:[1,0]
	v_max3_f32 v59, v59, v24, v26
	v_max3_f32 v76, v76, v25, v27
	global_load_dwordx4 v[24:27], v[0:1], off offset:2048 nt
	global_load_dwordx4 v[64:67], v[0:1], off offset:3072 nt
	v_pk_mul_f32 v[0:1], v[68:69], s[0:1] op_sel_hi:[1,0]
	v_readlane_b32 s0, v2, 26
	v_max3_f32 v54, v75, v0, v54
	v_max3_f32 v55, v74, v1, v55
	s_waitcnt vmcnt(11)
	v_and_b32_e32 v1, 0x7fffffff, v37
	v_and_b32_e32 v0, 0x7fffffff, v36
	v_and_b32_e32 v37, 0x7fffffff, v39
	v_and_b32_e32 v36, 0x7fffffff, v38
	s_waitcnt vmcnt(10)
	v_and_b32_e32 v39, 0x7fffffff, v41
	v_and_b32_e32 v38, 0x7fffffff, v40
	v_and_b32_e32 v41, 0x7fffffff, v43
	v_and_b32_e32 v40, 0x7fffffff, v42
	v_pk_mul_f32 v[36:37], v[36:37], s[0:1] op_sel_hi:[1,0]
	v_pk_mul_f32 v[0:1], v[0:1], s[0:1] op_sel_hi:[1,0]
	v_pk_mul_f32 v[40:41], v[40:41], s[0:1] op_sel_hi:[1,0]
	v_pk_mul_f32 v[38:39], v[38:39], s[0:1] op_sel_hi:[1,0]
	s_waitcnt vmcnt(9)
	v_and_b32_e32 v7, 0x7fffffff, v7
	v_and_b32_e32 v6, 0x7fffffff, v6
	v_and_b32_e32 v5, 0x7fffffff, v5
	v_and_b32_e32 v4, 0x7fffffff, v4
	s_waitcnt vmcnt(8)
	v_and_b32_e32 v17, 0x7fffffff, v17
	v_and_b32_e32 v16, 0x7fffffff, v16
	v_readlane_b32 s0, v2, 27
	v_and_b32_e32 v19, 0x7fffffff, v19
	v_and_b32_e32 v18, 0x7fffffff, v18
	v_pk_mul_f32 v[4:5], v[4:5], s[0:1] op_sel_hi:[1,0]
	v_pk_mul_f32 v[6:7], v[6:7], s[0:1] op_sel_hi:[1,0]
	v_pk_mul_f32 v[16:17], v[16:17], s[0:1] op_sel_hi:[1,0]
	v_pk_mul_f32 v[18:19], v[18:19], s[0:1] op_sel_hi:[1,0]
	v_max3_f32 v37, v72, v37, v7
	v_max3_f32 v36, v73, v36, v6
	v_max3_f32 v42, v52, v1, v5
	v_max3_f32 v3, v3, v0, v4
	v_max3_f32 v39, v76, v39, v17
	v_max3_f32 v38, v59, v38, v16
	s_waitcnt vmcnt(7)
	v_and_b32_e32 v1, 0x7fffffff, v31
	v_and_b32_e32 v0, 0x7fffffff, v30
	v_and_b32_e32 v5, 0x7fffffff, v29
	v_and_b32_e32 v4, 0x7fffffff, v28
	s_waitcnt vmcnt(6)
	v_and_b32_e32 v7, 0x7fffffff, v35
	v_and_b32_e32 v6, 0x7fffffff, v34
	v_and_b32_e32 v17, 0x7fffffff, v33
	v_and_b32_e32 v16, 0x7fffffff, v32
	v_readlane_b32 s0, v2, 28
	v_max3_f32 v41, v55, v41, v19
	v_max3_f32 v40, v54, v40, v18
	v_pk_mul_f32 v[4:5], v[4:5], s[0:1] op_sel_hi:[1,0]
	v_pk_mul_f32 v[0:1], v[0:1], s[0:1] op_sel_hi:[1,0]
	v_pk_mul_f32 v[16:17], v[16:17], s[0:1] op_sel_hi:[1,0]
	v_pk_mul_f32 v[6:7], v[6:7], s[0:1] op_sel_hi:[1,0]
	s_waitcnt vmcnt(5)
	v_and_b32_e32 v19, 0x7fffffff, v61
	v_and_b32_e32 v18, 0x7fffffff, v60
	v_and_b32_e32 v29, 0x7fffffff, v63
	v_and_b32_e32 v28, 0x7fffffff, v62
	s_waitcnt vmcnt(4)
	v_and_b32_e32 v9, 0x7fffffff, v9
	v_and_b32_e32 v8, 0x7fffffff, v8
	v_and_b32_e32 v11, 0x7fffffff, v11
	v_and_b32_e32 v10, 0x7fffffff, v10
	v_readlane_b32 s0, v2, 29
	s_nop 1
	v_pk_mul_f32 v[28:29], v[28:29], s[0:1] op_sel_hi:[1,0]
	v_pk_mul_f32 v[18:19], v[18:19], s[0:1] op_sel_hi:[1,0]
	v_pk_mul_f32 v[10:11], v[10:11], s[0:1] op_sel_hi:[1,0]
	v_pk_mul_f32 v[8:9], v[8:9], s[0:1] op_sel_hi:[1,0]
	v_max3_f32 v18, v3, v4, v18
	v_max3_f32 v19, v42, v5, v19
	v_max3_f32 v28, v36, v0, v28
	v_max3_f32 v29, v37, v1, v29
	v_max3_f32 v30, v38, v16, v8
	v_max3_f32 v31, v39, v17, v9
	v_max3_f32 v32, v40, v6, v10
	v_max3_f32 v33, v41, v7, v11
	s_waitcnt vmcnt(3)
	v_and_b32_e32 v1, 0x7fffffff, v13
	v_and_b32_e32 v0, 0x7fffffff, v12
	v_and_b32_e32 v5, 0x7fffffff, v15
	v_and_b32_e32 v4, 0x7fffffff, v14
	s_waitcnt vmcnt(2)
	v_and_b32_e32 v7, 0x7fffffff, v21
	v_and_b32_e32 v6, 0x7fffffff, v20
	v_and_b32_e32 v9, 0x7fffffff, v23
	v_and_b32_e32 v8, 0x7fffffff, v22
	v_readlane_b32 s0, v2, 30
	s_waitcnt vmcnt(1)
	v_and_b32_e32 v13, 0x7fffffff, v25
	v_and_b32_e32 v12, 0x7fffffff, v24
	v_pk_mul_f32 v[4:5], v[4:5], s[0:1] op_sel_hi:[1,0]
	v_pk_mul_f32 v[0:1], v[0:1], s[0:1] op_sel_hi:[1,0]
	v_pk_mul_f32 v[8:9], v[8:9], s[0:1] op_sel_hi:[1,0]
	v_pk_mul_f32 v[10:11], v[6:7], s[0:1] op_sel_hi:[1,0]
	v_and_b32_e32 v7, 0x7fffffff, v27
	v_and_b32_e32 v6, 0x7fffffff, v26
	v_readlane_b32 s0, v2, 31
	s_waitcnt vmcnt(0)
	v_and_b32_e32 v15, 0x7fffffff, v67
	v_and_b32_e32 v14, 0x7fffffff, v66
	v_and_b32_e32 v17, 0x7fffffff, v65
	v_and_b32_e32 v16, 0x7fffffff, v64
	v_pk_mul_f32 v[12:13], v[12:13], s[0:1] op_sel_hi:[1,0]
	v_pk_mul_f32 v[2:3], v[6:7], s[0:1] op_sel_hi:[1,0]
	v_pk_mul_f32 v[16:17], v[16:17], s[0:1] op_sel_hi:[1,0]
	v_pk_mul_f32 v[6:7], v[14:15], s[0:1] op_sel_hi:[1,0]
	v_max3_f32 v3, v29, v5, v3
	v_max3_f32 v2, v28, v4, v2
	v_max3_f32 v1, v19, v1, v13
	v_max3_f32 v0, v18, v0, v12
	v_max3_f32 v7, v33, v9, v7
	v_max3_f32 v6, v32, v8, v6
	v_max3_f32 v5, v31, v11, v17
	v_max3_f32 v4, v30, v10, v16
	ds_write_b128 v57, v[0:3]
	ds_write_b128 v57, v[4:7] offset:1024
	s_waitcnt lgkmcnt(0)
	s_barrier
	ds_read2st64_b32 v[0:1], v58 offset1:8
	ds_read2st64_b32 v[2:3], v58 offset0:16 offset1:24
	ds_read2st64_b32 v[4:5], v58 offset0:32 offset1:40
	ds_read2st64_b32 v[6:7], v58 offset0:48 offset1:56
	s_waitcnt lgkmcnt(3)
	v_max_f32_e32 v1, v1, v1
	v_max_f32_e32 v0, v0, v0
	v_max_f32_e32 v0, v0, v1
	s_waitcnt lgkmcnt(2)
	v_max3_f32 v0, v0, v2, v3
	s_waitcnt lgkmcnt(1)
	v_max3_f32 v0, v0, v4, v5
	s_waitcnt lgkmcnt(0)
	v_max3_f32 v2, v0, v6, v7
	v_lshl_add_u64 v[0:1], v[50:51], 0, s[2:3]
	global_atomic_umax v[0:1], v2, off
	s_barrier
	s_branch .LBB0_10

.LBB0_73:
	v_readlane_b32 s36, v251, 5
	v_readlane_b32 s50, v251, 19
	v_readlane_b32 s51, v251, 20
	s_add_u32 s0, s50, 0x2600000
	s_addc_u32 s1, s51, 0
	v_readlane_b32 s37, v251, 6
	v_readlane_b32 s38, v251, 7
	v_readlane_b32 s39, v251, 8
	v_readlane_b32 s40, v251, 9
	v_readlane_b32 s41, v251, 10
	v_readlane_b32 s42, v251, 11
	v_readlane_b32 s43, v251, 12
	v_readlane_b32 s44, v251, 13
	v_readlane_b32 s45, v251, 14
	v_readlane_b32 s46, v251, 15
	v_readlane_b32 s47, v251, 16
	v_readlane_b32 s48, v251, 17
	v_readlane_b32 s49, v251, 18
	v_writelane_b32 v251, s0, 50
	s_nop 1
	v_writelane_b32 v251, s1, 51
	s_add_u32 s0, s50, 0x7600000
	s_addc_u32 s1, s51, 0
	v_writelane_b32 v251, s0, 52
	s_nop 1
	v_writelane_b32 v251, s1, 53
	s_add_u32 s0, s50, 0x9600000
	s_addc_u32 s1, s51, 0
	v_writelane_b32 v251, s0, 54
	s_nop 1
	v_writelane_b32 v251, s1, 55
	s_add_u32 s0, s50, 0x14200000
	s_addc_u32 s1, s51, 0
	v_writelane_b32 v251, s0, 56
	s_nop 1
	v_writelane_b32 v251, s1, 57
	s_add_u32 s0, s50, 0x19800000
	s_addc_u32 s1, s51, 0
	v_writelane_b32 v251, s0, 58
	s_nop 1
	v_writelane_b32 v251, s1, 59
	s_add_u32 s0, s50, 0xd00000
	s_addc_u32 s1, s51, 0
	v_writelane_b32 v251, s0, 60
	s_nop 1
	v_writelane_b32 v251, s1, 61
	s_add_u32 s0, s50, 0x500000
	s_addc_u32 s1, s51, 0
	v_writelane_b32 v251, s0, 62
	s_nop 1
	v_writelane_b32 v251, s1, 63
	s_add_u32 s0, s50, 0x60000
	s_addc_u32 s1, s51, 0
	s_add_u32 s90, s50, 0x2e00000
	s_addc_u32 s91, s51, 0
	s_cmp_lt_i32 s96, 2
	s_cselect_b64 s[2:3], -1, 0
	s_cmp_gt_i32 s97, 1
	s_cselect_b64 s[4:5], -1, 0
	s_and_b64 s[2:3], s[2:3], s[4:5]
	s_andn2_b64 vcc, exec, s[2:3]
	s_cbranch_vccnz .LBB0_213
	v_readlane_b32 s3, v251, 42
	s_lshl_b32 s2, s3, 14
	s_add_i32 s7, s2, 0
	v_readlane_b32 s2, v251, 4
	s_lshl_b32 s2, s2, 3
	s_add_i32 s4, s2, s3
	v_readlane_b32 s2, v251, 3
	s_lshl_b32 s6, s2, 3
	s_cmpk_lt_i32 s4, 0x5000
	v_mbcnt_lo_u32_b32 v64, -1, 0
	v_mbcnt_hi_u32_b32 v64, -1, v64
	s_nop 0
	v_ashrrev_i32_e32 v9, 5, v64
	v_and_b32_e32 v8, 31, v64
	v_ashrrev_i32_e32 v20, 3, v64
	v_lshlrev_b32_e32 v21, 3, v64
	v_and_b32_e32 v18, 7, v64
	s_cbranch_scc0 .LBB0_83
	s_mul_hi_i32 s2, s4, 0x66666667
	s_lshr_b32 s3, s2, 31
	s_ashr_i32 s2, s2, 7
	s_add_i32 s5, s2, s3
	s_mul_i32 s2, s5, 0xfffffec0
	s_add_i32 s2, s2, s4
	s_lshl_b32 s2, s2, 5
	s_ashr_i32 s3, s2, 31
	s_lshl_b64 s[2:3], s[2:3], 2
	s_add_u32 s2, s58, s2
	s_addc_u32 s3, s59, s3
	v_lshl_add_u32 v2, s5, 6, v9
	s_mov_b32 s5, 0xa000
	v_mov_b64_e32 v[0:1], s[2:3]
	v_mad_i64_i32 v[2:3], s[2:3], v2, s5, v[0:1]
	v_mov_b32_e32 v1, 0
	v_lshlrev_b32_e32 v0, 2, v8
	v_lshl_add_u64 v[2:3], v[2:3], 0, v[0:1]
	s_mov_b32 s12, 0x14000
	v_add_co_u32_e32 v4, vcc, s12, v2
	s_mov_b32 s13, 0x28000
	s_nop 0
	v_addc_co_u32_e32 v5, vcc, 0, v3, vcc
	v_add_co_u32_e32 v10, vcc, s13, v2
	s_mov_b32 s14, 0x3c000
	s_nop 0
	v_addc_co_u32_e32 v11, vcc, 0, v3, vcc
	v_add_co_u32_e32 v12, vcc, s14, v2
	s_mov_b32 s33, 0x50000
	s_nop 0
	v_addc_co_u32_e32 v13, vcc, 0, v3, vcc
	v_add_co_u32_e32 v14, vcc, s33, v2
	s_mov_b32 s34, 0x64000
	s_nop 0
	v_addc_co_u32_e32 v15, vcc, 0, v3, vcc
	v_add_co_u32_e32 v16, vcc, s34, v2
	s_mov_b32 s35, 0x78000
	s_nop 0
	v_addc_co_u32_e32 v17, vcc, 0, v3, vcc
	v_add_co_u32_e32 v22, vcc, s35, v2
	s_mov_b32 s68, 0x8c000
	s_nop 0
	v_addc_co_u32_e32 v23, vcc, 0, v3, vcc
	v_add_co_u32_e32 v24, vcc, s68, v2
	s_mov_b32 s69, 0xa0000
	s_nop 0
	v_addc_co_u32_e32 v25, vcc, 0, v3, vcc
	global_load_dword v6, v[2:3], off nt
	global_load_dword v7, v[4:5], off nt
	global_load_dword v47, v[10:11], off nt
	global_load_dword v48, v[12:13], off nt
	global_load_dword v49, v[14:15], off nt
	global_load_dword v50, v[16:17], off nt
	global_load_dword v51, v[22:23], off nt
	global_load_dword v52, v[24:25], off nt
	v_add_co_u32_e32 v4, vcc, s69, v2
	s_mov_b32 s70, 0xb4000
	s_nop 0
	v_addc_co_u32_e32 v5, vcc, 0, v3, vcc
	v_add_co_u32_e32 v10, vcc, s70, v2
	s_mov_b32 s71, 0xc8000
	s_nop 0
	v_addc_co_u32_e32 v11, vcc, 0, v3, vcc
	v_add_co_u32_e32 v12, vcc, s71, v2
	s_mov_b32 s72, 0xdc000
	s_nop 0
	v_addc_co_u32_e32 v13, vcc, 0, v3, vcc
	v_add_co_u32_e32 v14, vcc, s72, v2
	s_mov_b32 s73, 0xf0000
	s_nop 0
	v_addc_co_u32_e32 v15, vcc, 0, v3, vcc
	v_add_co_u32_e32 v16, vcc, s73, v2
	s_mov_b32 s74, 0x104000
	s_nop 0
	v_addc_co_u32_e32 v17, vcc, 0, v3, vcc
	v_add_co_u32_e32 v22, vcc, s74, v2
	s_mov_b32 s75, 0x118000
	s_nop 0
	v_addc_co_u32_e32 v23, vcc, 0, v3, vcc
	v_add_co_u32_e32 v24, vcc, s75, v2
	s_mov_b32 s76, 0x12c000
	s_nop 0
	v_addc_co_u32_e32 v25, vcc, 0, v3, vcc
	v_add_co_u32_e32 v26, vcc, s76, v2
	s_mov_b32 s77, 0x140000
	s_nop 0
	v_addc_co_u32_e32 v27, vcc, 0, v3, vcc
	global_load_dword v53, v[4:5], off nt
	global_load_dword v54, v[10:11], off nt
	global_load_dword v55, v[12:13], off nt
	global_load_dword v56, v[14:15], off nt
	global_load_dword v57, v[16:17], off nt
	global_load_dword v58, v[22:23], off nt
	global_load_dword v59, v[24:25], off nt
	global_load_dword v60, v[26:27], off nt
	v_add_co_u32_e32 v4, vcc, s77, v2
	s_mov_b32 s78, 0x154000
	s_nop 0
	v_addc_co_u32_e32 v5, vcc, 0, v3, vcc
	v_add_co_u32_e32 v10, vcc, s78, v2
	s_mov_b32 s79, 0x168000
	s_nop 0
	v_addc_co_u32_e32 v11, vcc, 0, v3, vcc
	v_add_co_u32_e32 v12, vcc, s79, v2
	s_mov_b32 s80, 0x17c000
	s_nop 0
	v_addc_co_u32_e32 v13, vcc, 0, v3, vcc
	v_add_co_u32_e32 v14, vcc, s80, v2
	s_mov_b32 s81, 0x190000
	s_nop 0
	v_addc_co_u32_e32 v15, vcc, 0, v3, vcc
	v_add_co_u32_e32 v16, vcc, s81, v2
	s_mov_b32 s82, 0x1a4000
	s_nop 0
	v_addc_co_u32_e32 v17, vcc, 0, v3, vcc
	v_add_co_u32_e32 v22, vcc, s82, v2
	s_mov_b32 s83, 0x1b8000
	s_nop 0
	v_addc_co_u32_e32 v23, vcc, 0, v3, vcc
	v_add_co_u32_e32 v24, vcc, s83, v2
	s_mov_b32 s84, 0x1cc000
	s_nop 0
	v_addc_co_u32_e32 v25, vcc, 0, v3, vcc
	v_add_co_u32_e32 v26, vcc, s84, v2
	s_mov_b32 s85, 0x1e0000
	s_nop 0
	v_addc_co_u32_e32 v27, vcc, 0, v3, vcc
	global_load_dword v61, v[4:5], off nt
	global_load_dword v62, v[10:11], off nt
	global_load_dword v63, v[12:13], off nt
	global_load_dword v65, v[14:15], off nt
	global_load_dword v66, v[16:17], off nt
	global_load_dword v67, v[22:23], off nt
	global_load_dword v68, v[24:25], off nt
	global_load_dword v69, v[26:27], off nt
	v_add_co_u32_e32 v4, vcc, s85, v2
	s_mov_b32 s86, 0x1f4000
	s_nop 0
	v_addc_co_u32_e32 v5, vcc, 0, v3, vcc
	v_add_co_u32_e32 v10, vcc, s86, v2
	s_mov_b32 s87, 0x208000
	s_nop 0
	v_addc_co_u32_e32 v11, vcc, 0, v3, vcc
	v_add_co_u32_e32 v12, vcc, s87, v2
	s_mov_b32 s88, 0x21c000
	s_nop 0
	v_addc_co_u32_e32 v13, vcc, 0, v3, vcc
	v_add_co_u32_e32 v14, vcc, s88, v2
	s_mov_b32 s2, 0x230000
	s_nop 0
	v_addc_co_u32_e32 v15, vcc, 0, v3, vcc
	v_add_co_u32_e32 v16, vcc, s2, v2
	s_mov_b32 s2, 0x244000
	s_nop 0
	v_addc_co_u32_e32 v17, vcc, 0, v3, vcc
	v_add_co_u32_e32 v22, vcc, s2, v2
	s_mov_b32 s2, 0x258000
	s_nop 0
	v_addc_co_u32_e32 v23, vcc, 0, v3, vcc
	v_add_co_u32_e32 v24, vcc, s2, v2
	s_mov_b32 s2, 0x26c000
	s_nop 0
	v_addc_co_u32_e32 v25, vcc, 0, v3, vcc
	v_add_co_u32_e32 v2, vcc, s2, v2
	s_movk_i32 s2, 0x84
	s_nop 0
	v_addc_co_u32_e32 v3, vcc, 0, v3, vcc
	global_load_dword v70, v[4:5], off nt
	global_load_dword v71, v[10:11], off nt
	global_load_dword v72, v[12:13], off nt
	global_load_dword v73, v[14:15], off nt
	global_load_dword v74, v[16:17], off nt
	global_load_dword v75, v[22:23], off nt
	global_load_dword v76, v[24:25], off nt
	global_load_dword v77, v[2:3], off nt
	v_add_u32_e32 v11, s7, v0
	v_mul_lo_u32 v12, v9, s2
	v_and_b32_e32 v0, 56, v21
	v_readlane_b32 s2, v251, 50
	v_mul_u32_u24_e32 v4, 0x84, v0
	v_lshlrev_b32_e32 v0, 1, v0
	v_readlane_b32 s3, v251, 51
	s_movk_i32 s93, 0x7fff
	s_mov_b32 s94, 0xffff0000
	v_lshl_add_u64 v[2:3], s[2:3], 0, v[0:1]
	v_readlane_b32 s2, v251, 4
	v_readlane_b32 s3, v251, 42
	s_lshl_b32 s2, s2, 8
	s_lshl_b32 s3, s3, 5
	v_lshlrev_b32_e32 v0, 2, v20
	s_add_i32 s2, s2, s3
	v_add3_u32 v10, s7, v4, v0
	v_lshlrev_b32_e32 v0, 3, v18
	s_add_i32 s89, s2, 0xfffff800
	v_readlane_b32 s2, v251, 3
	v_lshl_add_u64 v[4:5], s[90:91], 0, v[0:1]
	s_lshl_b32 s92, s2, 8
	v_lshlrev_b32_e32 v0, 2, v8
	s_mov_b32 s95, 0x42fe0000
	s_mov_b32 s96, 0x40c0c00
	v_add_u32_e32 v11, v11, v12
	v_mov_b32_e32 v46, v1
	v_mov_b32_e32 v39, v1
	v_mov_b32_e32 v40, v1
	v_mov_b32_e32 v41, v1
	v_mov_b32_e32 v42, v1
	v_mov_b32_e32 v43, v1
	v_mov_b32_e32 v44, v1
	v_mov_b32_e32 v45, v1
	v_mov_b32_e32 v38, v1
	v_mov_b32_e32 v31, v1
	v_mov_b32_e32 v32, v1
	v_mov_b32_e32 v33, v1
	v_mov_b32_e32 v34, v1
	v_mov_b32_e32 v35, v1
	v_mov_b32_e32 v36, v1
	v_mov_b32_e32 v37, v1
	v_mov_b32_e32 v30, v1
	v_mov_b32_e32 v23, v1
	v_mov_b32_e32 v24, v1
	v_mov_b32_e32 v25, v1
	v_mov_b32_e32 v26, v1
	v_mov_b32_e32 v27, v1
	v_mov_b32_e32 v28, v1
	v_mov_b32_e32 v29, v1
	v_mov_b32_e32 v22, v1
	v_mov_b32_e32 v12, v1
	v_mov_b32_e32 v13, v1
	v_mov_b32_e32 v14, v1
	v_mov_b32_e32 v15, v1
	v_mov_b32_e32 v16, v1
	v_mov_b32_e32 v17, v1
	v_mov_b32_e32 v19, v1
	s_mov_b32 s2, s4
	s_branch .LBB0_77

.LBB0_77:
	s_add_i32 s97, s2, s6
	s_cmpk_gt_i32 s97, 0x4fff
	s_cselect_b64 s[8:9], -1, 0
	s_and_b64 vcc, exec, s[8:9]
	s_cbranch_vccnz .LBB0_79
	s_mul_hi_i32 s3, s97, 0x66666667
	s_lshr_b32 s10, s3, 31
	s_ashr_i32 s3, s3, 7
	s_add_i32 s3, s3, s10
	s_mul_i32 s10, s3, 0xffffd800
	s_add_i32 s11, s92, s89
	s_add_i32 s10, s11, s10
	s_addk_i32 s10, 0x800
	v_lshl_add_u32 v14, s3, 6, v9
	v_mov_b64_e32 v[12:13], s[58:59]
	v_mad_i64_i32 v[12:13], vcc, v14, s5, v[12:13]
	s_ashr_i32 s11, s10, 31
	v_lshl_add_u64 v[12:13], s[10:11], 2, v[12:13]
	v_lshl_add_u64 v[40:41], v[12:13], 0, v[0:1]
	v_add_co_u32_e32 v12, vcc, s12, v40
	s_nop 1
	v_addc_co_u32_e32 v13, vcc, 0, v41, vcc
	v_add_co_u32_e32 v14, vcc, s13, v40
	s_nop 1
	v_addc_co_u32_e32 v15, vcc, 0, v41, vcc
	v_add_co_u32_e32 v22, vcc, s14, v40
	s_nop 1
	v_addc_co_u32_e32 v23, vcc, 0, v41, vcc
	v_add_co_u32_e32 v24, vcc, s33, v40
	s_nop 1
	v_addc_co_u32_e32 v25, vcc, 0, v41, vcc
	v_add_co_u32_e32 v26, vcc, s34, v40
	s_nop 1
	v_addc_co_u32_e32 v27, vcc, 0, v41, vcc
	v_add_co_u32_e32 v28, vcc, s35, v40
	s_nop 1
	v_addc_co_u32_e32 v29, vcc, 0, v41, vcc
	v_add_co_u32_e32 v30, vcc, s68, v40
	s_nop 1
	v_addc_co_u32_e32 v31, vcc, 0, v41, vcc
	global_load_dword v19, v[40:41], off nt
	global_load_dword v17, v[12:13], off nt
	global_load_dword v16, v[14:15], off nt
	s_nop 0
	global_load_dword v15, v[22:23], off nt
	global_load_dword v14, v[24:25], off nt
	global_load_dword v13, v[26:27], off nt
	global_load_dword v12, v[28:29], off nt
	s_nop 0
	global_load_dword v22, v[30:31], off nt
	v_add_co_u32_e32 v24, vcc, s69, v40
	s_nop 1
	v_addc_co_u32_e32 v25, vcc, 0, v41, vcc
	v_add_co_u32_e32 v26, vcc, s70, v40
	s_nop 1
	v_addc_co_u32_e32 v27, vcc, 0, v41, vcc
	v_add_co_u32_e32 v30, vcc, s71, v40
	s_nop 1
	v_addc_co_u32_e32 v31, vcc, 0, v41, vcc
	v_add_co_u32_e32 v32, vcc, s72, v40
	s_nop 1
	v_addc_co_u32_e32 v33, vcc, 0, v41, vcc
	v_add_co_u32_e32 v34, vcc, s73, v40
	s_nop 1
	v_addc_co_u32_e32 v35, vcc, 0, v41, vcc
	v_add_co_u32_e32 v36, vcc, s74, v40
	s_nop 1
	v_addc_co_u32_e32 v37, vcc, 0, v41, vcc
	v_add_co_u32_e32 v38, vcc, s75, v40
	s_nop 1
	v_addc_co_u32_e32 v39, vcc, 0, v41, vcc
	v_add_co_u32_e32 v42, vcc, s76, v40
	s_nop 1
	v_addc_co_u32_e32 v43, vcc, 0, v41, vcc
	global_load_dword v29, v[24:25], off nt
	global_load_dword v28, v[26:27], off nt
	s_nop 0
	global_load_dword v27, v[30:31], off nt
	global_load_dword v26, v[32:33], off nt
	global_load_dword v25, v[34:35], off nt
	global_load_dword v24, v[36:37], off nt
	global_load_dword v23, v[38:39], off nt
	s_nop 0
	global_load_dword v30, v[42:43], off nt
	v_add_co_u32_e32 v32, vcc, s77, v40
	s_nop 1
	v_addc_co_u32_e32 v33, vcc, 0, v41, vcc
	v_add_co_u32_e32 v34, vcc, s78, v40
	s_nop 1
	v_addc_co_u32_e32 v35, vcc, 0, v41, vcc
	v_add_co_u32_e32 v38, vcc, s79, v40
	s_nop 1
	v_addc_co_u32_e32 v39, vcc, 0, v41, vcc
	v_add_co_u32_e32 v42, vcc, s80, v40
	s_nop 1
	v_addc_co_u32_e32 v43, vcc, 0, v41, vcc
	v_add_co_u32_e32 v44, vcc, s81, v40
	s_nop 1
	v_addc_co_u32_e32 v45, vcc, 0, v41, vcc
	v_add_co_u32_e32 v78, vcc, s82, v40
	s_nop 1
	v_addc_co_u32_e32 v79, vcc, 0, v41, vcc
	v_add_co_u32_e32 v80, vcc, s83, v40
	s_nop 1
	v_addc_co_u32_e32 v81, vcc, 0, v41, vcc
	v_add_co_u32_e32 v82, vcc, s84, v40
	s_nop 1
	v_addc_co_u32_e32 v83, vcc, 0, v41, vcc
	global_load_dword v37, v[32:33], off nt
	global_load_dword v36, v[34:35], off nt
	s_nop 0
	global_load_dword v35, v[38:39], off nt
	global_load_dword v34, v[42:43], off nt
	global_load_dword v33, v[44:45], off nt
	global_load_dword v32, v[78:79], off nt
	global_load_dword v31, v[80:81], off nt
	s_nop 0
	global_load_dword v38, v[82:83], off nt
	v_add_co_u32_e32 v42, vcc, s85, v40
	s_nop 1
	v_addc_co_u32_e32 v43, vcc, 0, v41, vcc
	v_add_co_u32_e32 v78, vcc, s86, v40
	s_nop 1
	v_addc_co_u32_e32 v79, vcc, 0, v41, vcc
	v_add_co_u32_e32 v80, vcc, s87, v40
	s_nop 1
	v_addc_co_u32_e32 v81, vcc, 0, v41, vcc
	v_add_co_u32_e32 v82, vcc, s88, v40
	s_nop 1
	v_addc_co_u32_e32 v83, vcc, 0, v41, vcc
	v_add_co_u32_e32 v84, vcc, 0x230000, v40
	s_nop 1
	v_addc_co_u32_e32 v85, vcc, 0, v41, vcc
	v_add_co_u32_e32 v86, vcc, 0x244000, v40
	s_nop 1
	v_addc_co_u32_e32 v87, vcc, 0, v41, vcc
	v_add_co_u32_e32 v88, vcc, 0x258000, v40
	s_nop 1
	v_addc_co_u32_e32 v89, vcc, 0, v41, vcc
	v_add_co_u32_e32 v90, vcc, 0x26c000, v40
	s_nop 1
	v_addc_co_u32_e32 v91, vcc, 0, v41, vcc
	global_load_dword v45, v[42:43], off nt
	global_load_dword v44, v[78:79], off nt
	s_nop 0
	global_load_dword v43, v[80:81], off nt
	global_load_dword v42, v[82:83], off nt
	global_load_dword v41, v[84:85], off nt
	global_load_dword v40, v[86:87], off nt
	global_load_dword v39, v[88:89], off nt
	global_load_dword v46, v[90:91], off nt

.LBB0_81:
	s_andn2_b64 vcc, exec, s[10:11]
	s_cbranch_vccnz .LBB0_76
	v_add_u32_e32 v86, 0x800, v78
	v_ashrrev_i32_e32 v87, 31, v86
	v_lshl_add_u64 v[88:89], v[86:87], 2, s[0:1]
	global_load_dword v90, v[88:89], off nt
	global_load_dword v91, v[88:89], off offset:32 nt
	s_waitcnt vmcnt(32)
	ds_write2_b32 v11, v6, v7 offset1:66
	s_waitcnt vmcnt(30)
	ds_write2_b32 v11, v47, v48 offset0:132 offset1:198
	s_waitcnt vmcnt(28)
	ds_write2_b32 v85, v49, v50 offset0:8 offset1:74
	s_waitcnt vmcnt(26)
	ds_write2_b32 v85, v51, v52 offset0:140 offset1:206
	s_waitcnt vmcnt(24)
	ds_write2_b32 v84, v53, v54 offset0:16 offset1:82
	s_waitcnt vmcnt(22)
	ds_write2_b32 v84, v55, v56 offset0:148 offset1:214
	s_waitcnt vmcnt(20)
	ds_write2_b32 v83, v57, v58 offset0:24 offset1:90
	s_waitcnt vmcnt(18)
	ds_write2_b32 v83, v59, v60 offset0:156 offset1:222
	s_waitcnt vmcnt(16)
	ds_write2_b32 v82, v61, v62 offset0:32 offset1:98
	s_waitcnt vmcnt(14)
	ds_write2_b32 v82, v63, v65 offset0:164 offset1:230
	s_waitcnt vmcnt(12)
	ds_write2_b32 v81, v66, v67 offset0:40 offset1:106
	s_waitcnt vmcnt(10)
	ds_write2_b32 v81, v68, v69 offset0:172 offset1:238
	s_waitcnt vmcnt(8)
	ds_write2_b32 v80, v70, v71 offset0:48 offset1:114
	s_waitcnt vmcnt(6)
	ds_write2_b32 v80, v72, v73 offset0:180 offset1:246
	s_waitcnt vmcnt(4)
	ds_write2_b32 v79, v74, v75 offset0:56 offset1:122
	s_waitcnt vmcnt(2)
	ds_write2_b32 v79, v76, v77 offset0:188 offset1:254
	global_load_dword v47, v[88:89], off offset:64 nt
	global_load_dword v65, v[88:89], off offset:96 nt
	s_waitcnt lgkmcnt(0)
	s_ashr_i32 s3, s2, 31
	ds_read2_b32 v[50:51], v10 offset0:33 offset1:41
	ds_read2_b32 v[52:53], v10 offset0:66 offset1:74
	ds_read2_b32 v[54:55], v10 offset0:99 offset1:107
	ds_read2_b32 v[56:57], v10 offset1:8
	ds_read2_b32 v[58:59], v10 offset0:132 offset1:140
	ds_read2_b32 v[60:61], v10 offset0:165 offset1:173
	ds_read2_b32 v[62:63], v10 offset0:198 offset1:206
	ds_read2_b32 v[66:67], v10 offset0:231 offset1:239
	v_lshl_add_u64 v[6:7], v[4:5], 0, s[2:3]
	s_waitcnt lgkmcnt(7)
	v_mov_b32_e32 v71, v50
	s_waitcnt lgkmcnt(5)
	v_mov_b32_e32 v69, v54
	s_waitcnt lgkmcnt(4)
	v_mov_b32_e32 v70, v56
	s_waitcnt lgkmcnt(3)
	v_mov_b32_e32 v74, v58
	s_waitcnt lgkmcnt(1)
	v_mov_b32_e32 v72, v62
	v_mov_b32_e32 v68, v52
	s_waitcnt lgkmcnt(0)
	v_mov_b32_e32 v73, v66
	v_mov_b32_e32 v75, v60
	v_lshlrev_b64 v[48:49], 12, v[86:87]
	v_lshl_add_u64 v[48:49], v[6:7], 0, v[48:49]
	s_waitcnt vmcnt(3)
	v_div_scale_f32 v50, s[2:3], v90, v90, s95
	s_waitcnt vmcnt(2)
	v_div_scale_f32 v54, s[2:3], v91, v91, s95
	v_rcp_f32_e32 v56, v50
	v_rcp_f32_e32 v58, v54
	v_div_scale_f32 v52, vcc, s95, v90, s95
	v_fma_f32 v62, -v50, v56, 1.0
	v_fma_f32 v66, -v54, v58, 1.0
	v_fmac_f32_e32 v56, v62, v56
	v_div_scale_f32 v60, s[2:3], s95, v91, s95
	v_fmac_f32_e32 v58, v66, v58
	v_mul_f32_e32 v62, v52, v56
	v_mul_f32_e32 v66, v60, v58
	v_fma_f32 v76, -v50, v62, v52
	v_fma_f32 v77, -v54, v66, v60
	v_fmac_f32_e32 v62, v76, v56
	v_fmac_f32_e32 v66, v77, v58
	v_fma_f32 v50, -v50, v62, v52
	v_fma_f32 v52, -v54, v66, v60
	v_div_fmas_f32 v50, v50, v56, v62
	s_mov_b64 vcc, s[2:3]
	v_div_fixup_f32 v50, v50, v90, s95
	v_div_fmas_f32 v52, v52, v58, v66
	v_cmp_lt_f32_e32 vcc, 0, v90
	v_div_fixup_f32 v52, v52, v91, s95
	s_nop 0
	v_cndmask_b32_e32 v50, 0, v50, vcc
	v_pk_mul_f32 v[68:69], v[50:51], v[68:69] op_sel_hi:[0,1]
	v_pk_mul_f32 v[70:71], v[50:51], v[70:71] op_sel_hi:[0,1]
	v_pk_mul_f32 v[74:75], v[50:51], v[74:75] op_sel_hi:[0,1]
	v_pk_mul_f32 v[72:73], v[50:51], v[72:73] op_sel_hi:[0,1]
	v_rndne_f32_e32 v50, v70
	v_rndne_f32_e32 v54, v71
	v_rndne_f32_e32 v58, v69
	v_rndne_f32_e32 v62, v75
	v_rndne_f32_e32 v56, v68
	v_rndne_f32_e32 v60, v74
	v_rndne_f32_e32 v66, v72
	v_rndne_f32_e32 v68, v73
	v_cvt_i32_f32_e32 v50, v50
	v_cvt_i32_f32_e32 v54, v54
	v_cvt_i32_f32_e32 v58, v58
	v_cvt_i32_f32_e32 v62, v62
	v_cvt_i32_f32_sdwa v56, v56 dst_sel:WORD_1 dst_unused:UNUSED_PAD src0_sel:DWORD
	v_cvt_i32_f32_e32 v60, v60
	v_cvt_i32_f32_sdwa v66, v66 dst_sel:WORD_1 dst_unused:UNUSED_PAD src0_sel:DWORD
	v_cvt_i32_f32_e32 v68, v68
	v_lshlrev_b32_e32 v54, 8, v54
	v_perm_b32 v50, v58, v50, s96
	v_lshlrev_b32_e32 v58, 8, v62
	v_and_b32_e32 v56, 0xff0000, v56
	v_and_b32_e32 v62, 0xff0000, v66
	v_perm_b32 v60, v68, v60, s96
	v_and_b32_e32 v54, 0xff00, v54
	v_and_b32_e32 v58, 0xff00, v58
	v_or3_b32 v68, v50, v54, v56
	v_or3_b32 v69, v60, v58, v62
	v_cmp_lt_f32_e32 vcc, 0, v91
	global_store_dwordx2 v[48:49], v[68:69], off
	v_mov_b32_e32 v50, v57
	v_cndmask_b32_e32 v48, 0, v52, vcc
	v_mov_b32_e32 v54, v53
	v_pk_mul_f32 v[50:51], v[48:49], v[50:51] op_sel_hi:[0,1]
	v_pk_mul_f32 v[52:53], v[48:49], v[54:55] op_sel_hi:[0,1]
	v_rndne_f32_e32 v49, v50
	v_rndne_f32_e32 v50, v51
	v_cvt_i32_f32_e32 v50, v50
	v_rndne_f32_e32 v51, v52
	v_rndne_f32_e32 v52, v53
	v_cvt_i32_f32_e32 v49, v49
	v_cvt_i32_f32_sdwa v51, v51 dst_sel:WORD_1 dst_unused:UNUSED_PAD src0_sel:DWORD
	v_cvt_i32_f32_e32 v52, v52
	v_lshlrev_b32_e32 v50, 8, v50
	v_and_b32_e32 v50, 0xff00, v50
	v_and_b32_e32 v51, 0xff0000, v51
	v_perm_b32 v49, v52, v49, s96
	v_mov_b32_e32 v66, v63
	v_mov_b32_e32 v60, v59
	v_or3_b32 v50, v49, v50, v51
	v_pk_mul_f32 v[52:53], v[48:49], v[66:67] op_sel_hi:[0,1]
	v_pk_mul_f32 v[48:49], v[48:49], v[60:61] op_sel_hi:[0,1]
	v_rndne_f32_e32 v49, v49
	v_rndne_f32_e32 v48, v48
	v_cvt_i32_f32_e32 v49, v49
	v_rndne_f32_e32 v51, v52
	v_rndne_f32_e32 v52, v53
	v_cvt_i32_f32_e32 v48, v48
	v_cvt_i32_f32_sdwa v51, v51 dst_sel:WORD_1 dst_unused:UNUSED_PAD src0_sel:DWORD
	v_cvt_i32_f32_e32 v52, v52
	v_lshlrev_b32_e32 v49, 8, v49
	v_and_b32_e32 v49, 0xff00, v49
	v_and_b32_e32 v51, 0xff0000, v51
	v_perm_b32 v48, v52, v48, s96
	s_waitcnt vmcnt(2)
	v_div_scale_f32 v52, s[2:3], v47, v47, s95
	v_or3_b32 v51, v48, v49, v51
	v_add_u32_e32 v48, 0x808, v78
	v_rcp_f32_e32 v53, v52
	v_ashrrev_i32_e32 v49, 31, v48
	v_lshlrev_b64 v[48:49], 12, v[48:49]
	v_lshl_add_u64 v[48:49], v[6:7], 0, v[48:49]
	global_store_dwordx2 v[48:49], v[50:51], off
	v_fma_f32 v48, -v52, v53, 1.0
	v_fmac_f32_e32 v53, v48, v53
	v_div_scale_f32 v48, vcc, s95, v47, s95
	v_mul_f32_e32 v49, v48, v53
	v_fma_f32 v50, -v52, v49, v48
	v_fmac_f32_e32 v49, v50, v53
	v_fma_f32 v48, -v52, v49, v48
	v_div_fmas_f32 v48, v48, v53, v49
	v_div_fixup_f32 v52, v48, v47, s95
	ds_read2_b32 v[48:49], v10 offset0:82 offset1:90
	ds_read2_b32 v[50:51], v10 offset0:115 offset1:123
	ds_read2_b32 v[54:55], v10 offset0:16 offset1:24
	ds_read2_b32 v[56:57], v10 offset0:49 offset1:57
	v_cmp_lt_f32_e32 vcc, 0, v47
	s_waitcnt lgkmcnt(3)
	v_mov_b32_e32 v58, v48
	v_cndmask_b32_e32 v52, 0, v52, vcc
	s_waitcnt lgkmcnt(2)
	v_mov_b32_e32 v59, v50
	s_waitcnt lgkmcnt(1)
	v_mov_b32_e32 v60, v54
	s_waitcnt lgkmcnt(0)
	v_mov_b32_e32 v61, v56
	v_pk_mul_f32 v[58:59], v[52:53], v[58:59] op_sel_hi:[0,1]
	v_pk_mul_f32 v[60:61], v[52:53], v[60:61] op_sel_hi:[0,1]
	v_rndne_f32_e32 v47, v60
	v_rndne_f32_e32 v48, v61
	v_rndne_f32_e32 v50, v58
	v_rndne_f32_e32 v53, v59
	ds_read2_b32 v[58:59], v10 offset0:214 offset1:222
	ds_read2_b32 v[60:61], v10 offset0:247 offset1:255
	ds_read2_b32 v[66:67], v10 offset0:148 offset1:156
	ds_read2_b32 v[68:69], v10 offset0:181 offset1:189
	v_cvt_i32_f32_e32 v48, v48
	v_cvt_i32_f32_e32 v47, v47
	v_cvt_i32_f32_sdwa v50, v50 dst_sel:WORD_1 dst_unused:UNUSED_PAD src0_sel:DWORD
	v_cvt_i32_f32_e32 v53, v53
	v_lshlrev_b32_e32 v48, 8, v48
	s_waitcnt lgkmcnt(3)
	v_mov_b32_e32 v70, v58
	s_waitcnt lgkmcnt(2)
	v_mov_b32_e32 v71, v60
	s_waitcnt lgkmcnt(1)
	v_mov_b32_e32 v72, v66
	s_waitcnt lgkmcnt(0)
	v_mov_b32_e32 v73, v68
	v_and_b32_e32 v48, 0xff00, v48
	v_and_b32_e32 v50, 0xff0000, v50
	v_perm_b32 v47, v53, v47, s96
	v_pk_mul_f32 v[70:71], v[52:53], v[70:71] op_sel_hi:[0,1]
	v_pk_mul_f32 v[52:53], v[52:53], v[72:73] op_sel_hi:[0,1]
	v_or3_b32 v62, v47, v48, v50
	v_rndne_f32_e32 v48, v53
	v_rndne_f32_e32 v47, v52
	v_cvt_i32_f32_e32 v48, v48
	v_rndne_f32_e32 v50, v70
	v_rndne_f32_e32 v52, v71
	v_cvt_i32_f32_e32 v47, v47
	v_cvt_i32_f32_sdwa v50, v50 dst_sel:WORD_1 dst_unused:UNUSED_PAD src0_sel:DWORD
	v_cvt_i32_f32_e32 v52, v52
	v_lshlrev_b32_e32 v48, 8, v48
	v_and_b32_e32 v48, 0xff00, v48
	v_and_b32_e32 v50, 0xff0000, v50
	v_perm_b32 v47, v52, v47, s96
	v_or3_b32 v63, v47, v48, v50
	s_waitcnt vmcnt(2)
	v_div_scale_f32 v47, s[2:3], v65, v65, s95
	v_rcp_f32_e32 v48, v47
	v_add_u32_e32 v52, 0x810, v78
	v_ashrrev_i32_e32 v53, 31, v52
	v_lshlrev_b64 v[52:53], 12, v[52:53]
	v_fma_f32 v50, -v47, v48, 1.0
	v_lshl_add_u64 v[52:53], v[6:7], 0, v[52:53]
	v_fmac_f32_e32 v48, v50, v48
	v_div_scale_f32 v50, vcc, s95, v65, s95
	global_store_dwordx2 v[52:53], v[62:63], off
	v_mul_f32_e32 v52, v50, v48
	v_fma_f32 v53, -v47, v52, v50
	v_fmac_f32_e32 v52, v53, v48
	v_fma_f32 v47, -v47, v52, v50
	v_div_fmas_f32 v47, v47, v48, v52
	v_div_fixup_f32 v47, v47, v65, s95
	v_cmp_lt_f32_e32 vcc, 0, v65
	v_mov_b32_e32 v56, v55
	v_mov_b32_e32 v50, v49
	v_cndmask_b32_e32 v48, 0, v47, vcc
	v_pk_mul_f32 v[52:53], v[48:49], v[56:57] op_sel_hi:[0,1]
	v_pk_mul_f32 v[50:51], v[48:49], v[50:51] op_sel_hi:[0,1]
	v_rndne_f32_e32 v49, v53
	v_rndne_f32_e32 v47, v52
	v_cvt_i32_f32_e32 v49, v49
	v_rndne_f32_e32 v50, v50
	v_rndne_f32_e32 v51, v51
	v_cvt_i32_f32_e32 v47, v47
	v_cvt_i32_f32_sdwa v50, v50 dst_sel:WORD_1 dst_unused:UNUSED_PAD src0_sel:DWORD
	v_cvt_i32_f32_e32 v51, v51
	v_lshlrev_b32_e32 v49, 8, v49
	v_and_b32_e32 v49, 0xff00, v49
	v_and_b32_e32 v50, 0xff0000, v50
	v_perm_b32 v47, v51, v47, s96
	v_mov_b32_e32 v60, v59
	v_mov_b32_e32 v68, v67
	v_or3_b32 v50, v47, v49, v50
	v_pk_mul_f32 v[52:53], v[48:49], v[60:61] op_sel_hi:[0,1]
	v_pk_mul_f32 v[48:49], v[48:49], v[68:69] op_sel_hi:[0,1]
	v_rndne_f32_e32 v47, v48
	v_rndne_f32_e32 v48, v49
	v_cvt_i32_f32_e32 v48, v48
	v_rndne_f32_e32 v49, v52
	v_rndne_f32_e32 v51, v53
	v_cvt_i32_f32_e32 v47, v47
	v_cvt_i32_f32_sdwa v49, v49 dst_sel:WORD_1 dst_unused:UNUSED_PAD src0_sel:DWORD
	v_cvt_i32_f32_e32 v51, v51
	v_lshlrev_b32_e32 v48, 8, v48
	v_and_b32_e32 v48, 0xff00, v48
	v_and_b32_e32 v49, 0xff0000, v49
	v_perm_b32 v47, v51, v47, s96
	v_or3_b32 v51, v47, v48, v49
	v_add_u32_e32 v48, 0x818, v78
	v_ashrrev_i32_e32 v49, 31, v48
	v_lshlrev_b64 v[48:49], 12, v[48:49]
	v_lshl_add_u64 v[6:7], v[6:7], 0, v[48:49]
	global_store_dwordx2 v[6:7], v[50:51], off
	s_waitcnt lgkmcnt(0)
	s_branch .LBB0_76
.LBB0_83:
	s_cmpk_lt_i32 s4, 0x2000
	s_cselect_b64 s[2:3], -1, 0
	v_writelane_b32 v250, s2, 0
	s_ashr_i32 s5, s4, 31
	s_nop 0
	v_writelane_b32 v250, s3, 1
	s_lshr_b32 s2, s5, 25
	s_add_i32 s2, s4, s2
	s_ashr_i32 s2, s2, 7
	s_lshl_b32 s95, s2, 6
	s_lshl_b32 s2, s2, 12
	s_lshl_b32 s3, s4, 5
	s_sub_i32 s2, s3, s2
	s_ashr_i32 s3, s2, 31
	v_writelane_b32 v250, s2, 2
	s_cmpk_gt_i32 s4, 0x1fff
	s_nop 0
	v_writelane_b32 v250, s3, 3
	s_cbranch_scc1 .LBB0_88
	v_readlane_b32 s2, v250, 2
	v_readlane_b32 s3, v250, 3
	v_readlane_b32 s36, v251, 21
	s_lshl_b64 s[2:3], s[2:3], 2
	v_readlane_b32 s44, v251, 29
	v_add_u32_e32 v0, s95, v9
	v_readlane_b32 s45, v251, 30
	s_add_u32 s2, s44, s2
	v_ashrrev_i32_e32 v1, 31, v0
	s_addc_u32 s3, s45, s3
	v_lshlrev_b64 v[0:1], 14, v[0:1]
	v_lshl_add_u64 v[2:3], s[2:3], 0, v[0:1]
	v_mov_b32_e32 v1, 0
	v_lshlrev_b32_e32 v0, 2, v8
	v_lshl_add_u64 v[2:3], v[2:3], 0, v[0:1]
	s_mov_b32 s8, 0x8000
	v_add_co_u32_e32 v4, vcc, s8, v2
	s_mov_b32 s9, 0x10000
	s_nop 0
	v_addc_co_u32_e32 v5, vcc, 0, v3, vcc
	v_add_co_u32_e32 v12, vcc, s9, v2
	s_mov_b32 s12, 0x18000
	s_nop 0
	v_addc_co_u32_e32 v13, vcc, 0, v3, vcc
	v_add_co_u32_e32 v14, vcc, s12, v2
	s_mov_b32 s13, 0x20000
	s_nop 0
	v_addc_co_u32_e32 v15, vcc, 0, v3, vcc
	v_add_co_u32_e32 v16, vcc, s13, v2
	s_mov_b32 s33, 0x28000
	s_nop 0
	v_addc_co_u32_e32 v17, vcc, 0, v3, vcc
	v_add_co_u32_e32 v22, vcc, s33, v2
	s_mov_b32 s34, 0x30000
	s_nop 0
	v_addc_co_u32_e32 v23, vcc, 0, v3, vcc
	v_add_co_u32_e32 v24, vcc, s34, v2
	s_mov_b32 s35, 0x38000
	s_nop 0
	v_addc_co_u32_e32 v25, vcc, 0, v3, vcc
	v_add_co_u32_e32 v26, vcc, s35, v2
	s_mov_b32 s58, 0x40000
	s_nop 0
	v_addc_co_u32_e32 v27, vcc, 0, v3, vcc
	global_load_dword v7, v[2:3], off nt
	global_load_dword v10, v[4:5], off nt
	global_load_dword v11, v[12:13], off nt
	s_nop 0
	global_load_dword v12, v[14:15], off nt
	global_load_dword v13, v[16:17], off nt
	s_nop 0
	global_load_dword v14, v[22:23], off nt
	global_load_dword v15, v[24:25], off nt
	global_load_dword v16, v[26:27], off nt
	v_add_co_u32_e32 v4, vcc, s58, v2
	s_mov_b32 s59, 0x48000
	s_nop 0
	v_addc_co_u32_e32 v5, vcc, 0, v3, vcc
	v_add_co_u32_e32 v22, vcc, s59, v2
	s_mov_b32 s68, 0x50000
	s_nop 0
	v_addc_co_u32_e32 v23, vcc, 0, v3, vcc
	v_add_co_u32_e32 v24, vcc, s68, v2
	s_mov_b32 s69, 0x58000
	s_nop 0
	v_addc_co_u32_e32 v25, vcc, 0, v3, vcc
	v_add_co_u32_e32 v26, vcc, s69, v2
	s_mov_b32 s70, 0x60000
	s_nop 0
	v_addc_co_u32_e32 v27, vcc, 0, v3, vcc
	v_add_co_u32_e32 v32, vcc, s70, v2
	s_mov_b32 s71, 0x68000
	s_nop 0
	v_addc_co_u32_e32 v33, vcc, 0, v3, vcc
	v_add_co_u32_e32 v34, vcc, s71, v2
	s_mov_b32 s72, 0x70000
	s_nop 0
	v_addc_co_u32_e32 v35, vcc, 0, v3, vcc
	v_add_co_u32_e32 v36, vcc, s72, v2
	s_mov_b32 s73, 0x78000
	s_nop 0
	v_addc_co_u32_e32 v37, vcc, 0, v3, vcc
	v_add_co_u32_e32 v38, vcc, s73, v2
	s_mov_b32 s74, 0x80000
	s_nop 0
	v_addc_co_u32_e32 v39, vcc, 0, v3, vcc
	global_load_dword v28, v[4:5], off nt
	global_load_dword v29, v[22:23], off nt
	global_load_dword v30, v[24:25], off nt
	global_load_dword v31, v[26:27], off nt
	s_nop 0
	global_load_dword v32, v[32:33], off nt
	s_nop 0
	global_load_dword v33, v[34:35], off nt
	s_nop 0
	global_load_dword v34, v[36:37], off nt
	global_load_dword v35, v[38:39], off nt
	v_add_co_u32_e32 v4, vcc, s74, v2
	s_mov_b32 s75, 0x88000
	s_nop 0
	v_addc_co_u32_e32 v5, vcc, 0, v3, vcc
	v_add_co_u32_e32 v22, vcc, s75, v2
	s_mov_b32 s76, 0x90000
	s_nop 0
	v_addc_co_u32_e32 v23, vcc, 0, v3, vcc
	v_add_co_u32_e32 v24, vcc, s76, v2
	s_mov_b32 s77, 0x98000
	s_nop 0
	v_addc_co_u32_e32 v25, vcc, 0, v3, vcc
	v_add_co_u32_e32 v26, vcc, s77, v2
	s_mov_b32 s78, 0xa0000
	s_nop 0
	v_addc_co_u32_e32 v27, vcc, 0, v3, vcc
	v_add_co_u32_e32 v36, vcc, s78, v2
	s_mov_b32 s79, 0xa8000
	s_nop 0
	v_addc_co_u32_e32 v37, vcc, 0, v3, vcc
	v_add_co_u32_e32 v38, vcc, s79, v2
	s_mov_b32 s80, 0xb0000
	s_nop 0
	v_addc_co_u32_e32 v39, vcc, 0, v3, vcc
	v_add_co_u32_e32 v40, vcc, s80, v2
	s_mov_b32 s81, 0xb8000
	s_nop 0
	v_addc_co_u32_e32 v41, vcc, 0, v3, vcc
	v_add_co_u32_e32 v42, vcc, s81, v2
	s_mov_b32 s82, 0xc0000
	s_nop 0
	v_addc_co_u32_e32 v43, vcc, 0, v3, vcc
	global_load_dword v44, v[4:5], off nt
	global_load_dword v45, v[22:23], off nt
	global_load_dword v46, v[24:25], off nt
	global_load_dword v47, v[26:27], off nt
	global_load_dword v48, v[36:37], off nt
	global_load_dword v49, v[38:39], off nt
	global_load_dword v50, v[40:41], off nt
	global_load_dword v58, v[42:43], off nt
	v_add_co_u32_e32 v4, vcc, s82, v2
	s_mov_b32 s83, 0xc8000
	s_nop 0
	v_addc_co_u32_e32 v5, vcc, 0, v3, vcc
	v_add_co_u32_e32 v22, vcc, s83, v2
	s_mov_b32 s84, 0xd0000
	s_nop 0
	v_addc_co_u32_e32 v23, vcc, 0, v3, vcc
	v_add_co_u32_e32 v24, vcc, s84, v2
	s_mov_b32 s85, 0xd8000
	s_nop 0
	v_addc_co_u32_e32 v25, vcc, 0, v3, vcc
	v_add_co_u32_e32 v26, vcc, s85, v2
	s_mov_b32 s2, 0xe0000
	s_nop 0
	v_addc_co_u32_e32 v27, vcc, 0, v3, vcc
	v_add_co_u32_e32 v36, vcc, s2, v2
	s_mov_b32 s2, 0xe8000
	s_nop 0
	v_addc_co_u32_e32 v37, vcc, 0, v3, vcc
	v_add_co_u32_e32 v38, vcc, s2, v2
	s_mov_b32 s2, 0xf0000
	s_nop 0
	v_addc_co_u32_e32 v39, vcc, 0, v3, vcc
	v_add_co_u32_e32 v40, vcc, s2, v2
	s_mov_b32 s2, 0xf8000
	s_nop 0
	v_addc_co_u32_e32 v41, vcc, 0, v3, vcc
	v_add_co_u32_e32 v2, vcc, s2, v2
	s_movk_i32 s2, 0x84
	s_nop 0
	v_addc_co_u32_e32 v3, vcc, 0, v3, vcc
	global_load_dword v60, v[4:5], off nt
	global_load_dword v61, v[22:23], off nt
	global_load_dword v62, v[24:25], off nt
	global_load_dword v63, v[26:27], off nt
	global_load_dword v65, v[36:37], off nt
	global_load_dword v66, v[38:39], off nt
	global_load_dword v74, v[40:41], off nt
	global_load_dword v76, v[2:3], off nt
	v_add_u32_e32 v6, s7, v0
	v_mul_lo_u32 v17, v9, s2
	v_and_b32_e32 v0, 56, v21
	v_readlane_b32 s2, v251, 52
	v_mul_u32_u24_e32 v4, 0x84, v0
	v_lshlrev_b32_e32 v0, 1, v0
	v_readlane_b32 s3, v251, 53
	v_add_u32_e32 v6, v6, v17
	s_movk_i32 s89, 0x7fff
	v_lshl_add_u64 v[2:3], s[2:3], 0, v[0:1]
	v_readlane_b32 s2, v251, 42
	s_lshl_b32 s86, s2, 5
	v_readlane_b32 s2, v251, 4
	v_readlane_b32 s3, v251, 3
	v_lshlrev_b32_e32 v0, 2, v20
	s_lshl_b32 s2, s2, 8
	s_lshl_b32 s87, s3, 8
	v_add3_u32 v4, s7, v4, v0
	v_add_u32_e32 v5, s2, v20
	s_add_i32 s88, s2, s87
	v_lshlrev_b32_e32 v0, 2, v8
	s_mov_b32 s92, 0xffff0000
	v_mov_b32_e32 v75, v1
	v_mov_b32_e32 v67, v1
	v_mov_b32_e32 v68, v1
	v_mov_b32_e32 v69, v1
	v_mov_b32_e32 v70, v1
	v_mov_b32_e32 v71, v1
	v_mov_b32_e32 v72, v1
	v_mov_b32_e32 v73, v1
	v_mov_b32_e32 v59, v1
	v_mov_b32_e32 v51, v1
	v_mov_b32_e32 v52, v1
	v_mov_b32_e32 v53, v1
	v_mov_b32_e32 v54, v1
	v_mov_b32_e32 v55, v1
	v_mov_b32_e32 v56, v1
	v_mov_b32_e32 v57, v1
	v_mov_b32_e32 v43, v1
	v_mov_b32_e32 v36, v1
	v_mov_b32_e32 v37, v1
	v_mov_b32_e32 v38, v1
	v_mov_b32_e32 v39, v1
	v_mov_b32_e32 v40, v1
	v_mov_b32_e32 v41, v1
	v_mov_b32_e32 v42, v1
	v_mov_b32_e32 v27, v1
	v_mov_b32_e32 v17, v1
	v_mov_b32_e32 v19, v1
	v_mov_b32_e32 v22, v1
	v_mov_b32_e32 v23, v1
	v_mov_b32_e32 v24, v1
	v_mov_b32_e32 v25, v1
	v_mov_b32_e32 v26, v1
	s_mov_b32 s94, s4
	v_readlane_b32 s37, v251, 22
	v_readlane_b32 s38, v251, 23
	v_readlane_b32 s39, v251, 24
	v_readlane_b32 s40, v251, 25
	v_readlane_b32 s41, v251, 26
	v_readlane_b32 s42, v251, 27
	v_readlane_b32 s43, v251, 28
	v_readlane_b32 s46, v251, 31
	v_readlane_b32 s47, v251, 32
	v_readlane_b32 s48, v251, 33
	v_readlane_b32 s49, v251, 34
	v_readlane_b32 s50, v251, 35
	v_readlane_b32 s51, v251, 36
	s_branch .LBB0_86

.LBB0_86:
	s_add_i32 s93, s94, s6
	s_cmpk_gt_i32 s93, 0x1fff
	s_cselect_b64 s[10:11], -1, 0
	s_and_b64 vcc, exec, s[10:11]
	s_cbranch_vccnz .LBB0_85
	s_ashr_i32 s2, s93, 31
	s_lshr_b32 s2, s2, 25
	s_add_i32 s2, s93, s2
	s_ashr_i32 s3, s2, 7
	v_lshl_add_u32 v22, s3, 6, v9
	s_add_i32 s2, s86, s88
	s_lshl_b32 s14, s3, 12
	v_ashrrev_i32_e32 v23, 31, v22
	v_readlane_b32 s16, v251, 21
	s_sub_i32 s2, s2, s14
	v_lshlrev_b64 v[22:23], 14, v[22:23]
	v_readlane_b32 s24, v251, 29
	v_readlane_b32 s25, v251, 30
	s_ashr_i32 s3, s2, 31
	v_readlane_b32 s17, v251, 22
	v_lshl_add_u64 v[22:23], s[24:25], 0, v[22:23]
	v_lshl_add_u64 v[22:23], s[2:3], 2, v[22:23]
	v_lshl_add_u64 v[68:69], v[22:23], 0, v[0:1]
	v_add_co_u32_e32 v22, vcc, s8, v68
	v_readlane_b32 s18, v251, 23
	s_nop 0
	v_addc_co_u32_e32 v23, vcc, 0, v69, vcc
	v_add_co_u32_e32 v36, vcc, s9, v68
	v_readlane_b32 s19, v251, 24
	s_nop 0
	v_addc_co_u32_e32 v37, vcc, 0, v69, vcc
	v_add_co_u32_e32 v38, vcc, s12, v68
	v_readlane_b32 s20, v251, 25
	s_nop 0
	v_addc_co_u32_e32 v39, vcc, 0, v69, vcc
	v_add_co_u32_e32 v40, vcc, s13, v68
	v_readlane_b32 s21, v251, 26
	s_nop 0
	v_addc_co_u32_e32 v41, vcc, 0, v69, vcc
	v_add_co_u32_e32 v42, vcc, s33, v68
	v_readlane_b32 s22, v251, 27
	s_nop 0
	v_addc_co_u32_e32 v43, vcc, 0, v69, vcc
	v_add_co_u32_e32 v52, vcc, s34, v68
	v_readlane_b32 s23, v251, 28
	s_nop 0
	v_addc_co_u32_e32 v53, vcc, 0, v69, vcc
	v_add_co_u32_e32 v54, vcc, s35, v68
	v_readlane_b32 s26, v251, 31
	s_nop 0
	v_addc_co_u32_e32 v55, vcc, 0, v69, vcc
	global_load_dword v26, v[68:69], off nt
	global_load_dword v25, v[22:23], off nt
	global_load_dword v24, v[36:37], off nt
	s_nop 0
	global_load_dword v23, v[38:39], off nt
	global_load_dword v22, v[40:41], off nt
	global_load_dword v19, v[42:43], off nt
	global_load_dword v17, v[52:53], off nt
	global_load_dword v27, v[54:55], off nt
	v_add_co_u32_e32 v36, vcc, s58, v68
	v_readlane_b32 s27, v251, 32
	s_nop 0
	v_addc_co_u32_e32 v37, vcc, 0, v69, vcc
	v_add_co_u32_e32 v38, vcc, s59, v68
	v_readlane_b32 s28, v251, 33
	s_nop 0
	v_addc_co_u32_e32 v39, vcc, 0, v69, vcc
	v_add_co_u32_e32 v52, vcc, s68, v68
	v_readlane_b32 s29, v251, 34
	s_nop 0
	v_addc_co_u32_e32 v53, vcc, 0, v69, vcc
	v_add_co_u32_e32 v54, vcc, s69, v68
	v_readlane_b32 s30, v251, 35
	s_nop 0
	v_addc_co_u32_e32 v55, vcc, 0, v69, vcc
	v_add_co_u32_e32 v56, vcc, s70, v68
	v_readlane_b32 s31, v251, 36
	s_nop 0
	v_addc_co_u32_e32 v57, vcc, 0, v69, vcc
	v_add_co_u32_e32 v70, vcc, s71, v68
	s_nop 1
	v_addc_co_u32_e32 v71, vcc, 0, v69, vcc
	v_add_co_u32_e32 v72, vcc, s72, v68
	s_nop 1
	v_addc_co_u32_e32 v73, vcc, 0, v69, vcc
	v_add_co_u32_e32 v78, vcc, s73, v68
	s_nop 1
	v_addc_co_u32_e32 v79, vcc, 0, v69, vcc
	global_load_dword v42, v[36:37], off nt
	global_load_dword v41, v[38:39], off nt
	global_load_dword v40, v[52:53], off nt
	s_nop 0
	global_load_dword v39, v[54:55], off nt
	global_load_dword v38, v[56:57], off nt
	global_load_dword v37, v[70:71], off nt
	global_load_dword v36, v[72:73], off nt
	global_load_dword v43, v[78:79], off nt
	v_add_co_u32_e32 v52, vcc, s74, v68
	s_nop 1
	v_addc_co_u32_e32 v53, vcc, 0, v69, vcc
	v_add_co_u32_e32 v54, vcc, s75, v68
	s_nop 1
	v_addc_co_u32_e32 v55, vcc, 0, v69, vcc
	v_add_co_u32_e32 v70, vcc, s76, v68
	s_nop 1
	v_addc_co_u32_e32 v71, vcc, 0, v69, vcc
	v_add_co_u32_e32 v72, vcc, s77, v68
	s_nop 1
	v_addc_co_u32_e32 v73, vcc, 0, v69, vcc
	v_add_co_u32_e32 v78, vcc, s78, v68
	s_nop 1
	v_addc_co_u32_e32 v79, vcc, 0, v69, vcc
	v_add_co_u32_e32 v80, vcc, s79, v68
	s_nop 1
	v_addc_co_u32_e32 v81, vcc, 0, v69, vcc
	v_add_co_u32_e32 v82, vcc, s80, v68
	s_nop 1
	v_addc_co_u32_e32 v83, vcc, 0, v69, vcc
	v_add_co_u32_e32 v84, vcc, s81, v68
	s_nop 1
	v_addc_co_u32_e32 v85, vcc, 0, v69, vcc
	global_load_dword v57, v[52:53], off nt
	global_load_dword v56, v[54:55], off nt
	s_nop 0
	global_load_dword v55, v[70:71], off nt
	global_load_dword v54, v[72:73], off nt
	global_load_dword v53, v[78:79], off nt
	global_load_dword v52, v[80:81], off nt
	global_load_dword v51, v[82:83], off nt
	global_load_dword v59, v[84:85], off nt
	v_add_co_u32_e32 v70, vcc, s82, v68
	s_nop 1
	v_addc_co_u32_e32 v71, vcc, 0, v69, vcc
	v_add_co_u32_e32 v78, vcc, s83, v68
	s_nop 1
	v_addc_co_u32_e32 v79, vcc, 0, v69, vcc
	v_add_co_u32_e32 v80, vcc, s84, v68
	s_nop 1
	v_addc_co_u32_e32 v81, vcc, 0, v69, vcc
	v_add_co_u32_e32 v82, vcc, s85, v68
	s_nop 1
	v_addc_co_u32_e32 v83, vcc, 0, v69, vcc
	v_add_co_u32_e32 v84, vcc, 0xe0000, v68
	s_nop 1
	v_addc_co_u32_e32 v85, vcc, 0, v69, vcc
	v_add_co_u32_e32 v86, vcc, 0xe8000, v68
	s_nop 1
	v_addc_co_u32_e32 v87, vcc, 0, v69, vcc
	v_add_co_u32_e32 v88, vcc, 0xf0000, v68
	s_nop 1
	v_addc_co_u32_e32 v89, vcc, 0, v69, vcc
	v_add_co_u32_e32 v90, vcc, 0xf8000, v68
	s_nop 1
	v_addc_co_u32_e32 v91, vcc, 0, v69, vcc
	global_load_dword v73, v[70:71], off nt
	global_load_dword v72, v[78:79], off nt
	s_nop 0
	global_load_dword v71, v[80:81], off nt
	global_load_dword v70, v[82:83], off nt
	global_load_dword v69, v[84:85], off nt
	global_load_dword v68, v[86:87], off nt
	global_load_dword v67, v[88:89], off nt
	global_load_dword v75, v[90:91], off nt
	s_branch .LBB0_85
.LBB0_88:
	v_readlane_b32 s2, v251, 0
	s_and_b32 s33, s2, 0xffffffc0
	v_readlane_b32 s2, v251, 4
	s_lshl_b32 s58, s2, 9
	v_readlane_b32 s2, v251, 3
	s_add_i32 s93, s58, s33
	s_lshl_b32 s34, s2, 9
	s_cmp_gt_i32 s4, 0xabff
	s_cbranch_scc1 .LBB0_101
	s_mul_hi_i32 s2, s4, 0x2fa0be83
	s_lshr_b32 s3, s2, 31
	s_ashr_i32 s2, s2, 7
	s_add_i32 s8, s2, s3
	s_mul_i32 s2, s8, 0xfffffd50
	s_add_i32 s2, s2, s4
	s_lshl_b32 s2, s2, 5
	s_ashr_i32 s3, s2, 31
	v_readlane_b32 s36, v251, 21
	s_lshl_b64 s[2:3], s[2:3], 2
	v_readlane_b32 s48, v251, 33
	v_readlane_b32 s49, v251, 34
	s_add_u32 s2, s48, s2
	s_addc_u32 s3, s49, s3
	v_lshl_add_u32 v2, s8, 6, v9
	s_mov_b32 s59, 0x15800
	v_mov_b64_e32 v[0:1], s[2:3]
	v_mad_i64_i32 v[0:1], s[2:3], v2, s59, v[0:1]
	v_mov_b32_e32 v11, 0
	v_lshlrev_b32_e32 v10, 2, v8
	v_lshl_add_u64 v[0:1], v[0:1], 0, v[10:11]
	s_mov_b32 s68, 0x2b000
	v_add_co_u32_e32 v2, vcc, s68, v0
	s_mov_b32 s69, 0x56000
	s_nop 0
	v_addc_co_u32_e32 v3, vcc, 0, v1, vcc
	v_add_co_u32_e32 v4, vcc, s69, v0
	s_mov_b32 s70, 0x81000
	s_nop 0
	v_addc_co_u32_e32 v5, vcc, 0, v1, vcc
	v_add_co_u32_e32 v6, vcc, s70, v0
	s_mov_b32 s71, 0xac000
	s_nop 0
	v_addc_co_u32_e32 v7, vcc, 0, v1, vcc
	v_add_co_u32_e32 v12, vcc, s71, v0
	s_mov_b32 s72, 0xd7000
	s_nop 0
	v_addc_co_u32_e32 v13, vcc, 0, v1, vcc
	v_add_co_u32_e32 v14, vcc, s72, v0
	s_mov_b32 s73, 0x102000
	s_nop 0
	v_addc_co_u32_e32 v15, vcc, 0, v1, vcc
	v_add_co_u32_e32 v22, vcc, s73, v0
	s_mov_b32 s74, 0x12d000
	s_nop 0
	v_addc_co_u32_e32 v23, vcc, 0, v1, vcc
	v_add_co_u32_e32 v24, vcc, s74, v0
	s_mov_b32 s75, 0x158000
	s_nop 0
	v_addc_co_u32_e32 v25, vcc, 0, v1, vcc
	global_load_dword v16, v[0:1], off nt
	global_load_dword v17, v[2:3], off nt
	global_load_dword v39, v[4:5], off nt
	global_load_dword v40, v[6:7], off nt
	global_load_dword v41, v[12:13], off nt
	global_load_dword v42, v[14:15], off nt
	global_load_dword v43, v[22:23], off nt
	global_load_dword v51, v[24:25], off nt
	v_add_co_u32_e32 v2, vcc, s75, v0
	s_mov_b32 s76, 0x183000
	s_nop 0
	v_addc_co_u32_e32 v3, vcc, 0, v1, vcc
	v_add_co_u32_e32 v4, vcc, s76, v0
	s_mov_b32 s77, 0x1ae000
	s_nop 0
	v_addc_co_u32_e32 v5, vcc, 0, v1, vcc
	v_add_co_u32_e32 v6, vcc, s77, v0
	s_mov_b32 s78, 0x1d9000
	s_nop 0
	v_addc_co_u32_e32 v7, vcc, 0, v1, vcc
	v_add_co_u32_e32 v12, vcc, s78, v0
	s_mov_b32 s79, 0x204000
	s_nop 0
	v_addc_co_u32_e32 v13, vcc, 0, v1, vcc
	v_add_co_u32_e32 v14, vcc, s79, v0
	s_mov_b32 s80, 0x22f000
	s_nop 0
	v_addc_co_u32_e32 v15, vcc, 0, v1, vcc
	v_add_co_u32_e32 v22, vcc, s80, v0
	s_mov_b32 s81, 0x25a000
	s_nop 0
	v_addc_co_u32_e32 v23, vcc, 0, v1, vcc
	v_add_co_u32_e32 v24, vcc, s81, v0
	s_mov_b32 s82, 0x285000
	s_nop 0
	v_addc_co_u32_e32 v25, vcc, 0, v1, vcc
	v_add_co_u32_e32 v26, vcc, s82, v0
	s_mov_b32 s83, 0x2b0000
	s_nop 0
	v_addc_co_u32_e32 v27, vcc, 0, v1, vcc
	global_load_dword v53, v[2:3], off nt
	global_load_dword v54, v[4:5], off nt
	global_load_dword v55, v[6:7], off nt
	global_load_dword v56, v[12:13], off nt
	global_load_dword v57, v[14:15], off nt
	global_load_dword v58, v[22:23], off nt
	global_load_dword v59, v[24:25], off nt
	global_load_dword v69, v[26:27], off nt
	v_add_co_u32_e32 v2, vcc, s83, v0
	s_mov_b32 s84, 0x2db000
	s_nop 0
	v_addc_co_u32_e32 v3, vcc, 0, v1, vcc
	v_add_co_u32_e32 v4, vcc, s84, v0
	s_mov_b32 s85, 0x306000
	s_nop 0
	v_addc_co_u32_e32 v5, vcc, 0, v1, vcc
	v_add_co_u32_e32 v6, vcc, s85, v0
	s_mov_b32 s86, 0x331000
	s_nop 0
	v_addc_co_u32_e32 v7, vcc, 0, v1, vcc
	v_add_co_u32_e32 v12, vcc, s86, v0
	s_mov_b32 s87, 0x35c000
	s_nop 0
	v_addc_co_u32_e32 v13, vcc, 0, v1, vcc
	v_add_co_u32_e32 v14, vcc, s87, v0
	s_mov_b32 s88, 0x387000
	s_nop 0
	v_addc_co_u32_e32 v15, vcc, 0, v1, vcc
	v_add_co_u32_e32 v22, vcc, s88, v0
	s_mov_b32 s89, 0x3b2000
	s_nop 0
	v_addc_co_u32_e32 v23, vcc, 0, v1, vcc
	v_add_co_u32_e32 v24, vcc, s89, v0
	s_mov_b32 s92, 0x3dd000
	s_nop 0
	v_addc_co_u32_e32 v25, vcc, 0, v1, vcc
	v_add_co_u32_e32 v26, vcc, s92, v0
	s_mov_b32 s8, s93
	s_nop 0
	v_addc_co_u32_e32 v27, vcc, 0, v1, vcc
	s_mov_b32 s93, 0x408000
	global_load_dword v70, v[2:3], off nt
	global_load_dword v71, v[4:5], off nt
	global_load_dword v72, v[6:7], off nt
	global_load_dword v73, v[12:13], off nt
	global_load_dword v74, v[14:15], off nt
	global_load_dword v75, v[22:23], off nt
	global_load_dword v76, v[24:25], off nt
	global_load_dword v77, v[26:27], off nt
	v_add_co_u32_e32 v2, vcc, s93, v0
	s_mov_b32 s94, 0x433000
	s_nop 0
	v_addc_co_u32_e32 v3, vcc, 0, v1, vcc
	v_add_co_u32_e32 v4, vcc, s94, v0
	v_writelane_b32 v250, s95, 4
	s_nop 0
	v_addc_co_u32_e32 v5, vcc, 0, v1, vcc
	s_mov_b32 s95, 0x45e000
	v_add_co_u32_e32 v6, vcc, s95, v0
	s_mov_b32 s96, 0x489000
	s_nop 0
	v_addc_co_u32_e32 v7, vcc, 0, v1, vcc
	v_add_co_u32_e32 v12, vcc, s96, v0
	s_mov_b32 s2, 0x4b4000
	s_nop 0
	v_addc_co_u32_e32 v13, vcc, 0, v1, vcc
	v_add_co_u32_e32 v14, vcc, s2, v0
	s_mov_b32 s2, 0x4df000
	s_nop 0
	v_addc_co_u32_e32 v15, vcc, 0, v1, vcc
	v_add_co_u32_e32 v22, vcc, s2, v0
	s_mov_b32 s2, 0x50a000
	s_nop 0
	v_addc_co_u32_e32 v23, vcc, 0, v1, vcc
	v_add_co_u32_e32 v24, vcc, s2, v0
	s_mov_b32 s2, 0x535000
	s_nop 0
	v_addc_co_u32_e32 v25, vcc, 0, v1, vcc
	v_add_co_u32_e32 v0, vcc, s2, v0
	s_movk_i32 s2, 0x84
	s_nop 0
	v_addc_co_u32_e32 v1, vcc, 0, v1, vcc
	global_load_dword v78, v[2:3], off nt
	global_load_dword v79, v[4:5], off nt
	global_load_dword v80, v[6:7], off nt
	global_load_dword v81, v[12:13], off nt
	global_load_dword v82, v[14:15], off nt
	global_load_dword v83, v[22:23], off nt
	global_load_dword v84, v[24:25], off nt
	global_load_dword v85, v[0:1], off nt
	v_mul_lo_u32 v3, v9, s2
	v_readlane_b32 s2, v251, 54
	v_readlane_b32 s46, v251, 31
	v_readlane_b32 s47, v251, 32
	v_add_u32_e32 v2, s7, v10
	v_lshlrev_b32_e32 v10, 3, v18
	v_readlane_b32 s3, v251, 55
	s_cmp_lg_u64 s[46:47], 0
	s_cselect_b64 s[10:11], -1, 0
	v_lshl_add_u64 v[14:15], s[2:3], 0, v[10:11]
	v_readlane_b32 s2, v251, 4
	v_readlane_b32 s3, v251, 42
	v_lshlrev_b32_e32 v0, 5, v18
	v_mov_b32_e32 v1, v11
	s_lshl_b32 s2, s2, 8
	s_lshl_b32 s3, s3, 5
	v_readlane_b32 s37, v251, 22
	v_readlane_b32 s44, v251, 29
	v_lshl_add_u64 v[12:13], s[46:47], 0, v[0:1]
	v_mul_u32_u24_e32 v0, 0x420, v18
	v_lshlrev_b32_e32 v1, 2, v20
	s_add_i32 s46, s2, s3
	v_readlane_b32 s2, v251, 3
	s_mov_b32 s15, s58
	v_add3_u32 v19, s7, v0, v1
	s_lshl_b32 s47, s2, 8
	v_lshlrev_b32_e32 v10, 2, v8
	v_add_u32_e32 v22, v2, v3
	s_mov_b32 s97, 0x42fe0000
	s_mov_b32 s35, 0x40c0c00
	s_mov_b32 s37, s8
	v_mov_b32_e32 v68, v11
	v_mov_b32_e32 v60, v11
	v_mov_b32_e32 v61, v11
	v_mov_b32_e32 v62, v11
	v_mov_b32_e32 v63, v11
	v_mov_b32_e32 v65, v11
	v_mov_b32_e32 v66, v11
	v_mov_b32_e32 v67, v11
	v_mov_b32_e32 v52, v11
	v_mov_b32_e32 v44, v11
	v_mov_b32_e32 v45, v11
	v_mov_b32_e32 v46, v11
	v_mov_b32_e32 v47, v11
	v_mov_b32_e32 v48, v11
	v_mov_b32_e32 v49, v11
	v_mov_b32_e32 v50, v11
	v_mov_b32_e32 v38, v11
	v_mov_b32_e32 v31, v11
	v_mov_b32_e32 v32, v11
	v_mov_b32_e32 v33, v11
	v_mov_b32_e32 v34, v11
	v_mov_b32_e32 v35, v11
	v_mov_b32_e32 v36, v11
	v_mov_b32_e32 v37, v11
	v_mov_b32_e32 v30, v11
	v_mov_b32_e32 v23, v11
	v_mov_b32_e32 v24, v11
	v_mov_b32_e32 v25, v11
	v_mov_b32_e32 v26, v11
	v_mov_b32_e32 v27, v11
	v_mov_b32_e32 v28, v11
	v_mov_b32_e32 v29, v11
	s_mov_b32 s44, s4
	v_readlane_b32 s38, v251, 23
	v_readlane_b32 s39, v251, 24
	v_readlane_b32 s40, v251, 25
	v_readlane_b32 s41, v251, 26
	v_readlane_b32 s42, v251, 27
	v_readlane_b32 s43, v251, 28
	v_readlane_b32 s45, v251, 30
	v_readlane_b32 s50, v251, 35
	v_readlane_b32 s51, v251, 36
	s_branch .LBB0_93
.LBB0_90:
	v_add_u32_e32 v0, s2, v20
	v_readlane_b32 s2, v251, 45
	v_ashrrev_i32_e32 v1, 31, v0
	v_readlane_b32 s3, v251, 46
	s_lshl_b32 s44, s58, 6
	s_andn2_b64 vcc, exec, s[10:11]
	v_lshl_add_u64 v[0:1], v[0:1], 2, s[2:3]
	global_load_dword v89, v[0:1], off nt
	global_load_dword v88, v[0:1], off offset:32 nt
	global_load_dword v87, v[0:1], off offset:64 nt
	global_load_dword v86, v[0:1], off offset:96 nt
	s_ashr_i32 s45, s44, 31
	s_cbranch_vccnz .LBB0_99
	v_lshl_add_u64 v[4:5], s[44:45], 2, v[12:13]
	global_load_dwordx4 v[0:3], v[4:5], off offset:16 nt
	s_nop 0
	global_load_dwordx4 v[4:7], v[4:5], off nt

.LBB0_93:
	s_add_i32 s9, s44, s6
	s_cmp_gt_i32 s9, 0xabff
	s_cselect_b64 s[12:13], -1, 0
	s_and_b64 vcc, exec, s[12:13]
	s_cbranch_vccnz .LBB0_95
	s_mul_hi_i32 s2, s9, 0x2fa0be83
	s_lshr_b32 s3, s2, 31
	s_ashr_i32 s2, s2, 7
	s_add_i32 s3, s2, s3
	v_readlane_b32 s16, v251, 21
	s_mul_i32 s2, s3, 0xffffaa00
	s_add_i32 s14, s47, s46
	v_readlane_b32 s28, v251, 33
	v_readlane_b32 s29, v251, 34
	s_add_i32 s2, s14, s2
	v_lshl_add_u32 v2, s3, 6, v9
	v_mov_b64_e32 v[0:1], s[28:29]
	v_mad_i64_i32 v[0:1], vcc, v2, s59, v[0:1]
	s_ashr_i32 s3, s2, 31
	v_lshl_add_u64 v[0:1], s[2:3], 2, v[0:1]
	v_lshl_add_u64 v[0:1], v[0:1], 0, v[10:11]
	v_add_co_u32_e32 v2, vcc, s68, v0
	v_readlane_b32 s17, v251, 22
	s_nop 0
	v_addc_co_u32_e32 v3, vcc, 0, v1, vcc
	v_add_co_u32_e32 v4, vcc, s69, v0
	v_readlane_b32 s18, v251, 23
	s_nop 0
	v_addc_co_u32_e32 v5, vcc, 0, v1, vcc
	v_add_co_u32_e32 v6, vcc, s70, v0
	v_readlane_b32 s19, v251, 24
	s_nop 0
	v_addc_co_u32_e32 v7, vcc, 0, v1, vcc
	v_add_co_u32_e32 v24, vcc, s71, v0
	v_readlane_b32 s20, v251, 25
	s_nop 0
	v_addc_co_u32_e32 v25, vcc, 0, v1, vcc
	v_add_co_u32_e32 v30, vcc, s72, v0
	v_readlane_b32 s21, v251, 26
	s_nop 0
	v_addc_co_u32_e32 v31, vcc, 0, v1, vcc
	v_add_co_u32_e32 v32, vcc, s73, v0
	v_readlane_b32 s22, v251, 27
	s_nop 0
	v_addc_co_u32_e32 v33, vcc, 0, v1, vcc
	v_add_co_u32_e32 v34, vcc, s74, v0
	v_readlane_b32 s23, v251, 28
	s_nop 0
	v_addc_co_u32_e32 v35, vcc, 0, v1, vcc
	global_load_dword v29, v[0:1], off nt
	global_load_dword v28, v[2:3], off nt
	global_load_dword v27, v[4:5], off nt
	global_load_dword v26, v[6:7], off nt
	s_nop 0
	global_load_dword v25, v[24:25], off nt
	s_nop 0
	global_load_dword v24, v[30:31], off nt
	global_load_dword v23, v[32:33], off nt
	s_nop 0
	global_load_dword v30, v[34:35], off nt
	v_add_co_u32_e32 v2, vcc, s75, v0
	v_readlane_b32 s24, v251, 29
	s_nop 0
	v_addc_co_u32_e32 v3, vcc, 0, v1, vcc
	v_add_co_u32_e32 v4, vcc, s76, v0
	v_readlane_b32 s25, v251, 30
	s_nop 0
	v_addc_co_u32_e32 v5, vcc, 0, v1, vcc
	v_add_co_u32_e32 v6, vcc, s77, v0
	v_readlane_b32 s26, v251, 31
	s_nop 0
	v_addc_co_u32_e32 v7, vcc, 0, v1, vcc
	v_add_co_u32_e32 v32, vcc, s78, v0
	v_readlane_b32 s27, v251, 32
	s_nop 0
	v_addc_co_u32_e32 v33, vcc, 0, v1, vcc
	v_add_co_u32_e32 v44, vcc, s79, v0
	v_readlane_b32 s30, v251, 35
	s_nop 0
	v_addc_co_u32_e32 v45, vcc, 0, v1, vcc
	v_add_co_u32_e32 v46, vcc, s80, v0
	v_readlane_b32 s31, v251, 36
	s_nop 0
	v_addc_co_u32_e32 v47, vcc, 0, v1, vcc
	v_add_co_u32_e32 v48, vcc, s81, v0
	s_nop 1
	v_addc_co_u32_e32 v49, vcc, 0, v1, vcc
	v_add_co_u32_e32 v60, vcc, s82, v0
	s_nop 1
	v_addc_co_u32_e32 v61, vcc, 0, v1, vcc
	global_load_dword v37, v[2:3], off nt
	global_load_dword v36, v[4:5], off nt
	global_load_dword v35, v[6:7], off nt
	global_load_dword v34, v[32:33], off nt
	s_nop 0
	global_load_dword v33, v[44:45], off nt
	global_load_dword v32, v[46:47], off nt
	global_load_dword v31, v[48:49], off nt
	global_load_dword v38, v[60:61], off nt
	v_add_co_u32_e32 v2, vcc, s83, v0
	s_nop 1
	v_addc_co_u32_e32 v3, vcc, 0, v1, vcc
	v_add_co_u32_e32 v4, vcc, s84, v0
	s_nop 1
	v_addc_co_u32_e32 v5, vcc, 0, v1, vcc
	v_add_co_u32_e32 v6, vcc, s85, v0
	s_nop 1
	v_addc_co_u32_e32 v7, vcc, 0, v1, vcc
	v_add_co_u32_e32 v44, vcc, s86, v0
	s_nop 1
	v_addc_co_u32_e32 v45, vcc, 0, v1, vcc
	v_add_co_u32_e32 v60, vcc, s87, v0
	s_nop 1
	v_addc_co_u32_e32 v61, vcc, 0, v1, vcc
	v_add_co_u32_e32 v62, vcc, s88, v0
	s_nop 1
	v_addc_co_u32_e32 v63, vcc, 0, v1, vcc
	v_add_co_u32_e32 v66, vcc, s89, v0
	s_nop 1
	v_addc_co_u32_e32 v67, vcc, 0, v1, vcc
	v_add_co_u32_e32 v86, vcc, s92, v0
	s_nop 1
	v_addc_co_u32_e32 v87, vcc, 0, v1, vcc
	global_load_dword v50, v[2:3], off nt
	global_load_dword v49, v[4:5], off nt
	global_load_dword v48, v[6:7], off nt
	global_load_dword v47, v[44:45], off nt
	global_load_dword v46, v[60:61], off nt
	s_nop 0
	global_load_dword v45, v[62:63], off nt
	global_load_dword v44, v[66:67], off nt
	global_load_dword v52, v[86:87], off nt
	v_add_co_u32_e32 v2, vcc, s93, v0
	s_nop 1
	v_addc_co_u32_e32 v3, vcc, 0, v1, vcc
	v_add_co_u32_e32 v4, vcc, s94, v0
	s_nop 1
	v_addc_co_u32_e32 v5, vcc, 0, v1, vcc
	v_add_co_u32_e32 v6, vcc, s95, v0
	s_nop 1
	v_addc_co_u32_e32 v7, vcc, 0, v1, vcc
	v_add_co_u32_e32 v60, vcc, s96, v0
	s_nop 1
	v_addc_co_u32_e32 v61, vcc, 0, v1, vcc
	v_add_co_u32_e32 v86, vcc, 0x4b4000, v0
	s_nop 1
	v_addc_co_u32_e32 v87, vcc, 0, v1, vcc
	v_add_co_u32_e32 v88, vcc, 0x4df000, v0
	s_nop 1
	v_addc_co_u32_e32 v89, vcc, 0, v1, vcc
	v_add_co_u32_e32 v90, vcc, 0x50a000, v0
	s_nop 1
	v_addc_co_u32_e32 v91, vcc, 0, v1, vcc
	v_add_co_u32_e32 v0, vcc, 0x535000, v0
	s_nop 1
	v_addc_co_u32_e32 v1, vcc, 0, v1, vcc
	global_load_dword v67, v[2:3], off nt
	global_load_dword v66, v[4:5], off nt
	global_load_dword v65, v[6:7], off nt
	global_load_dword v63, v[60:61], off nt
	global_load_dword v62, v[86:87], off nt
	s_nop 0
	global_load_dword v61, v[88:89], off nt
	global_load_dword v60, v[90:91], off nt
	global_load_dword v68, v[0:1], off nt

.LBB0_101:
	s_cmpk_gt_i32 s4, 0x55ff
	s_cbranch_scc1 .LBB0_106
	v_readlane_b32 s2, v250, 2
	v_readlane_b32 s3, v250, 3
	v_readlane_b32 s8, v251, 5
	s_lshl_b64 s[2:3], s[2:3], 2
	v_readlane_b32 s10, v251, 7
	v_add_u32_e32 v0, s95, v9
	v_readlane_b32 s11, v251, 8
	s_add_u32 s2, s10, s2
	v_ashrrev_i32_e32 v1, 31, v0
	s_addc_u32 s3, s11, s3
	v_lshlrev_b64 v[0:1], 14, v[0:1]
	v_lshl_add_u64 v[2:3], s[2:3], 0, v[0:1]
	v_mov_b32_e32 v1, 0
	v_lshlrev_b32_e32 v0, 2, v8
	v_lshl_add_u64 v[2:3], v[2:3], 0, v[0:1]
	s_mov_b32 s8, 0x8000
	v_readlane_b32 s9, v251, 6
	v_add_co_u32_e32 v4, vcc, s8, v2
	s_mov_b32 s9, 0x10000
	s_nop 0
	v_addc_co_u32_e32 v5, vcc, 0, v3, vcc
	v_readlane_b32 s12, v251, 9
	v_add_co_u32_e32 v12, vcc, s9, v2
	s_mov_b32 s12, 0x18000
	s_nop 0
	v_addc_co_u32_e32 v13, vcc, 0, v3, vcc
	v_readlane_b32 s13, v251, 10
	v_add_co_u32_e32 v14, vcc, s12, v2
	s_mov_b32 s13, 0x20000
	s_nop 0
	v_addc_co_u32_e32 v15, vcc, 0, v3, vcc
	v_add_co_u32_e32 v16, vcc, s13, v2
	s_mov_b32 s35, 0x28000
	s_nop 0
	v_addc_co_u32_e32 v17, vcc, 0, v3, vcc
	v_add_co_u32_e32 v22, vcc, s35, v2
	s_mov_b32 s44, 0x30000
	s_nop 0
	v_addc_co_u32_e32 v23, vcc, 0, v3, vcc
	v_add_co_u32_e32 v24, vcc, s44, v2
	s_mov_b32 s45, 0x38000
	s_nop 0
	v_addc_co_u32_e32 v25, vcc, 0, v3, vcc
	v_add_co_u32_e32 v26, vcc, s45, v2
	s_mov_b32 s46, 0x40000
	s_nop 0
	v_addc_co_u32_e32 v27, vcc, 0, v3, vcc
	global_load_dword v7, v[2:3], off nt
	global_load_dword v10, v[4:5], off nt
	global_load_dword v11, v[12:13], off nt
	s_nop 0
	global_load_dword v12, v[14:15], off nt
	global_load_dword v13, v[16:17], off nt
	s_nop 0
	global_load_dword v14, v[22:23], off nt
	global_load_dword v15, v[24:25], off nt
	global_load_dword v16, v[26:27], off nt
	v_add_co_u32_e32 v4, vcc, s46, v2
	s_mov_b32 s47, 0x48000
	s_nop 0
	v_addc_co_u32_e32 v5, vcc, 0, v3, vcc
	v_add_co_u32_e32 v22, vcc, s47, v2
	s_mov_b32 s48, 0x50000
	s_nop 0
	v_addc_co_u32_e32 v23, vcc, 0, v3, vcc
	v_add_co_u32_e32 v24, vcc, s48, v2
	s_mov_b32 s49, 0x58000
	s_nop 0
	v_addc_co_u32_e32 v25, vcc, 0, v3, vcc
	v_add_co_u32_e32 v26, vcc, s49, v2
	s_mov_b32 s59, 0x60000
	s_nop 0
	v_addc_co_u32_e32 v27, vcc, 0, v3, vcc
	v_add_co_u32_e32 v28, vcc, s59, v2
	s_mov_b32 s68, 0x68000
	s_nop 0
	v_addc_co_u32_e32 v29, vcc, 0, v3, vcc
	v_add_co_u32_e32 v30, vcc, s68, v2
	s_mov_b32 s69, 0x70000
	s_nop 0
	v_addc_co_u32_e32 v31, vcc, 0, v3, vcc
	v_add_co_u32_e32 v32, vcc, s69, v2
	s_mov_b32 s70, 0x78000
	s_nop 0
	v_addc_co_u32_e32 v33, vcc, 0, v3, vcc
	v_add_co_u32_e32 v34, vcc, s70, v2
	s_mov_b32 s71, 0x80000
	s_nop 0
	v_addc_co_u32_e32 v35, vcc, 0, v3, vcc
	global_load_dword v17, v[4:5], off nt
	global_load_dword v19, v[22:23], off nt
	s_nop 0
	global_load_dword v22, v[24:25], off nt
	global_load_dword v23, v[26:27], off nt
	s_nop 0
	global_load_dword v24, v[28:29], off nt
	global_load_dword v25, v[30:31], off nt
	global_load_dword v26, v[32:33], off nt
	s_nop 0
	global_load_dword v35, v[34:35], off nt
	v_add_co_u32_e32 v4, vcc, s71, v2
	s_mov_b32 s72, 0x88000
	s_nop 0
	v_addc_co_u32_e32 v5, vcc, 0, v3, vcc
	v_add_co_u32_e32 v28, vcc, s72, v2
	s_mov_b32 s73, 0x90000
	s_nop 0
	v_addc_co_u32_e32 v29, vcc, 0, v3, vcc
	v_add_co_u32_e32 v30, vcc, s73, v2
	s_mov_b32 s74, 0x98000
	s_nop 0
	v_addc_co_u32_e32 v31, vcc, 0, v3, vcc
	v_add_co_u32_e32 v32, vcc, s74, v2
	s_mov_b32 s75, 0xa0000
	s_nop 0
	v_addc_co_u32_e32 v33, vcc, 0, v3, vcc
	v_add_co_u32_e32 v36, vcc, s75, v2
	s_mov_b32 s76, 0xa8000
	s_nop 0
	v_addc_co_u32_e32 v37, vcc, 0, v3, vcc
	v_add_co_u32_e32 v38, vcc, s76, v2
	s_mov_b32 s77, 0xb0000
	s_nop 0
	v_addc_co_u32_e32 v39, vcc, 0, v3, vcc
	v_add_co_u32_e32 v40, vcc, s77, v2
	s_mov_b32 s78, 0xb8000
	s_nop 0
	v_addc_co_u32_e32 v41, vcc, 0, v3, vcc
	v_add_co_u32_e32 v42, vcc, s78, v2
	s_mov_b32 s79, 0xc0000
	s_nop 0
	v_addc_co_u32_e32 v43, vcc, 0, v3, vcc
	global_load_dword v44, v[4:5], off nt
	global_load_dword v45, v[28:29], off nt
	global_load_dword v46, v[30:31], off nt
	global_load_dword v47, v[32:33], off nt
	global_load_dword v48, v[36:37], off nt
	global_load_dword v49, v[38:39], off nt
	global_load_dword v50, v[40:41], off nt
	global_load_dword v51, v[42:43], off nt
	v_add_co_u32_e32 v4, vcc, s79, v2
	s_mov_b32 s80, 0xc8000
	s_nop 0
	v_addc_co_u32_e32 v5, vcc, 0, v3, vcc
	v_add_co_u32_e32 v28, vcc, s80, v2
	s_mov_b32 s81, 0xd0000
	s_nop 0
	v_addc_co_u32_e32 v29, vcc, 0, v3, vcc
	v_add_co_u32_e32 v30, vcc, s81, v2
	s_mov_b32 s82, 0xd8000
	s_nop 0
	v_addc_co_u32_e32 v31, vcc, 0, v3, vcc
	v_add_co_u32_e32 v32, vcc, s82, v2
	s_mov_b32 s2, 0xe0000
	s_nop 0
	v_addc_co_u32_e32 v33, vcc, 0, v3, vcc
	v_add_co_u32_e32 v36, vcc, s2, v2
	s_mov_b32 s2, 0xe8000
	s_nop 0
	v_addc_co_u32_e32 v37, vcc, 0, v3, vcc
	v_add_co_u32_e32 v38, vcc, s2, v2
	s_mov_b32 s2, 0xf0000
	s_nop 0
	v_addc_co_u32_e32 v39, vcc, 0, v3, vcc
	v_add_co_u32_e32 v40, vcc, s2, v2
	s_mov_b32 s2, 0xf8000
	s_nop 0
	v_addc_co_u32_e32 v41, vcc, 0, v3, vcc
	v_add_co_u32_e32 v2, vcc, s2, v2
	s_movk_i32 s2, 0x84
	s_nop 0
	v_addc_co_u32_e32 v3, vcc, 0, v3, vcc
	global_load_dword v60, v[4:5], off nt
	global_load_dword v61, v[28:29], off nt
	global_load_dword v62, v[30:31], off nt
	global_load_dword v63, v[32:33], off nt
	global_load_dword v65, v[36:37], off nt
	global_load_dword v66, v[38:39], off nt
	global_load_dword v67, v[40:41], off nt
	global_load_dword v68, v[2:3], off nt
	v_add_u32_e32 v6, s7, v0
	v_mul_lo_u32 v27, v9, s2
	v_and_b32_e32 v0, 56, v21
	v_readlane_b32 s2, v251, 56
	v_mul_u32_u24_e32 v4, 0x84, v0
	v_lshlrev_b32_e32 v0, 1, v0
	v_readlane_b32 s3, v251, 57
	v_add_u32_e32 v6, v6, v27
	s_movk_i32 s86, 0x7fff
	v_lshl_add_u64 v[2:3], s[2:3], 0, v[0:1]
	v_readlane_b32 s2, v251, 42
	s_lshl_b32 s83, s2, 5
	v_readlane_b32 s2, v251, 4
	v_readlane_b32 s3, v251, 3
	v_lshlrev_b32_e32 v0, 2, v20
	s_lshl_b32 s2, s2, 8
	s_lshl_b32 s84, s3, 8
	v_add3_u32 v4, s7, v4, v0
	v_add_u32_e32 v5, s2, v20
	s_add_i32 s85, s2, s84
	v_lshlrev_b32_e32 v0, 2, v8
	s_mov_b32 s87, 0xffff0000
	s_movk_i32 s88, 0x5600
	v_mov_b32_e32 v76, v1
	v_mov_b32_e32 v69, v1
	v_mov_b32_e32 v70, v1
	v_mov_b32_e32 v71, v1
	v_mov_b32_e32 v72, v1
	v_mov_b32_e32 v73, v1
	v_mov_b32_e32 v74, v1
	v_mov_b32_e32 v75, v1
	v_mov_b32_e32 v59, v1
	v_mov_b32_e32 v52, v1
	v_mov_b32_e32 v53, v1
	v_mov_b32_e32 v54, v1
	v_mov_b32_e32 v55, v1
	v_mov_b32_e32 v56, v1
	v_mov_b32_e32 v57, v1
	v_mov_b32_e32 v58, v1
	v_mov_b32_e32 v43, v1
	v_mov_b32_e32 v36, v1
	v_mov_b32_e32 v37, v1
	v_mov_b32_e32 v38, v1
	v_mov_b32_e32 v39, v1
	v_mov_b32_e32 v40, v1
	v_mov_b32_e32 v41, v1
	v_mov_b32_e32 v42, v1
	v_mov_b32_e32 v34, v1
	v_mov_b32_e32 v27, v1
	v_mov_b32_e32 v28, v1
	v_mov_b32_e32 v29, v1
	v_mov_b32_e32 v30, v1
	v_mov_b32_e32 v31, v1
	v_mov_b32_e32 v32, v1
	v_mov_b32_e32 v33, v1
	s_mov_b32 s92, s4
	v_readlane_b32 s14, v251, 11
	v_readlane_b32 s15, v251, 12
	v_readlane_b32 s16, v251, 13
	v_readlane_b32 s17, v251, 14
	v_readlane_b32 s18, v251, 15
	v_readlane_b32 s19, v251, 16
	v_readlane_b32 s20, v251, 17
	v_readlane_b32 s21, v251, 18
	v_readlane_b32 s22, v251, 19
	v_readlane_b32 s23, v251, 20
	s_branch .LBB0_104

.LBB0_104:
	s_add_i32 s89, s92, s6
	s_cmpk_gt_i32 s89, 0x55ff
	s_cselect_b64 s[10:11], -1, 0
	s_and_b64 vcc, exec, s[10:11]
	s_cbranch_vccnz .LBB0_103
	s_ashr_i32 s2, s89, 31
	s_lshr_b32 s2, s2, 25
	s_add_i32 s2, s89, s2
	s_ashr_i32 s3, s2, 7
	v_lshl_add_u32 v28, s3, 6, v9
	s_add_i32 s2, s83, s85
	s_lshl_b32 s14, s3, 12
	v_ashrrev_i32_e32 v29, 31, v28
	v_readlane_b32 s16, v251, 5
	s_sub_i32 s2, s2, s14
	v_lshlrev_b64 v[28:29], 14, v[28:29]
	v_readlane_b32 s18, v251, 7
	v_readlane_b32 s19, v251, 8
	s_ashr_i32 s3, s2, 31
	v_readlane_b32 s17, v251, 6
	v_lshl_add_u64 v[28:29], s[18:19], 0, v[28:29]
	v_lshl_add_u64 v[28:29], s[2:3], 2, v[28:29]
	v_lshl_add_u64 v[70:71], v[28:29], 0, v[0:1]
	v_add_co_u32_e32 v28, vcc, s8, v70
	v_readlane_b32 s20, v251, 9
	s_nop 0
	v_addc_co_u32_e32 v29, vcc, 0, v71, vcc
	v_add_co_u32_e32 v30, vcc, s9, v70
	v_readlane_b32 s21, v251, 10
	s_nop 0
	v_addc_co_u32_e32 v31, vcc, 0, v71, vcc
	v_add_co_u32_e32 v36, vcc, s12, v70
	v_readlane_b32 s22, v251, 11
	s_nop 0
	v_addc_co_u32_e32 v37, vcc, 0, v71, vcc
	v_add_co_u32_e32 v38, vcc, s13, v70
	v_readlane_b32 s23, v251, 12
	s_nop 0
	v_addc_co_u32_e32 v39, vcc, 0, v71, vcc
	v_add_co_u32_e32 v40, vcc, s35, v70
	v_readlane_b32 s24, v251, 13
	s_nop 0
	v_addc_co_u32_e32 v41, vcc, 0, v71, vcc
	v_add_co_u32_e32 v42, vcc, s44, v70
	v_readlane_b32 s25, v251, 14
	s_nop 0
	v_addc_co_u32_e32 v43, vcc, 0, v71, vcc
	v_add_co_u32_e32 v52, vcc, s45, v70
	v_readlane_b32 s26, v251, 15
	s_nop 0
	v_addc_co_u32_e32 v53, vcc, 0, v71, vcc
	global_load_dword v33, v[70:71], off nt
	global_load_dword v32, v[28:29], off nt
	s_nop 0
	global_load_dword v31, v[30:31], off nt
	s_nop 0
	global_load_dword v30, v[36:37], off nt
	global_load_dword v29, v[38:39], off nt
	global_load_dword v28, v[40:41], off nt
	global_load_dword v27, v[42:43], off nt
	global_load_dword v34, v[52:53], off nt
	v_add_co_u32_e32 v36, vcc, s46, v70
	v_readlane_b32 s27, v251, 16
	s_nop 0
	v_addc_co_u32_e32 v37, vcc, 0, v71, vcc
	v_add_co_u32_e32 v38, vcc, s47, v70
	v_readlane_b32 s28, v251, 17
	s_nop 0
	v_addc_co_u32_e32 v39, vcc, 0, v71, vcc
	v_add_co_u32_e32 v52, vcc, s48, v70
	v_readlane_b32 s29, v251, 18
	s_nop 0
	v_addc_co_u32_e32 v53, vcc, 0, v71, vcc
	v_add_co_u32_e32 v54, vcc, s49, v70
	v_readlane_b32 s30, v251, 19
	s_nop 0
	v_addc_co_u32_e32 v55, vcc, 0, v71, vcc
	v_add_co_u32_e32 v56, vcc, s59, v70
	v_readlane_b32 s31, v251, 20
	s_nop 0
	v_addc_co_u32_e32 v57, vcc, 0, v71, vcc
	v_add_co_u32_e32 v58, vcc, s68, v70
	s_nop 1
	v_addc_co_u32_e32 v59, vcc, 0, v71, vcc
	v_add_co_u32_e32 v72, vcc, s69, v70
	s_nop 1
	v_addc_co_u32_e32 v73, vcc, 0, v71, vcc
	v_add_co_u32_e32 v74, vcc, s70, v70
	s_nop 1
	v_addc_co_u32_e32 v75, vcc, 0, v71, vcc
	global_load_dword v42, v[36:37], off nt
	global_load_dword v41, v[38:39], off nt
	global_load_dword v40, v[52:53], off nt
	s_nop 0
	global_load_dword v39, v[54:55], off nt
	global_load_dword v38, v[56:57], off nt
	global_load_dword v37, v[58:59], off nt
	global_load_dword v36, v[72:73], off nt
	global_load_dword v43, v[74:75], off nt
	v_add_co_u32_e32 v52, vcc, s71, v70
	s_nop 1
	v_addc_co_u32_e32 v53, vcc, 0, v71, vcc
	v_add_co_u32_e32 v54, vcc, s72, v70
	s_nop 1
	v_addc_co_u32_e32 v55, vcc, 0, v71, vcc
	v_add_co_u32_e32 v72, vcc, s73, v70
	s_nop 1
	v_addc_co_u32_e32 v73, vcc, 0, v71, vcc
	v_add_co_u32_e32 v74, vcc, s74, v70
	s_nop 1
	v_addc_co_u32_e32 v75, vcc, 0, v71, vcc
	v_add_co_u32_e32 v76, vcc, s75, v70
	s_nop 1
	v_addc_co_u32_e32 v77, vcc, 0, v71, vcc
	v_add_co_u32_e32 v78, vcc, s76, v70
	s_nop 1
	v_addc_co_u32_e32 v79, vcc, 0, v71, vcc
	v_add_co_u32_e32 v80, vcc, s77, v70
	s_nop 1
	v_addc_co_u32_e32 v81, vcc, 0, v71, vcc
	v_add_co_u32_e32 v82, vcc, s78, v70
	s_nop 1
	v_addc_co_u32_e32 v83, vcc, 0, v71, vcc
	global_load_dword v58, v[52:53], off nt
	global_load_dword v57, v[54:55], off nt
	global_load_dword v56, v[72:73], off nt
	s_nop 0
	global_load_dword v55, v[74:75], off nt
	global_load_dword v54, v[76:77], off nt
	global_load_dword v53, v[78:79], off nt
	global_load_dword v52, v[80:81], off nt
	global_load_dword v59, v[82:83], off nt
	v_add_co_u32_e32 v72, vcc, s79, v70
	s_nop 1
	v_addc_co_u32_e32 v73, vcc, 0, v71, vcc
	v_add_co_u32_e32 v76, vcc, s80, v70
	s_nop 1
	v_addc_co_u32_e32 v77, vcc, 0, v71, vcc
	v_add_co_u32_e32 v78, vcc, s81, v70
	s_nop 1
	v_addc_co_u32_e32 v79, vcc, 0, v71, vcc
	v_add_co_u32_e32 v80, vcc, s82, v70
	s_nop 1
	v_addc_co_u32_e32 v81, vcc, 0, v71, vcc
	v_add_co_u32_e32 v82, vcc, 0xe0000, v70
	s_nop 1
	v_addc_co_u32_e32 v83, vcc, 0, v71, vcc
	v_add_co_u32_e32 v84, vcc, 0xe8000, v70
	s_nop 1
	v_addc_co_u32_e32 v85, vcc, 0, v71, vcc
	v_add_co_u32_e32 v86, vcc, 0xf0000, v70
	s_nop 1
	v_addc_co_u32_e32 v87, vcc, 0, v71, vcc
	v_add_co_u32_e32 v88, vcc, 0xf8000, v70
	s_nop 1
	v_addc_co_u32_e32 v89, vcc, 0, v71, vcc
	global_load_dword v75, v[72:73], off nt
	global_load_dword v74, v[76:77], off nt
	s_nop 0
	global_load_dword v73, v[78:79], off nt
	global_load_dword v72, v[80:81], off nt
	global_load_dword v71, v[82:83], off nt
	global_load_dword v70, v[84:85], off nt
	global_load_dword v69, v[86:87], off nt
	global_load_dword v76, v[88:89], off nt
	s_branch .LBB0_103
.LBB0_106:
	v_readlane_b32 s2, v250, 0
	v_readlane_b32 s3, v250, 1
	s_andn2_b64 vcc, exec, s[2:3]
	s_cbranch_vccnz .LBB0_114
	v_readlane_b32 s2, v250, 2
	v_readlane_b32 s3, v250, 3
	v_readlane_b32 s8, v251, 5
	s_lshl_b64 s[2:3], s[2:3], 2
	v_readlane_b32 s14, v251, 11
	v_add_u32_e32 v0, s95, v9
	v_readlane_b32 s15, v251, 12
	s_add_u32 s2, s14, s2
	v_ashrrev_i32_e32 v1, 31, v0
	s_addc_u32 s3, s15, s3
	v_lshlrev_b64 v[0:1], 14, v[0:1]
	v_readlane_b32 s18, v251, 15
	v_lshl_add_u64 v[0:1], s[2:3], 0, v[0:1]
	v_mov_b32_e32 v11, 0
	v_lshlrev_b32_e32 v10, 2, v8
	v_lshl_add_u64 v[0:1], v[0:1], 0, v[10:11]
	s_mov_b32 s18, 0x8000
	v_readlane_b32 s19, v251, 16
	v_add_co_u32_e32 v2, vcc, s18, v0
	s_mov_b32 s19, 0x10000
	s_nop 0
	v_addc_co_u32_e32 v3, vcc, 0, v1, vcc
	v_add_co_u32_e32 v4, vcc, s19, v0
	s_mov_b32 s14, 0x18000
	s_nop 0
	v_addc_co_u32_e32 v5, vcc, 0, v1, vcc
	v_add_co_u32_e32 v6, vcc, s14, v0
	s_mov_b32 s15, 0x20000
	s_nop 0
	v_addc_co_u32_e32 v7, vcc, 0, v1, vcc
	v_readlane_b32 s16, v251, 13
	v_add_co_u32_e32 v12, vcc, s15, v0
	s_mov_b32 s16, 0x28000
	s_nop 0
	v_addc_co_u32_e32 v13, vcc, 0, v1, vcc
	v_readlane_b32 s17, v251, 14
	v_add_co_u32_e32 v14, vcc, s16, v0
	s_mov_b32 s17, 0x30000
	s_nop 0
	v_addc_co_u32_e32 v15, vcc, 0, v1, vcc
	v_readlane_b32 s22, v251, 19
	v_add_co_u32_e32 v16, vcc, s17, v0
	s_mov_b32 s22, 0x38000
	s_nop 0
	v_addc_co_u32_e32 v17, vcc, 0, v1, vcc
	v_readlane_b32 s23, v251, 20
	v_add_co_u32_e32 v22, vcc, s22, v0
	s_mov_b32 s23, 0x40000
	s_nop 0
	v_addc_co_u32_e32 v23, vcc, 0, v1, vcc
	global_load_dword v19, v[0:1], off nt
	global_load_dword v49, v[2:3], off nt
	global_load_dword v50, v[4:5], off nt
	global_load_dword v51, v[6:7], off nt
	global_load_dword v52, v[12:13], off nt
	global_load_dword v53, v[14:15], off nt
	global_load_dword v54, v[16:17], off nt
	global_load_dword v55, v[22:23], off nt
	v_add_co_u32_e32 v2, vcc, s23, v0
	s_mov_b32 s59, 0x48000
	s_nop 0
	v_addc_co_u32_e32 v3, vcc, 0, v1, vcc
	v_add_co_u32_e32 v4, vcc, s59, v0
	s_mov_b32 s68, 0x50000
	s_nop 0
	v_addc_co_u32_e32 v5, vcc, 0, v1, vcc
	v_add_co_u32_e32 v6, vcc, s68, v0
	s_mov_b32 s69, 0x58000
	s_nop 0
	v_addc_co_u32_e32 v7, vcc, 0, v1, vcc
	v_add_co_u32_e32 v12, vcc, s69, v0
	s_mov_b32 s70, 0x60000
	s_nop 0
	v_addc_co_u32_e32 v13, vcc, 0, v1, vcc
	v_add_co_u32_e32 v14, vcc, s70, v0
	s_mov_b32 s71, 0x68000
	s_nop 0
	v_addc_co_u32_e32 v15, vcc, 0, v1, vcc
	v_add_co_u32_e32 v16, vcc, s71, v0
	s_mov_b32 s72, 0x70000
	s_nop 0
	v_addc_co_u32_e32 v17, vcc, 0, v1, vcc
	v_add_co_u32_e32 v22, vcc, s72, v0
	s_mov_b32 s73, 0x78000
	s_nop 0
	v_addc_co_u32_e32 v23, vcc, 0, v1, vcc
	v_add_co_u32_e32 v24, vcc, s73, v0
	s_mov_b32 s74, 0x80000
	s_nop 0
	v_addc_co_u32_e32 v25, vcc, 0, v1, vcc
	global_load_dword v65, v[2:3], off nt
	global_load_dword v66, v[4:5], off nt
	global_load_dword v67, v[6:7], off nt
	global_load_dword v68, v[12:13], off nt
	global_load_dword v69, v[14:15], off nt
	global_load_dword v70, v[16:17], off nt
	global_load_dword v71, v[22:23], off nt
	global_load_dword v72, v[24:25], off nt
	v_add_co_u32_e32 v2, vcc, s74, v0
	s_mov_b32 s75, 0x88000
	s_nop 0
	v_addc_co_u32_e32 v3, vcc, 0, v1, vcc
	v_add_co_u32_e32 v4, vcc, s75, v0
	s_mov_b32 s76, 0x90000
	s_nop 0
	v_addc_co_u32_e32 v5, vcc, 0, v1, vcc
	v_add_co_u32_e32 v6, vcc, s76, v0
	s_mov_b32 s77, 0x98000
	s_nop 0
	v_addc_co_u32_e32 v7, vcc, 0, v1, vcc
	v_add_co_u32_e32 v12, vcc, s77, v0
	s_mov_b32 s78, 0xa0000
	s_nop 0
	v_addc_co_u32_e32 v13, vcc, 0, v1, vcc
	v_add_co_u32_e32 v14, vcc, s78, v0
	s_mov_b32 s79, 0xa8000
	s_nop 0
	v_addc_co_u32_e32 v15, vcc, 0, v1, vcc
	v_add_co_u32_e32 v16, vcc, s79, v0
	s_mov_b32 s80, 0xb0000
	s_nop 0
	v_addc_co_u32_e32 v17, vcc, 0, v1, vcc
	v_add_co_u32_e32 v22, vcc, s80, v0
	s_mov_b32 s81, 0xb8000
	s_nop 0
	v_addc_co_u32_e32 v23, vcc, 0, v1, vcc
	v_add_co_u32_e32 v24, vcc, s81, v0
	s_mov_b32 s35, 0xc0000
	s_nop 0
	v_addc_co_u32_e32 v25, vcc, 0, v1, vcc
	global_load_dword v73, v[2:3], off nt
	global_load_dword v74, v[4:5], off nt
	global_load_dword v75, v[6:7], off nt
	global_load_dword v76, v[12:13], off nt
	global_load_dword v77, v[14:15], off nt
	global_load_dword v78, v[16:17], off nt
	global_load_dword v79, v[22:23], off nt
	global_load_dword v80, v[24:25], off nt
	v_add_co_u32_e32 v2, vcc, s35, v0
	s_mov_b32 s82, 0xc8000
	s_nop 0
	v_addc_co_u32_e32 v3, vcc, 0, v1, vcc
	v_add_co_u32_e32 v4, vcc, s82, v0
	s_mov_b32 s83, 0xd0000
	s_nop 0
	v_addc_co_u32_e32 v5, vcc, 0, v1, vcc
	v_add_co_u32_e32 v6, vcc, s83, v0
	s_mov_b32 s84, 0xd8000
	s_nop 0
	v_addc_co_u32_e32 v7, vcc, 0, v1, vcc
	v_add_co_u32_e32 v12, vcc, s84, v0
	s_mov_b32 s2, 0xe0000
	s_nop 0
	v_addc_co_u32_e32 v13, vcc, 0, v1, vcc
	v_add_co_u32_e32 v14, vcc, s2, v0
	s_mov_b32 s2, 0xe8000
	s_nop 0
	v_addc_co_u32_e32 v15, vcc, 0, v1, vcc
	v_add_co_u32_e32 v16, vcc, s2, v0
	s_mov_b32 s2, 0xf0000
	s_nop 0
	v_addc_co_u32_e32 v17, vcc, 0, v1, vcc
	v_add_co_u32_e32 v22, vcc, s2, v0
	s_mov_b32 s2, 0xf8000
	s_nop 0
	v_addc_co_u32_e32 v23, vcc, 0, v1, vcc
	v_add_co_u32_e32 v0, vcc, s2, v0
	s_movk_i32 s2, 0x84
	s_nop 0
	v_addc_co_u32_e32 v1, vcc, 0, v1, vcc
	global_load_dword v81, v[2:3], off nt
	global_load_dword v82, v[4:5], off nt
	global_load_dword v83, v[6:7], off nt
	global_load_dword v84, v[12:13], off nt
	global_load_dword v85, v[14:15], off nt
	global_load_dword v86, v[16:17], off nt
	global_load_dword v87, v[22:23], off nt
	global_load_dword v88, v[0:1], off nt
	v_mul_lo_u32 v3, v9, s2
	v_readlane_b32 s2, v251, 58
	v_readlane_b32 s12, v251, 9
	v_readlane_b32 s13, v251, 10
	v_add_u32_e32 v2, s7, v10
	v_lshlrev_b32_e32 v10, 3, v18
	v_readlane_b32 s3, v251, 59
	v_readlane_b32 s9, v251, 6
	v_readlane_b32 s20, v251, 17
	s_cmp_lg_u64 s[12:13], 0
	v_lshl_add_u64 v[14:15], s[2:3], 0, v[10:11]
	v_readlane_b32 s2, v251, 42
	v_readlane_b32 s21, v251, 18
	s_cselect_b64 s[8:9], -1, 0
	v_lshlrev_b32_e32 v0, 5, v18
	v_mov_b32_e32 v1, v11
	s_lshl_b32 s20, s2, 5
	v_readlane_b32 s2, v251, 4
	v_readlane_b32 s3, v251, 3
	v_lshl_add_u64 v[12:13], s[12:13], 0, v[0:1]
	v_mul_u32_u24_e32 v0, 0x420, v18
	v_lshlrev_b32_e32 v1, 2, v20
	s_lshl_b32 s2, s2, 8
	s_lshl_b32 s21, s3, 8
	v_add3_u32 v22, s7, v0, v1
	v_add_u32_e32 v23, s2, v20
	s_add_i32 s85, s2, s21
	v_lshlrev_b32_e32 v10, 2, v8
	v_add_u32_e32 v24, v2, v3
	s_mov_b32 s86, 0x42fe0000
	s_mov_b32 s87, 0x40c0c00
	v_mov_b32_e32 v63, v11
	v_mov_b32_e32 v56, v11
	v_mov_b32_e32 v57, v11
	v_mov_b32_e32 v58, v11
	v_mov_b32_e32 v59, v11
	v_mov_b32_e32 v60, v11
	v_mov_b32_e32 v61, v11
	v_mov_b32_e32 v62, v11
	v_mov_b32_e32 v48, v11
	v_mov_b32_e32 v41, v11
	v_mov_b32_e32 v42, v11
	v_mov_b32_e32 v43, v11
	v_mov_b32_e32 v44, v11
	v_mov_b32_e32 v45, v11
	v_mov_b32_e32 v46, v11
	v_mov_b32_e32 v47, v11
	v_mov_b32_e32 v40, v11
	v_mov_b32_e32 v33, v11
	v_mov_b32_e32 v34, v11
	v_mov_b32_e32 v35, v11
	v_mov_b32_e32 v36, v11
	v_mov_b32_e32 v37, v11
	v_mov_b32_e32 v38, v11
	v_mov_b32_e32 v39, v11
	v_mov_b32_e32 v32, v11
	v_mov_b32_e32 v25, v11
	v_mov_b32_e32 v26, v11
	v_mov_b32_e32 v27, v11
	v_mov_b32_e32 v28, v11
	v_mov_b32_e32 v29, v11
	v_mov_b32_e32 v30, v11
	v_mov_b32_e32 v31, v11
	s_mov_b32 s12, s4
	v_readlane_b32 s10, v251, 7
	v_readlane_b32 s11, v251, 8
	s_branch .LBB0_111
.LBB0_108:
	s_ashr_i32 s2, s12, 31
	s_lshr_b32 s2, s2, 25
	s_add_i32 s2, s12, s2
	s_ashr_i32 s2, s2, 7
	v_add_u32_e32 v0, s20, v23
	s_lshl_b32 s3, s2, 12
	v_subrev_u32_e32 v16, s3, v0
	v_readlane_b32 s12, v251, 43
	v_ashrrev_i32_e32 v17, 31, v16
	v_readlane_b32 s13, v251, 44
	s_andn2_b64 vcc, exec, s[8:9]
	s_nop 0
	v_lshl_add_u64 v[0:1], v[16:17], 2, s[12:13]
	global_load_dword v92, v[0:1], off nt
	global_load_dword v91, v[0:1], off offset:32 nt
	global_load_dword v90, v[0:1], off offset:64 nt
	global_load_dword v89, v[0:1], off offset:96 nt
	s_lshl_b32 s12, s2, 6
	s_ashr_i32 s13, s12, 31
	s_cbranch_vccnz .LBB0_113
	v_lshl_add_u64 v[4:5], s[12:13], 2, v[12:13]
	global_load_dwordx4 v[0:3], v[4:5], off offset:16 nt
	s_nop 0
	global_load_dwordx4 v[4:7], v[4:5], off nt

.LBB0_111:
	s_add_i32 s88, s12, s6
	s_cmpk_gt_i32 s88, 0x1fff
	s_cselect_b64 s[10:11], -1, 0
	s_and_b64 vcc, exec, s[10:11]
	s_cbranch_vccnz .LBB0_108
	s_ashr_i32 s2, s88, 31
	s_lshr_b32 s2, s2, 25
	s_add_i32 s2, s88, s2
	s_ashr_i32 s3, s2, 7
	v_lshl_add_u32 v0, s3, 6, v9
	s_add_i32 s2, s20, s85
	s_lshl_b32 s13, s3, 12
	v_ashrrev_i32_e32 v1, 31, v0
	v_readlane_b32 s36, v251, 5
	s_sub_i32 s2, s2, s13
	v_lshlrev_b64 v[0:1], 14, v[0:1]
	v_readlane_b32 s42, v251, 11
	v_readlane_b32 s43, v251, 12
	s_ashr_i32 s3, s2, 31
	v_readlane_b32 s37, v251, 6
	v_lshl_add_u64 v[0:1], s[42:43], 0, v[0:1]
	v_lshl_add_u64 v[0:1], s[2:3], 2, v[0:1]
	v_lshl_add_u64 v[0:1], v[0:1], 0, v[10:11]
	v_add_co_u32_e32 v2, vcc, s18, v0
	v_readlane_b32 s38, v251, 7
	s_nop 0
	v_addc_co_u32_e32 v3, vcc, 0, v1, vcc
	v_add_co_u32_e32 v4, vcc, s19, v0
	v_readlane_b32 s39, v251, 8
	s_nop 0
	v_addc_co_u32_e32 v5, vcc, 0, v1, vcc
	v_add_co_u32_e32 v6, vcc, s14, v0
	v_readlane_b32 s40, v251, 9
	s_nop 0
	v_addc_co_u32_e32 v7, vcc, 0, v1, vcc
	v_add_co_u32_e32 v16, vcc, s15, v0
	v_readlane_b32 s41, v251, 10
	s_nop 0
	v_addc_co_u32_e32 v17, vcc, 0, v1, vcc
	v_add_co_u32_e32 v32, vcc, s16, v0
	v_readlane_b32 s44, v251, 13
	s_nop 0
	v_addc_co_u32_e32 v33, vcc, 0, v1, vcc
	v_add_co_u32_e32 v34, vcc, s17, v0
	v_readlane_b32 s45, v251, 14
	s_nop 0
	v_addc_co_u32_e32 v35, vcc, 0, v1, vcc
	v_add_co_u32_e32 v36, vcc, s22, v0
	v_readlane_b32 s46, v251, 15
	s_nop 0
	v_addc_co_u32_e32 v37, vcc, 0, v1, vcc
	global_load_dword v31, v[0:1], off nt
	global_load_dword v30, v[2:3], off nt
	global_load_dword v29, v[4:5], off nt
	global_load_dword v28, v[6:7], off nt
	global_load_dword v27, v[16:17], off nt
	global_load_dword v26, v[32:33], off nt
	global_load_dword v25, v[34:35], off nt
	s_nop 0
	global_load_dword v32, v[36:37], off nt
	v_add_co_u32_e32 v2, vcc, s23, v0
	v_readlane_b32 s47, v251, 16
	s_nop 0
	v_addc_co_u32_e32 v3, vcc, 0, v1, vcc
	v_add_co_u32_e32 v4, vcc, s59, v0
	v_readlane_b32 s48, v251, 17
	s_nop 0
	v_addc_co_u32_e32 v5, vcc, 0, v1, vcc
	v_add_co_u32_e32 v6, vcc, s68, v0
	v_readlane_b32 s49, v251, 18
	s_nop 0
	v_addc_co_u32_e32 v7, vcc, 0, v1, vcc
	v_add_co_u32_e32 v16, vcc, s69, v0
	v_readlane_b32 s50, v251, 19
	s_nop 0
	v_addc_co_u32_e32 v17, vcc, 0, v1, vcc
	v_add_co_u32_e32 v34, vcc, s70, v0
	v_readlane_b32 s51, v251, 20
	s_nop 0
	v_addc_co_u32_e32 v35, vcc, 0, v1, vcc
	v_add_co_u32_e32 v40, vcc, s71, v0
	s_nop 1
	v_addc_co_u32_e32 v41, vcc, 0, v1, vcc
	v_add_co_u32_e32 v42, vcc, s72, v0
	s_nop 1
	v_addc_co_u32_e32 v43, vcc, 0, v1, vcc
	v_add_co_u32_e32 v44, vcc, s73, v0
	s_nop 1
	v_addc_co_u32_e32 v45, vcc, 0, v1, vcc
	global_load_dword v39, v[2:3], off nt
	global_load_dword v38, v[4:5], off nt
	global_load_dword v37, v[6:7], off nt
	global_load_dword v36, v[16:17], off nt
	s_nop 0
	global_load_dword v35, v[34:35], off nt
	s_nop 0
	global_load_dword v34, v[40:41], off nt
	global_load_dword v33, v[42:43], off nt
	s_nop 0
	global_load_dword v40, v[44:45], off nt
	v_add_co_u32_e32 v2, vcc, s74, v0
	s_nop 1
	v_addc_co_u32_e32 v3, vcc, 0, v1, vcc
	v_add_co_u32_e32 v4, vcc, s75, v0
	s_nop 1
	v_addc_co_u32_e32 v5, vcc, 0, v1, vcc
	v_add_co_u32_e32 v6, vcc, s76, v0
	s_nop 1
	v_addc_co_u32_e32 v7, vcc, 0, v1, vcc
	v_add_co_u32_e32 v16, vcc, s77, v0
	s_nop 1
	v_addc_co_u32_e32 v17, vcc, 0, v1, vcc
	v_add_co_u32_e32 v42, vcc, s78, v0
	s_nop 1
	v_addc_co_u32_e32 v43, vcc, 0, v1, vcc
	v_add_co_u32_e32 v56, vcc, s79, v0
	s_nop 1
	v_addc_co_u32_e32 v57, vcc, 0, v1, vcc
	v_add_co_u32_e32 v58, vcc, s80, v0
	s_nop 1
	v_addc_co_u32_e32 v59, vcc, 0, v1, vcc
	v_add_co_u32_e32 v60, vcc, s81, v0
	s_nop 1
	v_addc_co_u32_e32 v61, vcc, 0, v1, vcc
	global_load_dword v47, v[2:3], off nt
	global_load_dword v46, v[4:5], off nt
	global_load_dword v45, v[6:7], off nt
	global_load_dword v44, v[16:17], off nt
	s_nop 0
	global_load_dword v43, v[42:43], off nt
	s_nop 0
	global_load_dword v42, v[56:57], off nt
	global_load_dword v41, v[58:59], off nt
	global_load_dword v48, v[60:61], off nt
	v_add_co_u32_e32 v2, vcc, s35, v0
	s_nop 1
	v_addc_co_u32_e32 v3, vcc, 0, v1, vcc
	v_add_co_u32_e32 v4, vcc, s82, v0
	s_nop 1
	v_addc_co_u32_e32 v5, vcc, 0, v1, vcc
	v_add_co_u32_e32 v6, vcc, s83, v0
	s_nop 1
	v_addc_co_u32_e32 v7, vcc, 0, v1, vcc
	v_add_co_u32_e32 v16, vcc, s84, v0
	s_nop 1
	v_addc_co_u32_e32 v17, vcc, 0, v1, vcc
	v_add_co_u32_e32 v56, vcc, 0xe0000, v0
	s_nop 1
	v_addc_co_u32_e32 v57, vcc, 0, v1, vcc
	v_add_co_u32_e32 v90, vcc, 0xe8000, v0
	s_nop 1
	v_addc_co_u32_e32 v91, vcc, 0, v1, vcc
	v_add_co_u32_e32 v92, vcc, 0xf0000, v0
	s_nop 1
	v_addc_co_u32_e32 v93, vcc, 0, v1, vcc
	v_add_co_u32_e32 v0, vcc, 0xf8000, v0
	s_nop 1
	v_addc_co_u32_e32 v1, vcc, 0, v1, vcc
	global_load_dword v62, v[2:3], off nt
	global_load_dword v61, v[4:5], off nt
	global_load_dword v60, v[6:7], off nt
	global_load_dword v59, v[16:17], off nt
	global_load_dword v58, v[56:57], off nt
	s_nop 0
	global_load_dword v57, v[90:91], off nt
	global_load_dword v56, v[92:93], off nt
	global_load_dword v63, v[0:1], off nt
	s_branch .LBB0_108

.LBB0_114:
	v_readlane_b32 s96, v251, 48
	s_cmpk_gt_i32 s4, 0x1ff
	v_readlane_b32 s31, v251, 47
	v_readlane_b32 s97, v251, 49
	s_cbranch_scc1 .LBB0_120
	v_readlane_b32 s2, v250, 2
	v_readlane_b32 s3, v250, 3
	v_readlane_b32 s8, v251, 5
	s_lshl_b64 s[2:3], s[2:3], 2
	v_readlane_b32 s16, v251, 13
	v_add_u32_e32 v0, s95, v9
	v_readlane_b32 s17, v251, 14
	s_add_u32 s2, s16, s2
	v_ashrrev_i32_e32 v1, 31, v0
	s_addc_u32 s3, s17, s3
	v_lshlrev_b64 v[0:1], 14, v[0:1]
	v_lshl_add_u64 v[2:3], s[2:3], 0, v[0:1]
	v_mov_b32_e32 v1, 0
	v_lshlrev_b32_e32 v0, 2, v8
	v_lshl_add_u64 v[2:3], v[2:3], 0, v[0:1]
	s_mov_b32 s24, 0x8000
	v_add_co_u32_e32 v4, vcc, s24, v2
	s_mov_b32 s25, 0x10000
	s_nop 0
	v_addc_co_u32_e32 v5, vcc, 0, v3, vcc
	v_add_co_u32_e32 v12, vcc, s25, v2
	s_mov_b32 s26, 0x18000
	s_nop 0
	v_addc_co_u32_e32 v13, vcc, 0, v3, vcc
	v_add_co_u32_e32 v14, vcc, s26, v2
	s_mov_b32 s27, 0x20000
	s_nop 0
	v_addc_co_u32_e32 v15, vcc, 0, v3, vcc
	v_add_co_u32_e32 v16, vcc, s27, v2
	s_mov_b32 s28, 0x28000
	s_nop 0
	v_addc_co_u32_e32 v17, vcc, 0, v3, vcc
	v_add_co_u32_e32 v18, vcc, s28, v2
	s_mov_b32 s29, 0x30000
	s_nop 0
	v_addc_co_u32_e32 v19, vcc, 0, v3, vcc
	v_add_co_u32_e32 v22, vcc, s29, v2
	s_mov_b32 s30, 0x38000
	s_nop 0
	v_addc_co_u32_e32 v23, vcc, 0, v3, vcc
	v_add_co_u32_e32 v24, vcc, s30, v2
	s_mov_b32 s50, s31
	s_nop 0
	v_addc_co_u32_e32 v25, vcc, 0, v3, vcc
	s_mov_b32 s31, 0x40000
	global_load_dword v7, v[2:3], off nt
	global_load_dword v10, v[4:5], off nt
	global_load_dword v11, v[12:13], off nt
	s_nop 0
	global_load_dword v12, v[14:15], off nt
	global_load_dword v13, v[16:17], off nt
	s_nop 0
	global_load_dword v14, v[18:19], off nt
	global_load_dword v15, v[22:23], off nt
	global_load_dword v16, v[24:25], off nt
	v_add_co_u32_e32 v4, vcc, s31, v2
	s_mov_b32 s39, 0x48000
	s_nop 0
	v_addc_co_u32_e32 v5, vcc, 0, v3, vcc
	v_add_co_u32_e32 v18, vcc, s39, v2
	s_mov_b32 s40, 0x50000
	s_nop 0
	v_addc_co_u32_e32 v19, vcc, 0, v3, vcc
	v_add_co_u32_e32 v22, vcc, s40, v2
	s_mov_b32 s41, 0x58000
	s_nop 0
	v_addc_co_u32_e32 v23, vcc, 0, v3, vcc
	v_add_co_u32_e32 v28, vcc, s41, v2
	s_mov_b32 s42, 0x60000
	s_nop 0
	v_addc_co_u32_e32 v29, vcc, 0, v3, vcc
	v_add_co_u32_e32 v30, vcc, s42, v2
	s_mov_b32 s43, 0x68000
	s_nop 0
	v_addc_co_u32_e32 v31, vcc, 0, v3, vcc
	v_add_co_u32_e32 v32, vcc, s43, v2
	s_mov_b32 s35, 0x70000
	s_nop 0
	v_addc_co_u32_e32 v33, vcc, 0, v3, vcc
	v_add_co_u32_e32 v34, vcc, s35, v2
	s_mov_b32 s44, 0x78000
	s_nop 0
	v_addc_co_u32_e32 v35, vcc, 0, v3, vcc
	v_add_co_u32_e32 v36, vcc, s44, v2
	s_mov_b32 s45, 0x80000
	s_nop 0
	v_addc_co_u32_e32 v37, vcc, 0, v3, vcc
	global_load_dword v24, v[4:5], off nt
	global_load_dword v25, v[18:19], off nt
	global_load_dword v26, v[22:23], off nt
	global_load_dword v27, v[28:29], off nt
	s_nop 0
	global_load_dword v28, v[30:31], off nt
	global_load_dword v29, v[32:33], off nt
	s_nop 0
	global_load_dword v30, v[34:35], off nt
	global_load_dword v31, v[36:37], off nt
	v_add_co_u32_e32 v4, vcc, s45, v2
	s_mov_b32 s46, 0x88000
	s_nop 0
	v_addc_co_u32_e32 v5, vcc, 0, v3, vcc
	v_add_co_u32_e32 v18, vcc, s46, v2
	s_mov_b32 s47, 0x90000
	s_nop 0
	v_addc_co_u32_e32 v19, vcc, 0, v3, vcc
	v_add_co_u32_e32 v22, vcc, s47, v2
	s_mov_b32 s48, 0x98000
	s_nop 0
	v_addc_co_u32_e32 v23, vcc, 0, v3, vcc
	v_add_co_u32_e32 v32, vcc, s48, v2
	s_mov_b32 s49, 0xa0000
	s_nop 0
	v_addc_co_u32_e32 v33, vcc, 0, v3, vcc
	v_add_co_u32_e32 v34, vcc, s49, v2
	s_mov_b32 s59, 0xa8000
	s_nop 0
	v_addc_co_u32_e32 v35, vcc, 0, v3, vcc
	v_add_co_u32_e32 v36, vcc, s59, v2
	s_mov_b32 s68, 0xb0000
	s_nop 0
	v_addc_co_u32_e32 v37, vcc, 0, v3, vcc
	v_add_co_u32_e32 v38, vcc, s68, v2
	s_mov_b32 s69, 0xb8000
	s_nop 0
	v_addc_co_u32_e32 v39, vcc, 0, v3, vcc
	v_add_co_u32_e32 v48, vcc, s69, v2
	s_mov_b32 s70, 0xc0000
	s_nop 0
	v_addc_co_u32_e32 v49, vcc, 0, v3, vcc
	global_load_dword v40, v[4:5], off nt
	global_load_dword v41, v[18:19], off nt
	global_load_dword v42, v[22:23], off nt
	global_load_dword v43, v[32:33], off nt
	global_load_dword v44, v[34:35], off nt
	global_load_dword v45, v[36:37], off nt
	global_load_dword v46, v[38:39], off nt
	global_load_dword v54, v[48:49], off nt
	v_add_co_u32_e32 v4, vcc, s70, v2
	s_mov_b32 s71, 0xc8000
	s_nop 0
	v_addc_co_u32_e32 v5, vcc, 0, v3, vcc
	v_add_co_u32_e32 v18, vcc, s71, v2
	s_mov_b32 s72, 0xd0000
	s_nop 0
	v_addc_co_u32_e32 v19, vcc, 0, v3, vcc
	v_add_co_u32_e32 v22, vcc, s72, v2
	s_mov_b32 s73, 0xd8000
	s_nop 0
	v_addc_co_u32_e32 v23, vcc, 0, v3, vcc
	v_add_co_u32_e32 v32, vcc, s73, v2
	s_mov_b32 s2, 0xe0000
	s_nop 0
	v_addc_co_u32_e32 v33, vcc, 0, v3, vcc
	v_add_co_u32_e32 v34, vcc, s2, v2
	s_mov_b32 s2, 0xe8000
	s_nop 0
	v_addc_co_u32_e32 v35, vcc, 0, v3, vcc
	v_add_co_u32_e32 v36, vcc, s2, v2
	s_mov_b32 s2, 0xf0000
	s_nop 0
	v_addc_co_u32_e32 v37, vcc, 0, v3, vcc
	v_add_co_u32_e32 v38, vcc, s2, v2
	s_mov_b32 s2, 0xf8000
	s_nop 0
	v_addc_co_u32_e32 v39, vcc, 0, v3, vcc
	v_add_co_u32_e32 v2, vcc, s2, v2
	s_movk_i32 s2, 0x84
	s_nop 0
	v_addc_co_u32_e32 v3, vcc, 0, v3, vcc
	global_load_dword v56, v[4:5], off nt
	global_load_dword v57, v[18:19], off nt
	global_load_dword v58, v[22:23], off nt
	global_load_dword v59, v[32:33], off nt
	global_load_dword v60, v[34:35], off nt
	global_load_dword v61, v[36:37], off nt
	global_load_dword v70, v[38:39], off nt
	global_load_dword v72, v[2:3], off nt
	v_add_u32_e32 v6, s7, v0
	v_mul_lo_u32 v17, v9, s2
	v_and_b32_e32 v0, 56, v21
	v_readlane_b32 s2, v251, 60
	v_mul_u32_u24_e32 v4, 0x84, v0
	v_lshlrev_b32_e32 v0, 1, v0
	v_readlane_b32 s3, v251, 61
	v_add_u32_e32 v6, v6, v17
	s_movk_i32 s76, 0x7fff
	v_lshl_add_u64 v[2:3], s[2:3], 0, v[0:1]
	v_lshlrev_b32_e32 v0, 2, v20
	v_readlane_b32 s2, v251, 42
	v_add3_u32 v4, s7, v4, v0
	s_lshl_b32 s7, s2, 5
	v_readlane_b32 s2, v251, 4
	v_readlane_b32 s3, v251, 3
	s_lshl_b32 s2, s2, 8
	s_lshl_b32 s74, s3, 8
	v_add_u32_e32 v5, s2, v20
	s_add_i32 s75, s2, s74
	v_lshlrev_b32_e32 v0, 2, v8
	s_mov_b32 s77, 0xffff0000
	v_mov_b32_e32 v71, v1
	v_mov_b32_e32 v62, v1
	v_mov_b32_e32 v63, v1
	v_mov_b32_e32 v65, v1
	v_mov_b32_e32 v66, v1
	v_mov_b32_e32 v67, v1
	v_mov_b32_e32 v68, v1
	v_mov_b32_e32 v69, v1
	v_mov_b32_e32 v55, v1
	v_mov_b32_e32 v47, v1
	v_mov_b32_e32 v48, v1
	v_mov_b32_e32 v49, v1
	v_mov_b32_e32 v50, v1
	v_mov_b32_e32 v51, v1
	v_mov_b32_e32 v52, v1
	v_mov_b32_e32 v53, v1
	v_mov_b32_e32 v39, v1
	v_mov_b32_e32 v32, v1
	v_mov_b32_e32 v33, v1
	v_mov_b32_e32 v34, v1
	v_mov_b32_e32 v35, v1
	v_mov_b32_e32 v36, v1
	v_mov_b32_e32 v37, v1
	v_mov_b32_e32 v38, v1
	v_mov_b32_e32 v23, v1
	v_mov_b32_e32 v8, v1
	v_mov_b32_e32 v17, v1
	v_mov_b32_e32 v18, v1
	v_mov_b32_e32 v19, v1
	v_mov_b32_e32 v20, v1
	v_mov_b32_e32 v21, v1
	v_mov_b32_e32 v22, v1
	s_mov_b32 s79, s4
	v_readlane_b32 s9, v251, 6
	v_readlane_b32 s10, v251, 7
	v_readlane_b32 s11, v251, 8
	v_readlane_b32 s12, v251, 9
	v_readlane_b32 s13, v251, 10
	v_readlane_b32 s14, v251, 11
	v_readlane_b32 s15, v251, 12
	v_readlane_b32 s18, v251, 15
	v_readlane_b32 s19, v251, 16
	v_readlane_b32 s20, v251, 17
	v_readlane_b32 s21, v251, 18
	v_readlane_b32 s22, v251, 19
	v_readlane_b32 s23, v251, 20
	s_branch .LBB0_117

.LBB0_117:
	s_add_i32 s78, s79, s6
	s_cmpk_gt_i32 s78, 0x1ff
	s_cselect_b64 s[2:3], -1, 0
	s_and_b64 vcc, exec, s[2:3]
	s_cbranch_vccnz .LBB0_116
	s_ashr_i32 s36, s78, 31
	s_lshr_b32 s36, s36, 25
	s_add_i32 s36, s78, s36
	s_ashr_i32 s36, s36, 7
	v_lshl_add_u32 v18, s36, 6, v9
	s_add_i32 s37, s7, s75
	s_lshl_b32 s38, s36, 12
	v_ashrrev_i32_e32 v19, 31, v18
	v_readlane_b32 s8, v251, 5
	s_sub_i32 s80, s37, s38
	v_lshlrev_b64 v[18:19], 14, v[18:19]
	v_readlane_b32 s16, v251, 13
	v_readlane_b32 s17, v251, 14
	s_ashr_i32 s81, s80, 31
	v_readlane_b32 s9, v251, 6
	v_lshl_add_u64 v[18:19], s[16:17], 0, v[18:19]
	v_lshl_add_u64 v[18:19], s[80:81], 2, v[18:19]
	v_lshl_add_u64 v[62:63], v[18:19], 0, v[0:1]
	v_add_co_u32_e32 v18, vcc, s24, v62
	v_readlane_b32 s10, v251, 7
	s_nop 0
	v_addc_co_u32_e32 v19, vcc, 0, v63, vcc
	v_add_co_u32_e32 v32, vcc, s25, v62
	v_readlane_b32 s11, v251, 8
	s_nop 0
	v_addc_co_u32_e32 v33, vcc, 0, v63, vcc
	v_add_co_u32_e32 v34, vcc, s26, v62
	v_readlane_b32 s12, v251, 9
	s_nop 0
	v_addc_co_u32_e32 v35, vcc, 0, v63, vcc
	v_add_co_u32_e32 v36, vcc, s27, v62
	v_readlane_b32 s13, v251, 10
	s_nop 0
	v_addc_co_u32_e32 v37, vcc, 0, v63, vcc
	v_add_co_u32_e32 v38, vcc, s28, v62
	v_readlane_b32 s14, v251, 11
	s_nop 0
	v_addc_co_u32_e32 v39, vcc, 0, v63, vcc
	v_add_co_u32_e32 v48, vcc, s29, v62
	v_readlane_b32 s15, v251, 12
	s_nop 0
	v_addc_co_u32_e32 v49, vcc, 0, v63, vcc
	v_add_co_u32_e32 v50, vcc, s30, v62
	v_readlane_b32 s18, v251, 15
	s_nop 0
	v_addc_co_u32_e32 v51, vcc, 0, v63, vcc
	global_load_dword v22, v[62:63], off nt
	global_load_dword v21, v[18:19], off nt
	global_load_dword v20, v[32:33], off nt
	s_nop 0
	global_load_dword v19, v[34:35], off nt
	global_load_dword v18, v[36:37], off nt
	global_load_dword v17, v[38:39], off nt
	global_load_dword v8, v[48:49], off nt
	global_load_dword v23, v[50:51], off nt
	v_add_co_u32_e32 v32, vcc, s31, v62
	v_readlane_b32 s19, v251, 16
	s_nop 0
	v_addc_co_u32_e32 v33, vcc, 0, v63, vcc
	v_add_co_u32_e32 v34, vcc, s39, v62
	v_readlane_b32 s20, v251, 17
	s_nop 0
	v_addc_co_u32_e32 v35, vcc, 0, v63, vcc
	v_add_co_u32_e32 v48, vcc, s40, v62
	v_readlane_b32 s21, v251, 18
	s_nop 0
	v_addc_co_u32_e32 v49, vcc, 0, v63, vcc
	v_add_co_u32_e32 v50, vcc, s41, v62
	v_readlane_b32 s22, v251, 19
	s_nop 0
	v_addc_co_u32_e32 v51, vcc, 0, v63, vcc
	v_add_co_u32_e32 v52, vcc, s42, v62
	v_readlane_b32 s23, v251, 20
	s_nop 0
	v_addc_co_u32_e32 v53, vcc, 0, v63, vcc
	v_add_co_u32_e32 v66, vcc, s43, v62
	s_nop 1
	v_addc_co_u32_e32 v67, vcc, 0, v63, vcc
	v_add_co_u32_e32 v68, vcc, s35, v62
	s_nop 1
	v_addc_co_u32_e32 v69, vcc, 0, v63, vcc
	v_add_co_u32_e32 v74, vcc, s44, v62
	s_nop 1
	v_addc_co_u32_e32 v75, vcc, 0, v63, vcc
	global_load_dword v38, v[32:33], off nt
	global_load_dword v37, v[34:35], off nt
	global_load_dword v36, v[48:49], off nt
	s_nop 0
	global_load_dword v35, v[50:51], off nt
	global_load_dword v34, v[52:53], off nt
	global_load_dword v33, v[66:67], off nt
	global_load_dword v32, v[68:69], off nt
	global_load_dword v39, v[74:75], off nt
	v_add_co_u32_e32 v48, vcc, s45, v62
	s_nop 1
	v_addc_co_u32_e32 v49, vcc, 0, v63, vcc
	v_add_co_u32_e32 v50, vcc, s46, v62
	s_nop 1
	v_addc_co_u32_e32 v51, vcc, 0, v63, vcc
	v_add_co_u32_e32 v66, vcc, s47, v62
	s_nop 1
	v_addc_co_u32_e32 v67, vcc, 0, v63, vcc
	v_add_co_u32_e32 v68, vcc, s48, v62
	s_nop 1
	v_addc_co_u32_e32 v69, vcc, 0, v63, vcc
	v_add_co_u32_e32 v74, vcc, s49, v62
	s_nop 1
	v_addc_co_u32_e32 v75, vcc, 0, v63, vcc
	v_add_co_u32_e32 v76, vcc, s59, v62
	s_nop 1
	v_addc_co_u32_e32 v77, vcc, 0, v63, vcc
	v_add_co_u32_e32 v78, vcc, s68, v62
	s_nop 1
	v_addc_co_u32_e32 v79, vcc, 0, v63, vcc
	v_add_co_u32_e32 v80, vcc, s69, v62
	s_nop 1
	v_addc_co_u32_e32 v81, vcc, 0, v63, vcc
	global_load_dword v53, v[48:49], off nt
	global_load_dword v52, v[50:51], off nt
	s_nop 0
	global_load_dword v51, v[66:67], off nt
	global_load_dword v50, v[68:69], off nt
	global_load_dword v49, v[74:75], off nt
	global_load_dword v48, v[76:77], off nt
	global_load_dword v47, v[78:79], off nt
	global_load_dword v55, v[80:81], off nt
	v_add_co_u32_e32 v66, vcc, s70, v62
	s_nop 1
	v_addc_co_u32_e32 v67, vcc, 0, v63, vcc
	v_add_co_u32_e32 v74, vcc, s71, v62
	s_nop 1
	v_addc_co_u32_e32 v75, vcc, 0, v63, vcc
	v_add_co_u32_e32 v76, vcc, s72, v62
	s_nop 1
	v_addc_co_u32_e32 v77, vcc, 0, v63, vcc
	v_add_co_u32_e32 v78, vcc, s73, v62
	s_nop 1
	v_addc_co_u32_e32 v79, vcc, 0, v63, vcc
	v_add_co_u32_e32 v80, vcc, 0xe0000, v62
	s_nop 1
	v_addc_co_u32_e32 v81, vcc, 0, v63, vcc
	v_add_co_u32_e32 v82, vcc, 0xe8000, v62
	s_nop 1
	v_addc_co_u32_e32 v83, vcc, 0, v63, vcc
	v_add_co_u32_e32 v84, vcc, 0xf0000, v62
	s_nop 1
	v_addc_co_u32_e32 v85, vcc, 0, v63, vcc
	v_add_co_u32_e32 v86, vcc, 0xf8000, v62
	s_nop 1
	v_addc_co_u32_e32 v87, vcc, 0, v63, vcc
	global_load_dword v69, v[66:67], off nt
	global_load_dword v68, v[74:75], off nt
	s_nop 0
	global_load_dword v67, v[76:77], off nt
	global_load_dword v66, v[78:79], off nt
	global_load_dword v65, v[80:81], off nt
	global_load_dword v63, v[82:83], off nt
	global_load_dword v62, v[84:85], off nt
	global_load_dword v71, v[86:87], off nt
	s_branch .LBB0_116

.LBB0_123:
	v_add_co_u32_e32 v0, vcc, s5, v96
	v_readlane_b32 s68, v251, 5
	s_nop 0
	v_addc_co_u32_e32 v1, vcc, -1, v97, vcc
	global_load_dwordx4 v[40:43], v[0:1], off offset:-3072 nt
	global_load_dwordx4 v[36:39], v[0:1], off offset:-1024 nt
	global_load_dwordx4 v[32:35], v[0:1], off nt
	global_load_dwordx4 v[44:47], v[0:1], off offset:-2048 nt
	v_add_co_u32_e32 v0, vcc, s7, v96
	v_readlane_b32 s82, v251, 19
	s_nop 0
	v_addc_co_u32_e32 v1, vcc, -1, v97, vcc
	global_load_dwordx4 v[16:19], v[0:1], off offset:-2048 nt
	global_load_dwordx4 v[28:31], v[0:1], off offset:-3072 nt
	v_add_co_u32_e32 v2, vcc, 0xffffd000, v96
	v_readlane_b32 s83, v251, 20
	s_nop 0
	v_addc_co_u32_e32 v3, vcc, -1, v97, vcc
	global_load_dwordx4 v[60:63], v[2:3], off offset:-3072 nt
	global_load_dwordx4 v[56:59], v[2:3], off offset:-2048 nt
	global_load_dwordx4 v[48:51], v[2:3], off nt
	global_load_dwordx4 v[52:55], v[2:3], off offset:-1024 nt
	global_load_dwordx4 v[20:23], v[0:1], off offset:-1024 nt
	global_load_dwordx4 v[12:15], v[96:97], off offset:-3072 nt
	global_load_dwordx4 v[8:11], v[96:97], off offset:-2048 nt
	global_load_dwordx4 v[4:7], v[96:97], off offset:-1024 nt
	s_nop 0
	global_load_dwordx4 v[0:3], v[96:97], off nt
	global_load_dwordx4 v[24:27], v[96:97], off offset:-4096 nt
	v_readlane_b32 s69, v251, 6
	v_readlane_b32 s70, v251, 7
	v_readlane_b32 s71, v251, 8
	v_readlane_b32 s72, v251, 9
	v_readlane_b32 s73, v251, 10
	v_readlane_b32 s74, v251, 11
	v_readlane_b32 s75, v251, 12
	v_readlane_b32 s76, v251, 13
	v_readlane_b32 s77, v251, 14
	v_readlane_b32 s78, v251, 15
	v_readlane_b32 s79, v251, 16
	v_readlane_b32 s80, v251, 17
	v_readlane_b32 s81, v251, 18
	s_waitcnt vmcnt(15)
	v_pk_mul_f32 v[98:99], v[42:43], v[42:43]
	v_pk_mul_f32 v[100:101], v[40:41], v[40:41]
	s_waitcnt vmcnt(14)
	v_mul_f32_e32 v119, v38, v38
	s_waitcnt vmcnt(13)
	v_pk_mul_f32 v[110:111], v[34:35], v[34:35]
	v_pk_mul_f32 v[112:113], v[32:33], v[32:33]
	s_waitcnt vmcnt(12)
	v_mul_f32_e32 v114, v45, v45
	v_mul_f32_e32 v116, v47, v47
	v_mul_f32_e32 v133, v39, v39
	s_waitcnt vmcnt(9)
	v_pk_mul_f32 v[122:123], v[62:63], v[62:63]
	v_pk_mul_f32 v[124:125], v[60:61], v[60:61]
	v_mul_f32_e32 v118, v29, v29
	s_waitcnt vmcnt(8)
	v_pk_mul_f32 v[126:127], v[58:59], v[58:59]
	v_pk_mul_f32 v[128:129], v[56:57], v[56:57]
	v_pk_mov_b32 v[130:131], v[100:101], v[98:99] op_sel:[1,0]
	v_mov_b32_e32 v101, v99
	v_pk_mov_b32 v[98:99], v[112:113], v[110:111] op_sel:[1,0]
	v_mov_b32_e32 v113, v111
	v_pk_fma_f32 v[110:111], v[44:45], v[44:45], v[114:115] op_sel_hi:[1,1,0]
	v_pk_fma_f32 v[114:115], v[46:47], v[46:47], v[116:117] op_sel_hi:[1,1,0]
	v_pk_fma_f32 v[116:117], v[28:29], v[28:29], v[118:119] op_sel_hi:[1,1,0]
	s_waitcnt vmcnt(6)
	v_mul_f32_e32 v118, v53, v53
	v_mul_f32_e32 v132, v55, v55
	v_mul_f32_e32 v140, v50, v50
	v_mul_f32_e32 v141, v51, v51
	v_pk_mov_b32 v[134:135], v[124:125], v[122:123] op_sel:[1,0]
	v_mov_b32_e32 v125, v123
	v_pk_mov_b32 v[122:123], v[128:129], v[126:127] op_sel:[1,0]
	v_mov_b32_e32 v129, v127
	v_pk_add_f32 v[98:99], v[98:99], v[112:113]
	v_mov_b32_e32 v111, v119
	v_pk_fma_f32 v[112:113], v[52:53], v[52:53], v[118:119] op_sel_hi:[1,1,0]
	v_pk_fma_f32 v[118:119], v[54:55], v[54:55], v[132:133] op_sel_hi:[1,1,0]
	v_mov_b32_e32 v115, v133
	v_pk_add_f32 v[124:125], v[134:135], v[124:125]
	v_pk_add_f32 v[122:123], v[122:123], v[128:129]
	v_mov_b32_e32 v113, v140
	v_mov_b32_e32 v119, v141
	v_mul_f32_e32 v142, v48, v48
	v_mul_f32_e32 v143, v49, v49
	v_pk_add_f32 v[110:111], v[110:111], v[114:115]
	v_pk_add_f32 v[112:113], v[112:113], v[118:119]
	v_pk_add_f32 v[114:115], v[124:125], v[124:125] op_sel:[0,1] op_sel_hi:[1,0]
	v_pk_add_f32 v[118:119], v[122:123], v[122:123] op_sel:[0,1] op_sel_hi:[1,0]
	v_mov_b32_e32 v115, v142
	v_mov_b32_e32 v119, v143
	v_pk_add_f32 v[114:115], v[114:115], v[118:119]
	v_pk_add_f32 v[100:101], v[130:131], v[100:101]
	v_pk_add_f32 v[112:113], v[114:115], v[112:113]
	v_mul_f32_e32 v109, v36, v36
	v_mul_f32_e32 v121, v37, v37
	v_pk_add_f32 v[100:101], v[100:101], v[100:101] op_sel:[0,1] op_sel_hi:[1,0]
	v_pk_add_f32 v[112:113], v[112:113], v[112:113] op_sel:[0,1] op_sel_hi:[1,0]
	v_mov_b32_e32 v101, v121
	v_mov_b32_e32 v113, v109
	v_pk_add_f32 v[100:101], v[112:113], v[100:101]
	v_mul_f32_e32 v136, v16, v16
	v_pk_add_f32 v[100:101], v[100:101], v[110:111]
	v_mul_f32_e32 v137, v17, v17
	v_pk_add_f32 v[98:99], v[98:99], v[98:99] op_sel:[0,1] op_sel_hi:[1,0]
	v_pk_add_f32 v[100:101], v[100:101], v[100:101] op_sel:[0,1] op_sel_hi:[1,0]
	v_mul_f32_e32 v120, v31, v31
	v_mov_b32_e32 v99, v137
	v_mov_b32_e32 v101, v136
	v_mul_f32_e32 v138, v18, v18
	v_mul_f32_e32 v139, v19, v19
	v_pk_add_f32 v[98:99], v[100:101], v[98:99]
	v_pk_fma_f32 v[100:101], v[30:31], v[30:31], v[120:121] op_sel_hi:[1,1,0]
	v_mov_b32_e32 v117, v138
	v_mov_b32_e32 v101, v139
	v_pk_add_f32 v[100:101], v[116:117], v[100:101]
	s_waitcnt vmcnt(5)
	v_pk_mul_f32 v[110:111], v[20:21], v[20:21]
	v_pk_add_f32 v[98:99], v[98:99], v[100:101]
	v_pk_mul_f32 v[100:101], v[22:23], v[22:23]
	s_waitcnt vmcnt(4)
	v_mul_f32_e32 v109, v12, v12
	v_pk_mov_b32 v[112:113], v[110:111], v[100:101] op_sel:[1,0]
	v_mov_b32_e32 v111, v101
	v_pk_add_f32 v[100:101], v[112:113], v[110:111]
	v_mul_f32_e32 v110, v13, v13
	v_pk_add_f32 v[100:101], v[100:101], v[100:101] op_sel:[0,1] op_sel_hi:[1,0]
	v_pk_add_f32 v[98:99], v[98:99], v[98:99] op_sel:[0,1] op_sel_hi:[1,0]
	v_mov_b32_e32 v101, v110
	global_load_dwordx4 v[110:113], v[66:67], off nt
	v_mov_b32_e32 v99, v109
	v_pk_add_f32 v[98:99], v[98:99], v[100:101]
	s_waitcnt vmcnt(1)
	v_mul_f32_e32 v100, v25, v25
	v_mul_f32_e32 v114, v14, v14
	v_pk_fma_f32 v[100:101], v[24:25], v[24:25], v[100:101] op_sel_hi:[1,1,0]
	v_mul_f32_e32 v116, v15, v15
	v_mov_b32_e32 v101, v114
	v_mul_f32_e32 v114, v27, v27
	v_pk_fma_f32 v[114:115], v[26:27], v[26:27], v[114:115] op_sel_hi:[1,1,0]
	v_mul_f32_e32 v109, v0, v0
	v_mov_b32_e32 v115, v116
	v_pk_add_f32 v[100:101], v[100:101], v[114:115]
	v_pk_mul_f32 v[114:115], v[8:9], v[8:9]
	v_pk_add_f32 v[98:99], v[98:99], v[100:101]
	v_pk_mul_f32 v[100:101], v[10:11], v[10:11]
	v_pk_add_f32 v[98:99], v[98:99], v[98:99] op_sel:[0,1] op_sel_hi:[1,0]
	v_pk_mov_b32 v[116:117], v[114:115], v[100:101] op_sel:[1,0]
	v_mov_b32_e32 v115, v101
	v_pk_add_f32 v[100:101], v[116:117], v[114:115]
	v_mul_f32_e32 v114, v1, v1
	v_pk_add_f32 v[100:101], v[100:101], v[100:101] op_sel:[0,1] op_sel_hi:[1,0]
	v_mov_b32_e32 v99, v109
	v_mov_b32_e32 v101, v114
	v_pk_add_f32 v[98:99], v[98:99], v[100:101]
	v_mul_f32_e32 v100, v5, v5
	v_mul_f32_e32 v115, v2, v2
	v_pk_fma_f32 v[100:101], v[4:5], v[4:5], v[100:101] op_sel_hi:[1,1,0]
	v_mul_f32_e32 v114, v7, v7
	v_mul_f32_e32 v116, v3, v3
	v_mov_b32_e32 v101, v115
	v_pk_fma_f32 v[114:115], v[6:7], v[6:7], v[114:115] op_sel_hi:[1,1,0]
	s_nop 0
	v_mov_b32_e32 v115, v116
	v_pk_add_f32 v[100:101], v[100:101], v[114:115]
	v_lshl_add_u64 v[114:115], s[82:83], 0, v[94:95]
	v_pk_add_f32 v[98:99], v[98:99], v[100:101]
	s_nop 0
	v_add_f32_e32 v98, v98, v99
	ds_bpermute_b32 v99, v102, v98
	s_waitcnt lgkmcnt(0)
	v_add_f32_e32 v98, v98, v99
	ds_bpermute_b32 v99, v103, v98
	s_waitcnt lgkmcnt(0)
	v_add_f32_e32 v98, v98, v99
	ds_bpermute_b32 v99, v104, v98
	s_waitcnt lgkmcnt(0)
	v_add_f32_e32 v98, v98, v99
	ds_bpermute_b32 v99, v105, v98
	s_waitcnt lgkmcnt(0)
	v_add_f32_e32 v98, v98, v99
	ds_bpermute_b32 v99, v106, v98
	s_waitcnt lgkmcnt(0)
	v_add_f32_e32 v98, v98, v99
	ds_bpermute_b32 v99, v107, v98
	s_waitcnt lgkmcnt(0)
	v_add_f32_e32 v98, v98, v99
	v_fmamk_f32 v98, v98, 0x39800000, v65
	v_mul_f32_e32 v99, 0x4b800000, v98
	v_cmp_gt_f32_e32 vcc, s23, v98
	s_nop 1
	v_cndmask_b32_e32 v98, v98, v99, vcc
	v_rsq_f32_e32 v98, v98
	s_nop 0
	v_mul_f32_e32 v99, 0x45800000, v98
	v_cndmask_b32_e32 v100, v98, v99, vcc
	v_pk_mul_f32 v[98:99], v[100:101], v[60:61] op_sel_hi:[0,1]
	v_pk_mul_f32 v[60:61], v[100:101], v[62:63] op_sel_hi:[0,1]
	s_waitcnt vmcnt(0)
	v_pk_mul_f32 v[62:63], v[110:111], v[98:99]
	v_pk_mul_f32 v[60:61], v[112:113], v[60:61]
	v_bfe_u32 v98, v62, 16, 1
	v_add3_u32 v98, v62, v98, s24
	v_bfe_u32 v99, v63, 16, 1
	v_lshrrev_b32_e32 v98, 16, v98
	v_add3_u32 v99, v63, v99, s24
	v_and_or_b32 v110, v99, s25, v98
	v_bfe_u32 v98, v60, 16, 1
	v_add3_u32 v98, v60, v98, s24
	v_bfe_u32 v99, v61, 16, 1
	v_lshrrev_b32_e32 v98, 16, v98
	v_add3_u32 v99, v61, v99, s24
	v_and_or_b32 v111, v99, s25, v98
	v_add_co_u32_e32 v98, vcc, s45, v114
	v_pk_mul_f32 v[116:117], v[100:101], v[56:57] op_sel_hi:[0,1]
	s_nop 0
	v_addc_co_u32_e32 v99, vcc, 0, v115, vcc
	global_store_dwordx2 v[98:99], v[110:111], off offset:-4096
	global_load_dwordx4 v[110:113], v[66:67], off offset:1024 nt
	v_pk_mul_f32 v[56:57], v[100:101], v[58:59] op_sel_hi:[0,1]
	v_add_co_u32_e32 v114, vcc, s44, v114
	s_waitcnt vmcnt(0)
	v_pk_mul_f32 v[56:57], v[112:113], v[56:57]
	v_pk_mul_f32 v[58:59], v[110:111], v[116:117]
	v_bfe_u32 v110, v56, 16, 1
	v_bfe_u32 v101, v58, 16, 1
	v_bfe_u32 v109, v59, 16, 1
	v_bfe_u32 v111, v57, 16, 1
	v_add3_u32 v101, v58, v101, s24
	v_add3_u32 v110, v56, v110, s24
	v_add3_u32 v109, v59, v109, s24
	v_add3_u32 v111, v57, v111, s24
	v_lshrrev_b32_e32 v101, 16, v101
	v_lshrrev_b32_e32 v112, 16, v110
	v_addc_co_u32_e32 v115, vcc, 0, v115, vcc
	v_and_or_b32 v110, v109, s25, v101
	v_and_or_b32 v111, v111, s25, v112
	global_store_dwordx2 v[114:115], v[110:111], off offset:512
	global_load_dwordx4 v[110:113], v[66:67], off offset:2048 nt
	v_pk_mul_f32 v[116:117], v[100:101], v[52:53] op_sel_hi:[0,1]
	v_pk_mul_f32 v[52:53], v[100:101], v[54:55] op_sel_hi:[0,1]
	s_waitcnt vmcnt(0)
	v_pk_mul_f32 v[52:53], v[112:113], v[52:53]
	v_pk_mul_f32 v[54:55], v[110:111], v[116:117]
	v_bfe_u32 v110, v52, 16, 1
	v_bfe_u32 v101, v54, 16, 1
	v_bfe_u32 v109, v55, 16, 1
	v_bfe_u32 v111, v53, 16, 1
	v_add3_u32 v101, v54, v101, s24
	v_add3_u32 v110, v52, v110, s24
	v_add3_u32 v109, v55, v109, s24
	v_add3_u32 v111, v53, v111, s24
	v_lshrrev_b32_e32 v101, 16, v101
	v_lshrrev_b32_e32 v112, 16, v110
	v_and_or_b32 v110, v109, s25, v101
	v_and_or_b32 v111, v111, s25, v112
	global_store_dwordx2 v[114:115], v[110:111], off offset:1024
	global_load_dwordx4 v[110:113], v[66:67], off offset:3072 nt
	v_pk_mul_f32 v[116:117], v[100:101], v[48:49] op_sel_hi:[0,1]
	v_pk_mul_f32 v[48:49], v[100:101], v[50:51] op_sel_hi:[0,1]
	s_waitcnt vmcnt(0)
	v_pk_mul_f32 v[48:49], v[112:113], v[48:49]
	v_pk_mul_f32 v[50:51], v[110:111], v[116:117]
	v_bfe_u32 v110, v48, 16, 1
	v_bfe_u32 v101, v50, 16, 1
	v_bfe_u32 v109, v51, 16, 1
	v_bfe_u32 v111, v49, 16, 1
	v_add3_u32 v101, v50, v101, s24
	v_add3_u32 v110, v48, v110, s24
	v_add3_u32 v109, v51, v109, s24
	v_add3_u32 v111, v49, v111, s24
	v_lshrrev_b32_e32 v101, 16, v101
	v_lshrrev_b32_e32 v112, 16, v110
	v_and_or_b32 v110, v109, s25, v101
	v_and_or_b32 v111, v111, s25, v112
	global_store_dwordx2 v[114:115], v[110:111], off offset:1536
	global_load_dwordx4 v[110:113], v[68:69], off nt
	v_pk_mul_f32 v[116:117], v[100:101], v[40:41] op_sel_hi:[0,1]
	v_pk_mul_f32 v[40:41], v[100:101], v[42:43] op_sel_hi:[0,1]
	s_waitcnt vmcnt(0)
	v_pk_mul_f32 v[40:41], v[112:113], v[40:41]
	v_pk_mul_f32 v[42:43], v[110:111], v[116:117]
	v_bfe_u32 v110, v40, 16, 1
	v_bfe_u32 v101, v42, 16, 1
	v_bfe_u32 v109, v43, 16, 1
	v_bfe_u32 v111, v41, 16, 1
	v_add3_u32 v101, v42, v101, s24
	v_add3_u32 v110, v40, v110, s24
	v_add3_u32 v109, v43, v109, s24
	v_add3_u32 v111, v41, v111, s24
	v_lshrrev_b32_e32 v101, 16, v101
	v_lshrrev_b32_e32 v112, 16, v110
	v_and_or_b32 v110, v109, s25, v101
	v_and_or_b32 v111, v111, s25, v112
	global_store_dwordx2 v[114:115], v[110:111], off offset:2048
	global_load_dwordx4 v[110:113], v[70:71], off nt
	v_pk_mul_f32 v[116:117], v[100:101], v[44:45] op_sel_hi:[0,1]
	v_pk_mul_f32 v[44:45], v[100:101], v[46:47] op_sel_hi:[0,1]
	s_waitcnt vmcnt(0)
	v_pk_mul_f32 v[44:45], v[112:113], v[44:45]
	v_pk_mul_f32 v[46:47], v[110:111], v[116:117]
	v_bfe_u32 v110, v44, 16, 1
	v_bfe_u32 v101, v46, 16, 1
	v_bfe_u32 v109, v47, 16, 1
	v_bfe_u32 v111, v45, 16, 1
	v_add3_u32 v101, v46, v101, s24
	v_add3_u32 v110, v44, v110, s24
	v_add3_u32 v109, v47, v109, s24
	v_add3_u32 v111, v45, v111, s24
	v_lshrrev_b32_e32 v101, 16, v101
	v_lshrrev_b32_e32 v112, 16, v110
	v_and_or_b32 v110, v109, s25, v101
	v_and_or_b32 v111, v111, s25, v112
	global_store_dwordx2 v[114:115], v[110:111], off offset:2560
	global_load_dwordx4 v[110:113], v[72:73], off nt
	v_pk_mul_f32 v[116:117], v[100:101], v[36:37] op_sel_hi:[0,1]
	v_pk_mul_f32 v[36:37], v[100:101], v[38:39] op_sel_hi:[0,1]
	s_waitcnt vmcnt(0)
	v_pk_mul_f32 v[36:37], v[112:113], v[36:37]
	v_pk_mul_f32 v[38:39], v[110:111], v[116:117]
	v_bfe_u32 v110, v36, 16, 1
	v_bfe_u32 v101, v38, 16, 1
	v_bfe_u32 v109, v39, 16, 1
	v_bfe_u32 v111, v37, 16, 1
	v_add3_u32 v101, v38, v101, s24
	v_add3_u32 v110, v36, v110, s24
	v_add3_u32 v109, v39, v109, s24
	v_add3_u32 v111, v37, v111, s24
	v_lshrrev_b32_e32 v101, 16, v101
	v_lshrrev_b32_e32 v112, 16, v110
	v_and_or_b32 v110, v109, s25, v101
	v_and_or_b32 v111, v111, s25, v112
	global_store_dwordx2 v[114:115], v[110:111], off offset:3072
	global_load_dwordx4 v[110:113], v[74:75], off nt
	v_pk_mul_f32 v[116:117], v[100:101], v[32:33] op_sel_hi:[0,1]
	v_pk_mul_f32 v[32:33], v[100:101], v[34:35] op_sel_hi:[0,1]
	s_waitcnt vmcnt(0)
	v_pk_mul_f32 v[32:33], v[112:113], v[32:33]
	v_pk_mul_f32 v[34:35], v[110:111], v[116:117]
	v_bfe_u32 v110, v32, 16, 1
	v_bfe_u32 v101, v34, 16, 1
	v_bfe_u32 v109, v35, 16, 1
	v_bfe_u32 v111, v33, 16, 1
	v_add3_u32 v101, v34, v101, s24
	v_add3_u32 v110, v32, v110, s24
	v_add3_u32 v109, v35, v109, s24
	v_add3_u32 v111, v33, v111, s24
	v_lshrrev_b32_e32 v101, 16, v101
	v_lshrrev_b32_e32 v112, 16, v110
	v_and_or_b32 v110, v109, s25, v101
	v_and_or_b32 v111, v111, s25, v112
	global_store_dwordx2 v[114:115], v[110:111], off offset:3584
	global_load_dwordx4 v[110:113], v[76:77], off nt
	v_pk_mul_f32 v[114:115], v[100:101], v[28:29] op_sel_hi:[0,1]
	v_pk_mul_f32 v[28:29], v[100:101], v[30:31] op_sel_hi:[0,1]
	s_waitcnt vmcnt(0)
	v_pk_mul_f32 v[28:29], v[112:113], v[28:29]
	v_pk_mul_f32 v[30:31], v[110:111], v[114:115]
	v_bfe_u32 v110, v28, 16, 1
	v_bfe_u32 v101, v30, 16, 1
	v_bfe_u32 v109, v31, 16, 1
	v_bfe_u32 v111, v29, 16, 1
	v_add3_u32 v101, v30, v101, s24
	v_add3_u32 v110, v28, v110, s24
	v_add3_u32 v109, v31, v109, s24
	v_add3_u32 v111, v29, v111, s24
	v_lshrrev_b32_e32 v101, 16, v101
	v_lshrrev_b32_e32 v112, 16, v110
	v_and_or_b32 v110, v109, s25, v101
	v_and_or_b32 v111, v111, s25, v112
	global_store_dwordx2 v[98:99], v[110:111], off
	global_load_dwordx4 v[110:113], v[78:79], off nt
	v_pk_mul_f32 v[114:115], v[100:101], v[16:17] op_sel_hi:[0,1]
	v_pk_mul_f32 v[16:17], v[100:101], v[18:19] op_sel_hi:[0,1]
	s_waitcnt vmcnt(0)
	v_pk_mul_f32 v[16:17], v[112:113], v[16:17]
	v_pk_mul_f32 v[18:19], v[110:111], v[114:115]
	v_bfe_u32 v110, v16, 16, 1
	v_bfe_u32 v101, v18, 16, 1
	v_bfe_u32 v109, v19, 16, 1
	v_bfe_u32 v111, v17, 16, 1
	v_add3_u32 v101, v18, v101, s24
	v_add3_u32 v110, v16, v110, s24
	v_add3_u32 v109, v19, v109, s24
	v_add3_u32 v111, v17, v111, s24
	v_lshrrev_b32_e32 v101, 16, v101
	v_lshrrev_b32_e32 v112, 16, v110
	v_and_or_b32 v110, v109, s25, v101
	v_and_or_b32 v111, v111, s25, v112
	global_store_dwordx2 v[98:99], v[110:111], off offset:512
	global_load_dwordx4 v[110:113], v[80:81], off nt
	v_pk_mul_f32 v[114:115], v[100:101], v[20:21] op_sel_hi:[0,1]
	v_pk_mul_f32 v[20:21], v[100:101], v[22:23] op_sel_hi:[0,1]
	s_waitcnt vmcnt(0)
	v_pk_mul_f32 v[20:21], v[112:113], v[20:21]
	v_pk_mul_f32 v[22:23], v[110:111], v[114:115]
	v_bfe_u32 v110, v20, 16, 1
	v_bfe_u32 v101, v22, 16, 1
	v_bfe_u32 v109, v23, 16, 1
	v_bfe_u32 v111, v21, 16, 1
	v_add3_u32 v101, v22, v101, s24
	v_add3_u32 v110, v20, v110, s24
	v_add3_u32 v109, v23, v109, s24
	v_add3_u32 v111, v21, v111, s24
	v_lshrrev_b32_e32 v101, 16, v101
	v_lshrrev_b32_e32 v112, 16, v110
	v_and_or_b32 v110, v109, s25, v101
	v_and_or_b32 v111, v111, s25, v112
	global_store_dwordx2 v[98:99], v[110:111], off offset:1024
	global_load_dwordx4 v[110:113], v[82:83], off nt
	v_pk_mul_f32 v[114:115], v[100:101], v[24:25] op_sel_hi:[0,1]
	v_pk_mul_f32 v[24:25], v[100:101], v[26:27] op_sel_hi:[0,1]
	s_waitcnt vmcnt(0)
	v_pk_mul_f32 v[24:25], v[112:113], v[24:25]
	v_pk_mul_f32 v[26:27], v[110:111], v[114:115]
	v_bfe_u32 v110, v24, 16, 1
	v_bfe_u32 v101, v26, 16, 1
	v_bfe_u32 v109, v27, 16, 1
	v_bfe_u32 v111, v25, 16, 1
	v_add3_u32 v101, v26, v101, s24
	v_add3_u32 v110, v24, v110, s24
	v_add3_u32 v109, v27, v109, s24
	v_add3_u32 v111, v25, v111, s24
	v_lshrrev_b32_e32 v101, 16, v101
	v_lshrrev_b32_e32 v112, 16, v110
	v_and_or_b32 v110, v109, s25, v101
	v_and_or_b32 v111, v111, s25, v112
	global_store_dwordx2 v[98:99], v[110:111], off offset:1536
	global_load_dwordx4 v[110:113], v[84:85], off nt
	v_pk_mul_f32 v[114:115], v[100:101], v[12:13] op_sel_hi:[0,1]
	v_pk_mul_f32 v[12:13], v[100:101], v[14:15] op_sel_hi:[0,1]
	s_waitcnt vmcnt(0)
	v_pk_mul_f32 v[12:13], v[112:113], v[12:13]
	v_pk_mul_f32 v[14:15], v[110:111], v[114:115]
	v_bfe_u32 v110, v12, 16, 1
	v_bfe_u32 v101, v14, 16, 1
	v_bfe_u32 v109, v15, 16, 1
	v_bfe_u32 v111, v13, 16, 1
	v_add3_u32 v101, v14, v101, s24
	v_add3_u32 v110, v12, v110, s24
	v_add3_u32 v109, v15, v109, s24
	v_add3_u32 v111, v13, v111, s24
	v_lshrrev_b32_e32 v101, 16, v101
	v_lshrrev_b32_e32 v112, 16, v110
	v_and_or_b32 v110, v109, s25, v101
	v_and_or_b32 v111, v111, s25, v112
	global_store_dwordx2 v[98:99], v[110:111], off offset:2048
	global_load_dwordx4 v[110:113], v[86:87], off nt
	v_pk_mul_f32 v[114:115], v[100:101], v[8:9] op_sel_hi:[0,1]
	v_pk_mul_f32 v[8:9], v[100:101], v[10:11] op_sel_hi:[0,1]
	s_waitcnt vmcnt(0)
	v_pk_mul_f32 v[8:9], v[112:113], v[8:9]
	v_pk_mul_f32 v[10:11], v[110:111], v[114:115]
	v_bfe_u32 v110, v8, 16, 1
	v_bfe_u32 v101, v10, 16, 1
	v_bfe_u32 v109, v11, 16, 1
	v_bfe_u32 v111, v9, 16, 1
	v_add3_u32 v101, v10, v101, s24
	v_add3_u32 v110, v8, v110, s24
	v_add3_u32 v109, v11, v109, s24
	v_add3_u32 v111, v9, v111, s24
	v_lshrrev_b32_e32 v101, 16, v101
	v_lshrrev_b32_e32 v112, 16, v110
	v_and_or_b32 v110, v109, s25, v101
	v_and_or_b32 v111, v111, s25, v112
	global_store_dwordx2 v[98:99], v[110:111], off offset:2560
	global_load_dwordx4 v[110:113], v[88:89], off nt
	v_pk_mul_f32 v[114:115], v[100:101], v[4:5] op_sel_hi:[0,1]
	v_pk_mul_f32 v[4:5], v[100:101], v[6:7] op_sel_hi:[0,1]
	s_waitcnt vmcnt(0)
	v_pk_mul_f32 v[4:5], v[112:113], v[4:5]
	v_pk_mul_f32 v[6:7], v[110:111], v[114:115]
	v_bfe_u32 v110, v4, 16, 1
	v_bfe_u32 v101, v6, 16, 1
	v_bfe_u32 v109, v7, 16, 1
	v_bfe_u32 v111, v5, 16, 1
	v_add3_u32 v101, v6, v101, s24
	v_add3_u32 v110, v4, v110, s24
	v_add3_u32 v109, v7, v109, s24
	v_add3_u32 v111, v5, v111, s24
	v_lshrrev_b32_e32 v101, 16, v101
	v_lshrrev_b32_e32 v112, 16, v110
	v_and_or_b32 v110, v109, s25, v101
	v_and_or_b32 v111, v111, s25, v112
	global_store_dwordx2 v[98:99], v[110:111], off offset:3072
	global_load_dwordx4 v[110:113], v[90:91], off nt
	v_pk_mul_f32 v[0:1], v[100:101], v[0:1] op_sel_hi:[0,1]
	v_pk_mul_f32 v[2:3], v[100:101], v[2:3] op_sel_hi:[0,1]
	v_max_f32_e64 v100, |v60|, |v61|
	v_max_f32_e64 v101, |v56|, |v57|
	v_max3_f32 v100, |v62|, |v63|, v100
	v_max3_f32 v101, |v58|, |v59|, v101
	v_max3_f32 v100, v100, 0, v101
	v_max_f32_e64 v101, |v52|, |v53|
	v_max_f32_e64 v109, |v48|, |v49|
	v_max3_f32 v101, |v54|, |v55|, v101
	v_max3_f32 v109, |v50|, |v51|, v109
	v_max3_f32 v100, v100, v101, v109
	v_max_f32_e64 v101, |v40|, |v41|
	v_max_f32_e64 v109, |v44|, |v45|
	v_max3_f32 v101, |v42|, |v43|, v101
	v_max3_f32 v109, |v46|, |v47|, v109
	v_max3_f32 v100, v100, v101, v109
	v_max_f32_e64 v101, |v36|, |v37|
	v_max_f32_e64 v109, |v32|, |v33|
	v_max3_f32 v101, |v38|, |v39|, v101
	v_max3_f32 v109, |v34|, |v35|, v109
	v_max3_f32 v100, v100, v101, v109
	v_max_f32_e64 v101, |v28|, |v29|
	v_max_f32_e64 v109, |v16|, |v17|
	v_max3_f32 v101, |v30|, |v31|, v101
	v_max3_f32 v109, |v18|, |v19|, v109
	v_max3_f32 v100, v100, v101, v109
	v_max_f32_e64 v101, |v20|, |v21|
	v_max_f32_e64 v109, |v24|, |v25|
	v_max3_f32 v101, |v22|, |v23|, v101
	v_max3_f32 v109, |v26|, |v27|, v109
	v_max3_f32 v100, v100, v101, v109
	v_max_f32_e64 v101, |v12|, |v13|
	v_max_f32_e64 v109, |v8|, |v9|
	v_max3_f32 v101, |v14|, |v15|, v101
	v_max3_f32 v109, |v10|, |v11|, v109
	v_max3_f32 v109, v100, v101, v109
	v_max_f32_e64 v100, |v4|, |v5|
	v_max3_f32 v114, |v6|, |v7|, v100
	s_waitcnt vmcnt(0)
	v_pk_mul_f32 v[2:3], v[112:113], v[2:3]
	v_pk_mul_f32 v[100:101], v[110:111], v[0:1]
	v_max_f32_e64 v0, |v2|, |v3|
	v_max3_f32 v0, |v100|, |v101|, v0
	v_max3_f32 v0, v109, v114, v0
	ds_bpermute_b32 v1, v102, v0
	v_bfe_u32 v111, v100, 16, 1
	v_bfe_u32 v112, v101, 16, 1
	v_add3_u32 v111, v100, v111, s24
	v_add3_u32 v112, v101, v112, s24
	s_waitcnt lgkmcnt(0)
	v_max_f32_e32 v1, v1, v1
	v_max_f32_e32 v109, v0, v1
	ds_bpermute_b32 v110, v103, v109
	v_bfe_u32 v113, v2, 16, 1
	v_add3_u32 v113, v2, v113, s24
	v_bfe_u32 v114, v3, 16, 1
	v_lshl_add_u64 v[0:1], s[82:83], 0, v[92:93]
	s_waitcnt lgkmcnt(0)
	v_max_f32_e32 v110, v110, v110
	v_max_f32_e32 v109, v109, v110
	ds_bpermute_b32 v110, v104, v109
	v_add3_u32 v114, v3, v114, s24
	v_add_co_u32_e32 v0, vcc, s48, v0
	s_waitcnt lgkmcnt(0)
	v_max_f32_e32 v110, v110, v110
	v_max_f32_e32 v109, v109, v110
	ds_bpermute_b32 v110, v105, v109
	v_addc_co_u32_e32 v1, vcc, 0, v1, vcc
	s_waitcnt lgkmcnt(0)
	v_max_f32_e32 v110, v110, v110
	v_max_f32_e32 v109, v109, v110
	ds_bpermute_b32 v110, v106, v109
	s_waitcnt lgkmcnt(0)
	v_max_f32_e32 v110, v110, v110
	v_max_f32_e32 v109, v109, v110
	ds_bpermute_b32 v115, v107, v109
	v_lshrrev_b32_e32 v110, 16, v111
	v_and_or_b32 v110, v112, s25, v110
	v_lshrrev_b32_e32 v111, 16, v113
	v_and_or_b32 v111, v114, s25, v111
	s_waitcnt lgkmcnt(0)
	v_max_f32_e32 v112, v115, v115
	v_max_f32_e32 v109, v109, v112
	v_div_scale_f32 v112, s[20:21], v109, v109, s46
	v_rcp_f32_e32 v113, v112
	global_store_dwordx2 v[98:99], v[110:111], off offset:3584
	v_div_scale_f32 v98, vcc, s46, v109, s46
	v_fma_f32 v99, -v112, v113, 1.0
	v_fmac_f32_e32 v113, v99, v113
	v_mul_f32_e32 v99, v98, v113
	v_fma_f32 v110, -v112, v99, v98
	v_fmac_f32_e32 v99, v110, v113
	v_fma_f32 v98, -v112, v99, v98
	v_div_fmas_f32 v98, v98, v113, v99
	v_div_fixup_f32 v98, v98, v109, s46
	v_cmp_lt_f32_e32 vcc, 0, v109
	s_nop 1
	v_cndmask_b32_e32 v98, 0, v98, vcc
	v_pk_mul_f32 v[62:63], v[98:99], v[62:63] op_sel_hi:[0,1]
	v_pk_mul_f32 v[60:61], v[98:99], v[60:61] op_sel_hi:[0,1]
	v_pk_mul_f32 v[56:57], v[98:99], v[56:57] op_sel_hi:[0,1]
	v_pk_mul_f32 v[58:59], v[98:99], v[58:59] op_sel_hi:[0,1]
	v_pk_mul_f32 v[52:53], v[98:99], v[52:53] op_sel_hi:[0,1]
	v_pk_mul_f32 v[54:55], v[98:99], v[54:55] op_sel_hi:[0,1]
	v_pk_mul_f32 v[48:49], v[98:99], v[48:49] op_sel_hi:[0,1]
	v_pk_mul_f32 v[50:51], v[98:99], v[50:51] op_sel_hi:[0,1]
	v_pk_mul_f32 v[40:41], v[98:99], v[40:41] op_sel_hi:[0,1]
	v_pk_mul_f32 v[42:43], v[98:99], v[42:43] op_sel_hi:[0,1]
	v_pk_mul_f32 v[44:45], v[98:99], v[44:45] op_sel_hi:[0,1]
	v_pk_mul_f32 v[46:47], v[98:99], v[46:47] op_sel_hi:[0,1]
	v_pk_mul_f32 v[36:37], v[98:99], v[36:37] op_sel_hi:[0,1]
	v_pk_mul_f32 v[38:39], v[98:99], v[38:39] op_sel_hi:[0,1]
	v_pk_mul_f32 v[32:33], v[98:99], v[32:33] op_sel_hi:[0,1]
	v_pk_mul_f32 v[34:35], v[98:99], v[34:35] op_sel_hi:[0,1]
	v_pk_mul_f32 v[28:29], v[98:99], v[28:29] op_sel_hi:[0,1]
	v_pk_mul_f32 v[30:31], v[98:99], v[30:31] op_sel_hi:[0,1]
	v_pk_mul_f32 v[16:17], v[98:99], v[16:17] op_sel_hi:[0,1]
	v_pk_mul_f32 v[18:19], v[98:99], v[18:19] op_sel_hi:[0,1]
	v_pk_mul_f32 v[20:21], v[98:99], v[20:21] op_sel_hi:[0,1]
	v_pk_mul_f32 v[22:23], v[98:99], v[22:23] op_sel_hi:[0,1]
	v_pk_mul_f32 v[24:25], v[98:99], v[24:25] op_sel_hi:[0,1]
	v_pk_mul_f32 v[26:27], v[98:99], v[26:27] op_sel_hi:[0,1]
	v_pk_mul_f32 v[12:13], v[98:99], v[12:13] op_sel_hi:[0,1]
	v_pk_mul_f32 v[14:15], v[98:99], v[14:15] op_sel_hi:[0,1]
	v_pk_mul_f32 v[8:9], v[98:99], v[8:9] op_sel_hi:[0,1]
	v_pk_mul_f32 v[10:11], v[98:99], v[10:11] op_sel_hi:[0,1]
	v_pk_mul_f32 v[4:5], v[98:99], v[4:5] op_sel_hi:[0,1]
	v_pk_mul_f32 v[6:7], v[98:99], v[6:7] op_sel_hi:[0,1]
	v_pk_mul_f32 v[2:3], v[98:99], v[2:3] op_sel_hi:[0,1]
	v_pk_mul_f32 v[98:99], v[98:99], v[100:101] op_sel_hi:[0,1]
	v_rndne_f32_e32 v63, v63
	v_rndne_f32_e32 v62, v62
	v_rndne_f32_e32 v60, v60
	v_rndne_f32_e32 v61, v61
	v_rndne_f32_e32 v59, v59
	v_rndne_f32_e32 v55, v55
	v_rndne_f32_e32 v51, v51
	v_rndne_f32_e32 v42, v42
	v_rndne_f32_e32 v43, v43
	v_rndne_f32_e32 v41, v41
	v_rndne_f32_e32 v47, v47
	v_rndne_f32_e32 v39, v39
	v_rndne_f32_e32 v35, v35
	v_rndne_f32_e32 v31, v31
	v_rndne_f32_e32 v18, v18
	v_rndne_f32_e32 v19, v19
	v_rndne_f32_e32 v17, v17
	v_rndne_f32_e32 v22, v22
	v_rndne_f32_e32 v23, v23
	v_rndne_f32_e32 v21, v21
	v_rndne_f32_e32 v27, v27
	v_rndne_f32_e32 v15, v15
	v_rndne_f32_e32 v10, v10
	v_rndne_f32_e32 v11, v11
	v_rndne_f32_e32 v9, v9
	v_rndne_f32_e32 v6, v6
	v_rndne_f32_e32 v7, v7
	v_rndne_f32_e32 v5, v5
	v_rndne_f32_e32 v99, v99
	v_cvt_i32_f32_e32 v63, v63
	v_rndne_f32_e32 v58, v58
	v_rndne_f32_e32 v56, v56
	v_rndne_f32_e32 v57, v57
	v_rndne_f32_e32 v54, v54
	v_rndne_f32_e32 v52, v52
	v_rndne_f32_e32 v53, v53
	v_rndne_f32_e32 v50, v50
	v_rndne_f32_e32 v48, v48
	v_rndne_f32_e32 v49, v49
	v_rndne_f32_e32 v40, v40
	v_rndne_f32_e32 v46, v46
	v_rndne_f32_e32 v44, v44
	v_rndne_f32_e32 v45, v45
	v_rndne_f32_e32 v38, v38
	v_rndne_f32_e32 v36, v36
	v_rndne_f32_e32 v37, v37
	v_rndne_f32_e32 v34, v34
	v_rndne_f32_e32 v32, v32
	v_rndne_f32_e32 v33, v33
	v_rndne_f32_e32 v30, v30
	v_rndne_f32_e32 v28, v28
	v_rndne_f32_e32 v29, v29
	v_rndne_f32_e32 v16, v16
	v_rndne_f32_e32 v20, v20
	v_rndne_f32_e32 v26, v26
	v_rndne_f32_e32 v24, v24
	v_rndne_f32_e32 v25, v25
	v_rndne_f32_e32 v14, v14
	v_rndne_f32_e32 v12, v12
	v_rndne_f32_e32 v13, v13
	v_rndne_f32_e32 v8, v8
	v_rndne_f32_e32 v4, v4
	v_rndne_f32_e32 v98, v98
	v_rndne_f32_e32 v2, v2
	v_rndne_f32_e32 v3, v3
	v_cvt_i32_f32_e32 v62, v62
	v_cvt_i32_f32_sdwa v60, v60 dst_sel:WORD_1 dst_unused:UNUSED_PAD src0_sel:DWORD
	v_cvt_i32_f32_e32 v61, v61
	v_cvt_i32_f32_e32 v59, v59
	v_cvt_i32_f32_e32 v55, v55
	v_cvt_i32_f32_e32 v51, v51
	v_cvt_i32_f32_e32 v42, v42
	v_cvt_i32_f32_e32 v43, v43
	v_cvt_i32_f32_e32 v41, v41
	v_cvt_i32_f32_e32 v47, v47
	v_cvt_i32_f32_e32 v39, v39
	v_cvt_i32_f32_e32 v35, v35
	v_cvt_i32_f32_e32 v31, v31
	v_cvt_i32_f32_e32 v18, v18
	v_cvt_i32_f32_e32 v19, v19
	v_cvt_i32_f32_e32 v17, v17
	v_cvt_i32_f32_e32 v22, v22
	v_cvt_i32_f32_e32 v23, v23
	v_cvt_i32_f32_e32 v21, v21
	v_cvt_i32_f32_e32 v27, v27
	v_cvt_i32_f32_e32 v15, v15
	v_cvt_i32_f32_e32 v10, v10
	v_cvt_i32_f32_e32 v11, v11
	v_cvt_i32_f32_e32 v9, v9
	v_cvt_i32_f32_e32 v6, v6
	v_cvt_i32_f32_e32 v7, v7
	v_cvt_i32_f32_e32 v5, v5
	v_cvt_i32_f32_e32 v99, v99
	v_cvt_i32_f32_e32 v58, v58
	v_cvt_i32_f32_sdwa v56, v56 dst_sel:WORD_1 dst_unused:UNUSED_PAD src0_sel:DWORD
	v_cvt_i32_f32_e32 v57, v57
	v_cvt_i32_f32_e32 v54, v54
	v_cvt_i32_f32_sdwa v52, v52 dst_sel:WORD_1 dst_unused:UNUSED_PAD src0_sel:DWORD
	v_cvt_i32_f32_e32 v53, v53
	v_cvt_i32_f32_e32 v50, v50
	v_cvt_i32_f32_sdwa v48, v48 dst_sel:WORD_1 dst_unused:UNUSED_PAD src0_sel:DWORD
	v_cvt_i32_f32_e32 v49, v49
	v_cvt_i32_f32_sdwa v40, v40 dst_sel:WORD_1 dst_unused:UNUSED_PAD src0_sel:DWORD
	v_cvt_i32_f32_e32 v46, v46
	v_cvt_i32_f32_sdwa v44, v44 dst_sel:WORD_1 dst_unused:UNUSED_PAD src0_sel:DWORD
	v_cvt_i32_f32_e32 v45, v45
	v_cvt_i32_f32_e32 v38, v38
	v_cvt_i32_f32_sdwa v36, v36 dst_sel:WORD_1 dst_unused:UNUSED_PAD src0_sel:DWORD
	v_cvt_i32_f32_e32 v37, v37
	v_cvt_i32_f32_e32 v34, v34
	v_cvt_i32_f32_sdwa v32, v32 dst_sel:WORD_1 dst_unused:UNUSED_PAD src0_sel:DWORD
	v_cvt_i32_f32_e32 v33, v33
	v_cvt_i32_f32_e32 v30, v30
	v_cvt_i32_f32_sdwa v28, v28 dst_sel:WORD_1 dst_unused:UNUSED_PAD src0_sel:DWORD
	v_cvt_i32_f32_e32 v29, v29
	v_cvt_i32_f32_sdwa v16, v16 dst_sel:WORD_1 dst_unused:UNUSED_PAD src0_sel:DWORD
	v_cvt_i32_f32_sdwa v20, v20 dst_sel:WORD_1 dst_unused:UNUSED_PAD src0_sel:DWORD
	v_cvt_i32_f32_e32 v26, v26
	v_cvt_i32_f32_sdwa v24, v24 dst_sel:WORD_1 dst_unused:UNUSED_PAD src0_sel:DWORD
	v_cvt_i32_f32_e32 v25, v25
	v_cvt_i32_f32_e32 v14, v14
	v_cvt_i32_f32_sdwa v12, v12 dst_sel:WORD_1 dst_unused:UNUSED_PAD src0_sel:DWORD
	v_cvt_i32_f32_e32 v13, v13
	v_cvt_i32_f32_sdwa v8, v8 dst_sel:WORD_1 dst_unused:UNUSED_PAD src0_sel:DWORD
	v_cvt_i32_f32_sdwa v4, v4 dst_sel:WORD_1 dst_unused:UNUSED_PAD src0_sel:DWORD
	v_cvt_i32_f32_e32 v98, v98
	v_cvt_i32_f32_sdwa v2, v2 dst_sel:WORD_1 dst_unused:UNUSED_PAD src0_sel:DWORD
	v_cvt_i32_f32_e32 v3, v3
	v_lshlrev_b32_e32 v63, 8, v63
	v_and_b32_e32 v60, 0xff0000, v60
	v_perm_b32 v61, v61, v62, s47
	v_lshlrev_b32_e32 v59, 8, v59
	v_lshlrev_b32_e32 v55, 8, v55
	v_lshlrev_b32_e32 v51, 8, v51
	v_lshlrev_b32_e32 v43, 8, v43
	v_perm_b32 v41, v41, v42, s47
	v_lshlrev_b32_e32 v42, 8, v47
	v_lshlrev_b32_e32 v39, 8, v39
	v_lshlrev_b32_e32 v35, 8, v35
	v_lshlrev_b32_e32 v31, 8, v31
	v_lshlrev_b32_e32 v19, 8, v19
	v_perm_b32 v17, v17, v18, s47
	v_lshlrev_b32_e32 v18, 8, v23
	v_perm_b32 v21, v21, v22, s47
	v_lshlrev_b32_e32 v22, 8, v27
	v_lshlrev_b32_e32 v15, 8, v15
	v_lshlrev_b32_e32 v11, 8, v11
	v_perm_b32 v9, v9, v10, s47
	v_lshlrev_b32_e32 v7, 8, v7
	v_perm_b32 v5, v5, v6, s47
	v_lshlrev_b32_e32 v6, 8, v99
	v_and_b32_e32 v10, 0xff00, v63
	v_and_b32_e32 v56, 0xff0000, v56
	v_perm_b32 v57, v57, v58, s47
	v_and_b32_e32 v52, 0xff0000, v52
	v_perm_b32 v53, v53, v54, s47
	v_and_b32_e32 v48, 0xff0000, v48
	v_perm_b32 v49, v49, v50, s47
	v_and_b32_e32 v40, 0xff0000, v40
	v_and_b32_e32 v44, 0xff0000, v44
	v_perm_b32 v45, v45, v46, s47
	v_and_b32_e32 v36, 0xff0000, v36
	v_perm_b32 v37, v37, v38, s47
	v_and_b32_e32 v32, 0xff0000, v32
	v_perm_b32 v33, v33, v34, s47
	v_and_b32_e32 v28, 0xff0000, v28
	v_perm_b32 v29, v29, v30, s47
	v_and_b32_e32 v16, 0xff0000, v16
	v_and_b32_e32 v20, 0xff0000, v20
	v_and_b32_e32 v23, 0xff0000, v24
	v_perm_b32 v24, v25, v26, s47
	v_and_b32_e32 v12, 0xff0000, v12
	v_perm_b32 v13, v13, v14, s47
	v_and_b32_e32 v8, 0xff0000, v8
	v_and_b32_e32 v4, 0xff0000, v4
	v_and_b32_e32 v2, 0xff0000, v2
	v_perm_b32 v3, v3, v98, s47
	v_and_b32_e32 v14, 0xff00, v59
	v_and_b32_e32 v25, 0xff00, v55
	v_and_b32_e32 v26, 0xff00, v51
	v_and_b32_e32 v27, 0xff00, v43
	v_and_b32_e32 v30, 0xff00, v42
	v_and_b32_e32 v34, 0xff00, v39
	v_and_b32_e32 v35, 0xff00, v35
	v_and_b32_e32 v31, 0xff00, v31
	v_and_b32_e32 v19, 0xff00, v19
	v_and_b32_e32 v18, 0xff00, v18
	v_and_b32_e32 v22, 0xff00, v22
	v_and_b32_e32 v15, 0xff00, v15
	v_and_b32_e32 v11, 0xff00, v11
	v_and_b32_e32 v7, 0xff00, v7
	v_and_b32_e32 v6, 0xff00, v6
	v_or3_b32 v10, v61, v10, v60
	v_or3_b32 v14, v57, v14, v56
	v_or3_b32 v25, v53, v25, v52
	v_or3_b32 v26, v49, v26, v48
	v_or3_b32 v27, v41, v27, v40
	v_or3_b32 v30, v45, v30, v44
	v_or3_b32 v34, v37, v34, v36
	v_or3_b32 v32, v33, v35, v32
	v_or3_b32 v28, v29, v31, v28
	v_or3_b32 v16, v17, v19, v16
	v_or3_b32 v17, v21, v18, v20
	v_or3_b32 v18, v24, v22, v23
	v_or3_b32 v12, v13, v15, v12
	v_or3_b32 v8, v9, v11, v8
	v_or3_b32 v4, v5, v7, v4
	v_or3_b32 v2, v3, v6, v2
	global_store_dword v[0:1], v10, off
	global_store_dword v[0:1], v14, off offset:256
	global_store_dword v[0:1], v25, off offset:512
	global_store_dword v[0:1], v26, off offset:768
	global_store_dword v[0:1], v27, off offset:1024
	global_store_dword v[0:1], v30, off offset:1280
	global_store_dword v[0:1], v34, off offset:1536
	global_store_dword v[0:1], v32, off offset:1792
	global_store_dword v[0:1], v28, off offset:2048
	global_store_dword v[0:1], v16, off offset:2304
	global_store_dword v[0:1], v17, off offset:2560
	global_store_dword v[0:1], v18, off offset:2816
	global_store_dword v[0:1], v12, off offset:3072
	global_store_dword v[0:1], v8, off offset:3328
	global_store_dword v[0:1], v4, off offset:3584
	global_store_dword v[0:1], v2, off offset:3840
	s_and_saveexec_b64 s[20:21], s[2:3]
	s_cbranch_execz .LBB0_122
	v_readlane_b32 s68, v251, 5
	v_readlane_b32 s82, v251, 19
	v_readlane_b32 s83, v251, 20
	s_add_u32 s56, s82, s14
	s_addc_u32 s57, s83, s22
	v_mul_f32_e32 v0, 0x3c010204, v109
	v_readlane_b32 s69, v251, 6
	v_readlane_b32 s70, v251, 7
	v_readlane_b32 s71, v251, 8
	v_readlane_b32 s72, v251, 9
	v_readlane_b32 s73, v251, 10
	v_readlane_b32 s74, v251, 11
	v_readlane_b32 s75, v251, 12
	v_readlane_b32 s76, v251, 13
	v_readlane_b32 s77, v251, 14
	v_readlane_b32 s78, v251, 15
	v_readlane_b32 s79, v251, 16
	v_readlane_b32 s80, v251, 17
	v_readlane_b32 s81, v251, 18
	global_store_dword v108, v0, s[56:57]
	s_branch .LBB0_122

.LBB0_128:
	global_load_dwordx4 v[20:23], v[36:37], off nt
	v_add_u32_e32 v1, s33, v56
	v_cmp_gt_i32_e32 vcc, s14, v1
	v_mov_b32_e32 v0, 0
	v_mov_b32_e32 v12, 0
	v_mov_b32_e32 v13, 0
	v_mov_b32_e32 v14, 0
	v_mov_b32_e32 v15, 0
	s_and_saveexec_b64 s[2:3], vcc
	s_cbranch_execz .LBB0_130
	v_lshl_add_u64 v[2:3], v[36:37], 0, s[44:45]
	global_load_dwordx4 v[12:15], v[2:3], off nt
.LBB0_130:
	s_or_b64 exec, exec, s[2:3]
	v_add_u32_e32 v38, s33, v50
	v_add_u32_e32 v4, s34, v1
	v_cmp_gt_i32_e64 s[2:3], s14, v4
	v_ashrrev_i32_e32 v39, 31, v38
	v_mov_b32_e32 v1, 0
	v_mov_b32_e32 v2, 0
	v_mov_b32_e32 v3, 0
	s_and_saveexec_b64 s[4:5], s[2:3]
	s_cbranch_execz .LBB0_132
	v_lshl_add_u64 v[0:1], v[38:39], 4, s[54:55]
	global_load_dwordx4 v[0:3], v[0:1], off nt
.LBB0_132:
	s_or_b64 exec, exec, s[4:5]
	v_add_u32_e32 v40, s33, v51
	v_add_u32_e32 v5, s34, v4
	v_cmp_gt_i32_e64 s[4:5], s14, v5
	v_mov_b32_e32 v4, 0
	v_ashrrev_i32_e32 v41, 31, v40
	v_mov_b32_e32 v16, 0
	v_mov_b32_e32 v17, 0
	v_mov_b32_e32 v18, 0
	v_mov_b32_e32 v19, 0
	s_and_saveexec_b64 s[6:7], s[4:5]
	s_cbranch_execz .LBB0_134
	v_lshl_add_u64 v[6:7], v[40:41], 4, s[54:55]
	global_load_dwordx4 v[16:19], v[6:7], off nt
.LBB0_134:
	s_or_b64 exec, exec, s[6:7]
	v_add_u32_e32 v42, s33, v52
	v_add_u32_e32 v8, s34, v5
	v_cmp_gt_i32_e64 s[6:7], s14, v8
	v_ashrrev_i32_e32 v43, 31, v42
	v_mov_b32_e32 v5, 0
	v_mov_b32_e32 v6, 0
	v_mov_b32_e32 v7, 0
	s_and_saveexec_b64 s[8:9], s[6:7]
	s_cbranch_execz .LBB0_136
	v_lshl_add_u64 v[4:5], v[42:43], 4, s[54:55]
	global_load_dwordx4 v[4:7], v[4:5], off nt
.LBB0_136:
	s_or_b64 exec, exec, s[8:9]
	v_add_u32_e32 v44, s33, v53
	v_add_u32_e32 v9, s34, v8
	v_cmp_gt_i32_e64 s[8:9], s14, v9
	v_mov_b32_e32 v8, 0
	v_ashrrev_i32_e32 v45, 31, v44
	v_mov_b32_e32 v24, 0
	v_mov_b32_e32 v25, 0
	v_mov_b32_e32 v26, 0
	v_mov_b32_e32 v27, 0
	s_and_saveexec_b64 s[10:11], s[8:9]
	s_cbranch_execz .LBB0_138
	v_lshl_add_u64 v[10:11], v[44:45], 4, s[54:55]
	global_load_dwordx4 v[24:27], v[10:11], off nt
.LBB0_138:
	s_or_b64 exec, exec, s[10:11]
	v_add_u32_e32 v46, s33, v54
	v_add_u32_e32 v28, s34, v9
	v_cmp_gt_i32_e64 s[10:11], s14, v28
	v_ashrrev_i32_e32 v47, 31, v46
	v_mov_b32_e32 v9, 0
	v_mov_b32_e32 v10, 0
	v_mov_b32_e32 v11, 0
	s_and_saveexec_b64 s[12:13], s[10:11]
	s_cbranch_execz .LBB0_140
	v_lshl_add_u64 v[8:9], v[46:47], 4, s[54:55]
	global_load_dwordx4 v[8:11], v[8:9], off nt
.LBB0_140:
	s_or_b64 exec, exec, s[12:13]
	v_add_u32_e32 v48, s33, v55
	v_add_u32_e32 v57, s34, v28
	v_cmp_gt_i32_e64 s[12:13], s14, v57
	v_mov_b32_e32 v28, 0
	v_ashrrev_i32_e32 v49, 31, v48
	v_mov_b32_e32 v29, 0
	v_mov_b32_e32 v30, 0
	v_mov_b32_e32 v31, 0
	s_and_saveexec_b64 s[56:57], s[12:13]
	s_cbranch_execz .LBB0_142
	v_lshl_add_u64 v[28:29], v[48:49], 4, s[54:55]
	global_load_dwordx4 v[28:31], v[28:29], off nt

.LBB0_158:
	global_load_dwordx4 v[4:7], v[0:1], off nt
	v_add_u32_e32 v32, s34, v32
	v_cmp_lt_i32_e32 vcc, s12, v32
	v_lshl_add_u64 v[0:1], v[0:1], 0, s[4:5]
	s_or_b64 s[8:9], vcc, s[8:9]
	s_waitcnt vmcnt(0)
	v_bfe_u32 v8, v4, 16, 1
	v_bfe_u32 v10, v6, 16, 1
	v_bfe_u32 v9, v5, 16, 1
	v_bfe_u32 v11, v7, 16, 1
	v_add3_u32 v4, v4, v8, s10
	v_add3_u32 v6, v6, v10, s10
	v_add3_u32 v5, v5, v9, s10
	v_add3_u32 v7, v7, v11, s10
	v_lshrrev_b32_e32 v4, 16, v4
	v_lshrrev_b32_e32 v6, 16, v6
	v_and_or_b32 v4, v5, s11, v4
	v_and_or_b32 v5, v7, s11, v6
	global_store_dwordx2 v[2:3], v[4:5], off
	v_lshl_add_u64 v[2:3], v[2:3], 0, s[6:7]
	s_andn2_b64 exec, exec, s[8:9]
	s_cbranch_execnz .LBB0_158
